# cprep unit: QK-norm weights loaded once instead of per item, rope table loads software-pipelined one item ahead (no per-item load/store round trips)
# baseline (speedup 1.0000x reference)
.LBB0_369:
	s_or_b64 exec, exec, s[0:1]
	v_readlane_b32 s8, v254, 27
	v_readlane_b32 s22, v254, 41
	v_readlane_b32 s23, v254, 42
	v_readlane_b32 s16, v254, 35
	v_readlane_b32 s17, v254, 36
	v_readlane_b32 s18, v254, 37
	v_readlane_b32 s19, v254, 38
	v_readlane_b32 s20, v254, 39
	v_readlane_b32 s21, v254, 40
	s_mov_b64 s[66:67], s[22:23]
	s_lshl_b32 s4, s6, 1
	s_lshl_b32 s0, s6, 17
	s_mov_b64 s[62:63], s[18:19]
	v_ashrrev_i32_e32 v37, 31, v36
	s_add_u32 s0, s62, s0
	v_lshlrev_b64 v[24:25], 4, v[36:37]
	s_addc_u32 s1, s63, 0
	v_lshl_add_u64 v[8:9], s[0:1], 0, v[24:25]
	s_movk_i32 s5, 0x2000
	v_add_co_u32_e32 v4, vcc, s5, v8
	s_movk_i32 s5, 0x4000
	s_nop 0
	v_addc_co_u32_e32 v5, vcc, 0, v9, vcc
	v_add_co_u32_e32 v10, vcc, s5, v8
	s_movk_i32 s5, 0x6000
	s_nop 0
	v_addc_co_u32_e32 v11, vcc, 0, v9, vcc
	global_load_dwordx4 v[0:3], v[8:9], off
	s_nop 0
	global_load_dwordx4 v[4:7], v[4:5], off
	v_add_u32_e32 v26, 0x200, v36
	global_load_dwordx4 v[12:15], v[10:11], off
	v_add_co_u32_e32 v10, vcc, s5, v8
	s_mov_b32 s5, 0x8000
	s_nop 0
	v_addc_co_u32_e32 v11, vcc, 0, v9, vcc
	global_load_dwordx4 v[20:23], v[10:11], off
	v_add_co_u32_e32 v10, vcc, s5, v8
	s_mov_b32 s5, 0xa000
	s_nop 0
	v_addc_co_u32_e32 v11, vcc, 0, v9, vcc
	global_load_dwordx4 v[28:31], v[10:11], off
	v_add_co_u32_e32 v10, vcc, s5, v8
	s_mov_b32 s5, 0xc000
	s_nop 0
	v_addc_co_u32_e32 v11, vcc, 0, v9, vcc
	global_load_dwordx4 v[48:51], v[10:11], off
	v_add_co_u32_e32 v10, vcc, s5, v8
	s_mov_b32 s5, 0xe000
	s_nop 0
	v_addc_co_u32_e32 v11, vcc, 0, v9, vcc
	v_add_co_u32_e32 v8, vcc, s5, v8
	global_load_dwordx4 v[56:59], v[10:11], off
	s_nop 0
	v_addc_co_u32_e32 v9, vcc, 0, v9, vcc
	global_load_dwordx4 v[60:63], v[8:9], off
	v_and_b32_e32 v32, 0xf8, v39
	s_mov_b32 s5, s2
	v_readlane_b32 s9, v254, 28
	v_ashrrev_i32_e32 v33, 2, v36
	v_add_u32_e32 v34, s5, v32
	v_ashrrev_i32_e32 v35, 5, v26
	v_add_u32_e32 v16, 0x400, v36
	v_bfi_b32 v32, -16, v33, v36
	v_mad_u64_u32 v[40:41], s[8:9], v38, s79, v[34:35]
	v_add_u32_e32 v18, 0x600, v36
	v_ashrrev_i32_e32 v42, 5, v16
	v_mul_lo_u32 v43, v32, s79
	v_mad_u64_u32 v[38:39], s[8:9], v35, s79, v[34:35]
	v_add_u32_e32 v8, 0x800, v36
	v_add_u32_e32 v39, s5, v43
	v_mad_u64_u32 v[42:43], s[8:9], v42, s79, v[34:35]
	v_add_u32_e32 v10, 0xa00, v36
	v_add_u32_e32 v82, 0xc00, v36
	v_add_u32_e32 v84, 0xe00, v36
	s_add_u32 s0, s0, 0x10000
	v_and_b32_e32 v55, 15, v36
	v_bfe_u32 v37, v36, 4, 2
	s_addc_u32 s1, s1, 0
	s_lshl_b32 s5, s6, 7
	v_and_b32_e32 v74, 8, v36
	v_lshlrev_b32_e32 v70, 3, v37
	v_ashrrev_i32_e32 v33, 31, v32
	v_lshl_add_u32 v43, v37, 4, v39
	v_lshl_add_u64 v[78:79], s[96:97], 0, v[32:33]
	v_mov_b64_e32 v[76:77], s[26:27]
	v_lshlrev_b32_e32 v33, 2, v37
	s_lshl_b32 s90, s6, 8
	v_or_b32_e32 v88, 48, v74
	s_mov_b64 s[64:65], s[20:21]
	v_or_b32_e32 v89, 32, v74
	s_movk_i32 s6, 0x60
	v_ashrrev_i32_e32 v83, 31, v82
	v_ashrrev_i32_e32 v85, 31, v84
	s_waitcnt lgkmcnt(0)
	v_ashrrev_i32_e32 v17, 31, v16
	v_lshl_add_u64 v[96:97], v[16:17], 4, s[0:1]
	v_bitop3_b32 v16, v70, v89, s6 bitop3:0x36
	v_ashrrev_i32_e32 v11, 31, v10
	v_lshlrev_b32_e32 v109, 1, v16
	v_ashrrev_i32_e32 v9, 31, v8
	s_waitcnt vmcnt(7)
	v_cvt_pk_bf16_f32 v0, v0, v1
	v_cvt_pk_bf16_f32 v1, v2, v3
	ds_write_b64 v40, v[0:1]
	s_waitcnt vmcnt(6)
	v_cvt_pk_bf16_f32 v0, v4, v5
	v_cvt_pk_bf16_f32 v1, v6, v7
	ds_write_b64 v38, v[0:1]
	s_waitcnt vmcnt(5)
	v_cvt_pk_bf16_f32 v0, v12, v13
	v_cvt_pk_bf16_f32 v1, v14, v15
	v_ashrrev_i32_e32 v2, 5, v18
	ds_write_b64 v42, v[0:1]
	s_waitcnt vmcnt(4)
	v_cvt_pk_bf16_f32 v0, v20, v21
	v_cvt_pk_bf16_f32 v1, v22, v23
	v_mad_u64_u32 v[44:45], s[8:9], v2, s79, v[34:35]
	v_ashrrev_i32_e32 v2, 5, v8
	ds_write_b64 v44, v[0:1]
	s_waitcnt vmcnt(3)
	v_cvt_pk_bf16_f32 v0, v28, v29
	v_cvt_pk_bf16_f32 v1, v30, v31
	v_mad_u64_u32 v[46:47], s[8:9], v2, s79, v[34:35]
	v_ashrrev_i32_e32 v2, 5, v10
	ds_write_b64 v46, v[0:1]
	s_waitcnt vmcnt(2)
	v_cvt_pk_bf16_f32 v0, v48, v49
	v_cvt_pk_bf16_f32 v1, v50, v51
	v_mad_u64_u32 v[48:49], s[8:9], v2, s79, v[34:35]
	v_ashrrev_i32_e32 v2, 5, v82
	ds_write_b64 v48, v[0:1]
	v_mad_u64_u32 v[50:51], s[8:9], v2, s79, v[34:35]
	s_waitcnt vmcnt(1)
	v_cvt_pk_bf16_f32 v0, v56, v57
	v_cvt_pk_bf16_f32 v1, v58, v59
	v_ashrrev_i32_e32 v2, 5, v84
	ds_write_b64 v50, v[0:1]
	s_waitcnt vmcnt(0)
	v_cvt_pk_bf16_f32 v0, v60, v61
	v_cvt_pk_bf16_f32 v1, v62, v63
	v_mad_u64_u32 v[52:53], s[8:9], v2, s79, v[34:35]
	ds_write_b64 v52, v[0:1]
	v_or_b32_e32 v0, s5, v55
	v_mad_u32_u24 v41, v0, s79, 0
	v_bitop3_b32 v0, v70, v36, 8 bitop3:0x78
	v_bitop3_b32 v12, v70, v74, 16 bitop3:0x1e
	v_bitop3_b32 v20, v70, v74, 32 bitop3:0x1e
	v_bitop3_b32 v28, v70, v74, 48 bitop3:0x1e
	v_bitop3_b32 v36, v70, v74, 32 bitop3:0x36
	v_lshlrev_b32_e32 v45, 1, v0
	v_lshlrev_b32_e32 v47, 1, v12
	v_lshlrev_b32_e32 v49, 1, v20
	v_lshlrev_b32_e32 v53, 1, v28
	v_lshlrev_b32_e32 v99, 1, v36
	v_add_u32_e32 v4, v41, v45
	v_add_u32_e32 v12, v41, v47
	v_add_u32_e32 v20, v41, v49
	v_or_b32_e32 v51, 16, v74
	v_add_u32_e32 v28, v41, v53
	v_or_b32_e32 v29, 32, v70
	v_add_u32_e32 v36, v41, v99
	s_waitcnt lgkmcnt(0)
	s_barrier
	ds_read_b128 v[0:3], v43
	ds_read_b128 v[4:7], v4
	ds_read_b128 v[12:15], v12 offset:4352
	ds_read_b128 v[20:23], v20 offset:8704
	v_lshl_add_u32 v98, v29, 1, v39
	ds_read_b128 v[28:31], v28 offset:13056
	ds_read_b128 v[56:59], v98
	ds_read_b128 v[60:63], v36
	v_bitop3_b32 v36, v70, v51, 32 bitop3:0x36
	v_mad_u64_u32 v[34:35], s[8:9], v78, s33, v[76:77]
	v_lshlrev_b32_e32 v100, 1, v36
	v_mad_i32_i24 v35, v79, s33, v35
	v_add_u32_e32 v36, v41, v100
	ds_read_b128 v[64:67], v36 offset:4352
	v_lshl_add_u64 v[36:37], v[34:35], 0, v[70:71]
	v_lshl_add_u64 v[90:91], v[36:37], 0, s[90:91]
	global_load_dwordx2 v[92:93], v[90:91], off
	s_waitcnt lgkmcnt(6)
	v_mfma_f32_16x16x32_bf16 v[4:7], v[4:7], v[0:3], 0
	v_lshlrev_b64 v[34:35], 11, v[78:79]
	v_lshl_add_u64 v[10:11], v[10:11], 4, s[0:1]
	v_add_u32_e32 v16, v41, v109
	s_waitcnt lgkmcnt(5)
	v_mfma_f32_16x16x32_bf16 v[12:15], v[12:15], v[0:3], 0
	v_lshl_add_u64 v[86:87], v[8:9], 4, s[0:1]
	v_ashrrev_i32_e32 v19, 31, v18
	v_ashrrev_i32_e32 v27, 31, v26
	s_waitcnt lgkmcnt(4)
	v_mfma_f32_16x16x32_bf16 v[20:23], v[20:23], v[0:3], 0
	v_lshl_add_u64 v[18:19], v[18:19], 4, s[0:1]
	v_lshl_add_u64 v[26:27], v[26:27], 4, s[0:1]
	v_lshl_add_u64 v[34:35], s[28:29], 0, v[34:35]
	s_waitcnt lgkmcnt(3)
	v_mfma_f32_16x16x32_bf16 v[0:3], v[28:31], v[0:3], 0
	v_bitop3_b32 v28, v70, v74, 32 bitop3:0x14
	v_bitop3_b32 v29, v70, v88, 32 bitop3:0x36
	v_lshlrev_b32_e32 v101, 1, v28
	v_lshlrev_b32_e32 v102, 1, v29
	v_add_u32_e32 v28, v41, v101
	v_add_u32_e32 v54, v41, v102
	s_waitcnt lgkmcnt(1)
	v_mfma_f32_16x16x32_bf16 v[4:7], v[60:63], v[56:59], v[4:7]
	ds_read_b128 v[28:31], v28 offset:8704
	ds_read_b128 v[60:63], v54 offset:13056
	v_or_b32_e32 v54, 64, v70
	v_lshl_add_u32 v103, v54, 1, v39
	v_bitop3_b32 v54, v70, v74, 64 bitop3:0x36
	v_lshlrev_b32_e32 v104, 1, v54
	s_waitcnt lgkmcnt(2)
	v_mfma_f32_16x16x32_bf16 v[12:15], v[64:67], v[56:59], v[12:15]
	v_add_u32_e32 v54, v41, v104
	ds_read_b128 v[64:67], v103
	ds_read_b128 v[78:81], v54
	global_load_dwordx2 v[94:95], v[90:91], off offset:32
	s_waitcnt lgkmcnt(3)
	v_mfma_f32_16x16x32_bf16 v[20:23], v[28:31], v[56:59], v[20:23]
	v_add_u32_e32 v28, s90, v32
	v_ashrrev_i32_e32 v29, 31, v28
	v_lshl_add_u64 v[28:29], v[28:29], 2, s[64:65]
	s_waitcnt lgkmcnt(2)
	v_mfma_f32_16x16x32_bf16 v[0:3], v[60:63], v[56:59], v[0:3]
	global_load_dword v54, v[28:29], off
	v_bitop3_b32 v60, v70, v88, 64 bitop3:0x36
	v_lshlrev_b32_e32 v107, 1, v60
	s_waitcnt lgkmcnt(0)
	v_mfma_f32_16x16x32_bf16 v[28:31], v[78:81], v[64:67], v[4:7]
	v_add_u32_e32 v60, v41, v107
	ds_read_b128 v[60:63], v60 offset:13056
	v_bitop3_b32 v56, v70, v89, 64 bitop3:0x36
	v_bitop3_b32 v4, v70, v51, 64 bitop3:0x36
	v_lshlrev_b32_e32 v105, 1, v4
	v_add_u32_e32 v4, v41, v105
	ds_read_b128 v[4:7], v4 offset:4352
	v_lshlrev_b32_e32 v106, 1, v56
	s_waitcnt lgkmcnt(1)
	v_mfma_f32_16x16x32_bf16 v[60:63], v[60:63], v[64:67], v[0:3]
	v_add_u32_e32 v56, v41, v106
	s_nop 1
	v_bitop3_b32 v0, v70, v74, s6 bitop3:0x36
	v_lshlrev_b32_e32 v74, 1, v0
	ds_read_b128 v[56:59], v56 offset:8704
	s_waitcnt lgkmcnt(1)
	v_mfma_f32_16x16x32_bf16 v[78:81], v[4:7], v[64:67], v[12:15]
	v_add_u32_e32 v0, v41, v74
	v_lshl_add_u64 v[4:5], v[84:85], 4, s[0:1]
	v_lshl_add_u64 v[6:7], v[82:83], 4, s[0:1]
	v_or_b32_e32 v12, 0x60, v70
	v_lshl_add_u32 v108, v12, 1, v39
	ds_read_b128 v[12:15], v0
	ds_read_b128 v[82:85], v108
	v_bitop3_b32 v0, v70, v51, s6 bitop3:0x36
	v_lshlrev_b32_e32 v51, 1, v0
	v_add_u32_e32 v0, v41, v51
	s_waitcnt lgkmcnt(2)
	v_mfma_f32_16x16x32_bf16 v[56:59], v[56:59], v[64:67], v[20:23]
	v_mov_b32_e32 v134, v230
	s_lshl_b32 s35, s81, 6
	v_readlane_b32 s10, v254, 29
	ds_read_b128 v[20:23], v0 offset:4352
	global_load_dwordx4 v[0:3], v[4:5], off
	s_nop 0
	global_load_dwordx4 v[4:7], v[6:7], off
	s_waitcnt lgkmcnt(1)
	v_mfma_f32_16x16x32_bf16 v[64:67], v[12:15], v[82:85], v[28:31]
	global_load_dwordx4 v[8:11], v[10:11], off
	s_nop 0
	global_load_dwordx4 v[12:15], v[86:87], off
	ds_read_b128 v[28:31], v16 offset:8704
	v_bitop3_b32 v16, v70, v88, s6 bitop3:0x36
	v_lshlrev_b32_e32 v110, 1, v16
	v_add_u32_e32 v16, v41, v110
	s_waitcnt lgkmcnt(1)
	v_mfma_f32_16x16x32_bf16 v[78:81], v[20:23], v[82:85], v[78:81]
	ds_read_b128 v[86:89], v16 offset:13056
	global_load_dwordx4 v[16:19], v[18:19], off
	s_nop 0
	global_load_dwordx4 v[20:23], v[96:97], off
	v_lshl_add_u64 v[96:97], s[0:1], 0, v[24:25]
	s_waitcnt lgkmcnt(1)
	v_mfma_f32_16x16x32_bf16 v[56:59], v[28:31], v[82:85], v[56:59]
	global_load_dwordx4 v[24:27], v[26:27], off
	s_nop 0
	global_load_dwordx4 v[28:31], v[96:97], off
	s_nop 0
	global_load_dwordx2 v[96:97], v[90:91], off offset:64
	s_nop 0
	global_load_dwordx2 v[90:91], v[90:91], off offset:96
	v_or_b32_e32 v70, s5, v33
	v_lshlrev_b32_e32 v70, 1, v70
	s_waitcnt lgkmcnt(0)
	v_mfma_f32_16x16x32_bf16 v[60:63], v[86:89], v[82:85], v[60:63]
	s_waitcnt vmcnt(12)
	v_lshlrev_b32_e32 v82, 16, v92
	v_and_b32_e32 v83, 0xffff0000, v92
	v_mul_f32_e32 v39, 0x3d372713, v82
	v_fma_f32 v39, v39, v82, 1.0
	v_mul_f32_e32 v41, 0x3d372713, v83
	v_mul_f32_e32 v39, v39, v82
	v_fma_f32 v41, v41, v83, 1.0
	v_mul_f32_e32 v39, 0xc0135761, v39
	v_mul_f32_e32 v41, v41, v83
	v_exp_f32_e32 v39, v39
	v_mul_f32_e32 v41, 0xc0135761, v41
	v_exp_f32_e32 v41, v41
	v_lshlrev_b32_e32 v86, 16, v93
	v_add_f32_e32 v39, 1.0, v39
	v_rcp_f32_e32 v84, v39
	v_add_f32_e32 v39, 1.0, v41
	v_and_b32_e32 v87, 0xffff0000, v93
	v_mul_f32_e32 v41, 0x3d372713, v86
	v_fma_f32 v41, v41, v86, 1.0
	v_mul_f32_e32 v85, 0x3d372713, v87
	v_mul_f32_e32 v41, v41, v86
	v_fma_f32 v85, v85, v87, 1.0
	v_mul_f32_e32 v41, 0xc0135761, v41
	v_mul_f32_e32 v85, v85, v87
	v_exp_f32_e32 v41, v41
	v_mul_f32_e32 v85, 0xc0135761, v85
	v_exp_f32_e32 v89, v85
	v_rcp_f32_e32 v85, v39
	v_add_f32_e32 v39, 1.0, v41
	v_rcp_f32_e32 v88, v39
	v_add_f32_e32 v39, 1.0, v89
	v_rcp_f32_e32 v89, v39
	v_pk_mul_f32 v[82:83], v[84:85], v[82:83]
	s_waitcnt vmcnt(10)
	v_pk_add_f32 v[64:65], v[54:55], v[64:65] op_sel_hi:[0,1]
	v_pk_mul_f32 v[64:65], v[82:83], v[64:65]
	v_pk_mul_f32 v[82:83], v[88:89], v[86:87]
	v_pk_add_f32 v[66:67], v[54:55], v[66:67] op_sel_hi:[0,1]
	v_pk_mul_f32 v[66:67], v[82:83], v[66:67]
	v_lshlrev_b32_e32 v82, 16, v94
	v_and_b32_e32 v83, 0xffff0000, v94
	v_mul_f32_e32 v39, 0x3d372713, v82
	v_fma_f32 v39, v39, v82, 1.0
	v_mul_f32_e32 v41, 0x3d372713, v83
	v_mul_f32_e32 v39, v39, v82
	v_fma_f32 v41, v41, v83, 1.0
	v_mul_f32_e32 v39, 0xc0135761, v39
	v_mul_f32_e32 v41, v41, v83
	v_exp_f32_e32 v39, v39
	v_mul_f32_e32 v41, 0xc0135761, v41
	v_exp_f32_e32 v41, v41
	v_cvt_pk_bf16_f32 v64, v64, v65
	v_cvt_pk_bf16_f32 v65, v66, v67
	v_lshl_add_u64 v[66:67], v[34:35], 0, v[70:71]
	v_add_f32_e32 v39, 1.0, v39
	v_lshlrev_b32_e32 v84, 16, v95
	global_store_dwordx2 v[66:67], v[64:65], off
	v_rcp_f32_e32 v64, v39
	v_add_f32_e32 v39, 1.0, v41
	v_and_b32_e32 v85, 0xffff0000, v95
	v_mul_f32_e32 v41, 0x3d372713, v84
	v_fma_f32 v41, v41, v84, 1.0
	v_mul_f32_e32 v65, 0x3d372713, v85
	v_mul_f32_e32 v41, v41, v84
	v_fma_f32 v65, v65, v85, 1.0
	v_mul_f32_e32 v41, 0xc0135761, v41
	v_mul_f32_e32 v65, v65, v85
	v_exp_f32_e32 v41, v41
	v_mul_f32_e32 v65, 0xc0135761, v65
	v_exp_f32_e32 v70, v65
	v_rcp_f32_e32 v65, v39
	v_add_f32_e32 v39, 1.0, v41
	v_rcp_f32_e32 v86, v39
	v_add_f32_e32 v39, 1.0, v70
	v_rcp_f32_e32 v87, v39
	v_pk_mul_f32 v[64:65], v[64:65], v[82:83]
	v_pk_add_f32 v[78:79], v[54:55], v[78:79] op_sel_hi:[0,1]
	v_pk_mul_f32 v[64:65], v[64:65], v[78:79]
	v_pk_mul_f32 v[78:79], v[86:87], v[84:85]
	v_pk_add_f32 v[80:81], v[54:55], v[80:81] op_sel_hi:[0,1]
	v_pk_mul_f32 v[78:79], v[78:79], v[80:81]
	v_cvt_pk_bf16_f32 v64, v64, v65
	v_cvt_pk_bf16_f32 v65, v78, v79
	s_waitcnt vmcnt(2)
	v_lshlrev_b32_e32 v78, 16, v96
	v_and_b32_e32 v79, 0xffff0000, v96
	v_mul_f32_e32 v39, 0x3d372713, v78
	v_fma_f32 v39, v39, v78, 1.0
	v_mul_f32_e32 v41, 0x3d372713, v79
	v_mul_f32_e32 v39, v39, v78
	v_fma_f32 v41, v41, v79, 1.0
	v_mul_f32_e32 v39, 0xc0135761, v39
	v_mul_f32_e32 v41, v41, v79
	v_exp_f32_e32 v39, v39
	v_mul_f32_e32 v41, 0xc0135761, v41
	v_exp_f32_e32 v41, v41
	v_lshlrev_b32_e32 v80, 16, v97
	v_add_f32_e32 v39, 1.0, v39
	global_store_dwordx2 v[66:67], v[64:65], off offset:32
	v_rcp_f32_e32 v64, v39
	v_add_f32_e32 v39, 1.0, v41
	v_and_b32_e32 v81, 0xffff0000, v97
	v_mul_f32_e32 v41, 0x3d372713, v80
	v_fma_f32 v41, v41, v80, 1.0
	v_mul_f32_e32 v65, 0x3d372713, v81
	v_mul_f32_e32 v41, v41, v80
	v_fma_f32 v65, v65, v81, 1.0
	v_mul_f32_e32 v41, 0xc0135761, v41
	v_mul_f32_e32 v65, v65, v81
	v_exp_f32_e32 v41, v41
	v_mul_f32_e32 v65, 0xc0135761, v65
	v_exp_f32_e32 v70, v65
	v_rcp_f32_e32 v65, v39
	v_add_f32_e32 v39, 1.0, v41
	v_rcp_f32_e32 v82, v39
	v_add_f32_e32 v39, 1.0, v70
	v_rcp_f32_e32 v83, v39
	v_pk_mul_f32 v[64:65], v[64:65], v[78:79]
	v_pk_add_f32 v[56:57], v[54:55], v[56:57] op_sel_hi:[0,1]
	v_pk_mul_f32 v[56:57], v[64:65], v[56:57]
	v_pk_mul_f32 v[64:65], v[82:83], v[80:81]
	v_pk_add_f32 v[58:59], v[54:55], v[58:59] op_sel_hi:[0,1]
	v_pk_mul_f32 v[58:59], v[64:65], v[58:59]
	v_cvt_pk_bf16_f32 v56, v56, v57
	v_cvt_pk_bf16_f32 v57, v58, v59
	s_waitcnt vmcnt(2)
	v_lshlrev_b32_e32 v58, 16, v90
	v_and_b32_e32 v59, 0xffff0000, v90
	v_mul_f32_e32 v39, 0x3d372713, v58
	v_fma_f32 v39, v39, v58, 1.0
	v_mul_f32_e32 v41, 0x3d372713, v59
	v_mul_f32_e32 v39, v39, v58
	v_fma_f32 v41, v41, v59, 1.0
	v_mul_f32_e32 v39, 0xc0135761, v39
	v_mul_f32_e32 v41, v41, v59
	v_exp_f32_e32 v39, v39
	v_mul_f32_e32 v41, 0xc0135761, v41
	v_exp_f32_e32 v41, v41
	v_lshlrev_b32_e32 v64, 16, v91
	v_add_f32_e32 v39, 1.0, v39
	global_store_dwordx2 v[66:67], v[56:57], off offset:64
	v_rcp_f32_e32 v56, v39
	v_add_f32_e32 v39, 1.0, v41
	v_and_b32_e32 v65, 0xffff0000, v91
	v_mul_f32_e32 v41, 0x3d372713, v64
	v_fma_f32 v41, v41, v64, 1.0
	v_mul_f32_e32 v57, 0x3d372713, v65
	v_mul_f32_e32 v41, v41, v64
	v_fma_f32 v57, v57, v65, 1.0
	v_mul_f32_e32 v41, 0xc0135761, v41
	v_mul_f32_e32 v57, v57, v65
	v_exp_f32_e32 v41, v41
	v_mul_f32_e32 v57, 0xc0135761, v57
	v_exp_f32_e32 v70, v57
	v_rcp_f32_e32 v57, v39
	v_add_f32_e32 v39, 1.0, v41
	v_rcp_f32_e32 v78, v39
	v_add_f32_e32 v39, 1.0, v70
	v_rcp_f32_e32 v79, v39
	v_pk_mul_f32 v[56:57], v[56:57], v[58:59]
	v_pk_add_f32 v[58:59], v[54:55], v[60:61] op_sel_hi:[0,1]
	v_pk_mul_f32 v[56:57], v[56:57], v[58:59]
	v_pk_mul_f32 v[58:59], v[78:79], v[64:65]
	v_pk_add_f32 v[60:61], v[54:55], v[62:63] op_sel_hi:[0,1]
	v_pk_mul_f32 v[58:59], v[58:59], v[60:61]
	s_or_b32 s0, s4, 1
	v_cvt_pk_bf16_f32 v56, v56, v57
	v_cvt_pk_bf16_f32 v57, v58, v59
	v_cvt_pk_bf16_f32 v28, v28, v29
	v_cvt_pk_bf16_f32 v29, v30, v31
	v_cvt_pk_bf16_f32 v24, v24, v25
	v_cvt_pk_bf16_f32 v25, v26, v27
	v_cvt_pk_bf16_f32 v20, v20, v21
	v_cvt_pk_bf16_f32 v21, v22, v23
	v_cvt_pk_bf16_f32 v16, v16, v17
	v_cvt_pk_bf16_f32 v17, v18, v19
	v_cvt_pk_bf16_f32 v12, v12, v13
	v_cvt_pk_bf16_f32 v13, v14, v15
	v_cvt_pk_bf16_f32 v8, v8, v9
	v_cvt_pk_bf16_f32 v9, v10, v11
	v_cvt_pk_bf16_f32 v4, v4, v5
	v_cvt_pk_bf16_f32 v5, v6, v7
	v_cvt_pk_bf16_f32 v0, v0, v1
	v_cvt_pk_bf16_f32 v1, v2, v3
	s_lshl_b32 s1, s0, 6
	global_store_dwordx2 v[66:67], v[56:57], off offset:96
	s_barrier
	ds_write_b64 v40, v[28:29]
	ds_write_b64 v38, v[24:25]
	ds_write_b64 v42, v[20:21]
	ds_write_b64 v44, v[16:17]
	ds_write_b64 v46, v[12:13]
	ds_write_b64 v48, v[8:9]
	ds_write_b64 v50, v[4:5]
	ds_write_b64 v52, v[0:1]
	v_or_b32_e32 v0, s1, v55
	v_mad_u32_u24 v40, v0, s79, 0
	v_add_u32_e32 v0, v40, v45
	v_add_u32_e32 v4, v40, v47
	v_add_u32_e32 v16, v40, v49
	v_add_u32_e32 v20, v40, v53
	s_waitcnt lgkmcnt(0)
	s_barrier
	ds_read_b128 v[0:3], v0
	ds_read_b128 v[4:7], v4 offset:4352
	ds_read_b128 v[8:11], v43
	ds_read_b128 v[12:15], v98
	ds_read_b128 v[16:19], v16 offset:8704
	ds_read_b128 v[20:23], v20 offset:13056
	v_add_u32_e32 v24, v40, v99
	ds_read_b128 v[24:27], v24
	s_waitcnt lgkmcnt(4)
	v_mfma_f32_16x16x32_bf16 v[0:3], v[0:3], v[8:11], 0
	s_lshl_b32 s90, s0, 7
	v_lshl_add_u64 v[36:37], v[36:37], 0, s[90:91]
	global_load_dwordx2 v[38:39], v[36:37], off
	v_mfma_f32_16x16x32_bf16 v[4:7], v[4:7], v[8:11], 0
	v_readlane_b32 s11, v254, 30
	s_cmpk_gt_i32 s81, 0x7f
	s_cselect_b64 s[86:87], -1, 0
	s_waitcnt lgkmcnt(2)
	v_mfma_f32_16x16x32_bf16 v[16:19], v[16:19], v[8:11], 0
	s_and_b32 s93, s35, 0x3c0
	s_mov_b64 s[60:61], s[16:17]
	v_readlane_b32 s12, v254, 31
	s_waitcnt lgkmcnt(1)
	v_mfma_f32_16x16x32_bf16 v[8:11], v[20:23], v[8:11], 0
	v_add_u32_e32 v20, v40, v100
	ds_read_b128 v[20:23], v20 offset:4352
	v_readlane_b32 s13, v254, 32
	s_waitcnt lgkmcnt(1)
	v_mfma_f32_16x16x32_bf16 v[0:3], v[24:27], v[12:15], v[0:3]
	v_add_u32_e32 v24, v40, v101
	ds_read_b128 v[24:27], v24 offset:8704
	v_readlane_b32 s14, v254, 33
	s_waitcnt lgkmcnt(1)
	v_mfma_f32_16x16x32_bf16 v[4:7], v[20:23], v[12:15], v[4:7]
	v_add_u32_e32 v20, v40, v102
	ds_read_b128 v[20:23], v20 offset:13056
	v_readlane_b32 s15, v254, 34
	s_waitcnt lgkmcnt(1)
	v_mfma_f32_16x16x32_bf16 v[16:19], v[24:27], v[12:15], v[16:19]
	v_add_u32_e32 v24, v40, v104
	ds_read_b128 v[24:27], v24
	s_waitcnt lgkmcnt(1)
	v_mfma_f32_16x16x32_bf16 v[8:11], v[20:23], v[12:15], v[8:11]
	v_add_u32_e32 v12, v40, v105
	ds_read_b128 v[12:15], v12 offset:4352
	ds_read_b128 v[20:23], v103
	ds_read_b128 v[28:31], v108
	s_waitcnt lgkmcnt(1)
	v_mfma_f32_16x16x32_bf16 v[0:3], v[24:27], v[20:23], v[0:3]
	v_add_u32_e32 v24, v40, v106
	ds_read_b128 v[24:27], v24 offset:8704
	v_mfma_f32_16x16x32_bf16 v[4:7], v[12:15], v[20:23], v[4:7]
	v_add_u32_e32 v12, v40, v107
	ds_read_b128 v[12:15], v12 offset:13056
	s_waitcnt lgkmcnt(1)
	v_mfma_f32_16x16x32_bf16 v[16:19], v[24:27], v[20:23], v[16:19]
	v_add_u32_e32 v24, v40, v74
	ds_read_b128 v[24:27], v24
	s_waitcnt lgkmcnt(1)
	v_mfma_f32_16x16x32_bf16 v[8:11], v[12:15], v[20:23], v[8:11]
	v_add_u32_e32 v12, v40, v51
	ds_read_b128 v[12:15], v12 offset:4352
	s_waitcnt lgkmcnt(1)
	v_mfma_f32_16x16x32_bf16 v[20:23], v[24:27], v[28:31], v[0:3]
	s_nop 2
	v_add_u32_e32 v0, s90, v32
	v_ashrrev_i32_e32 v1, 31, v0
	v_lshl_add_u64 v[0:1], v[0:1], 2, s[64:65]
	s_waitcnt lgkmcnt(0)
	v_mfma_f32_16x16x32_bf16 v[2:5], v[12:15], v[28:31], v[4:7]
	global_load_dword v0, v[0:1], off
	v_add_u32_e32 v1, v40, v110
	ds_read_b128 v[24:27], v1 offset:13056
	v_add_u32_e32 v6, v40, v109
	ds_read_b128 v[12:15], v6 offset:8704
	s_waitcnt lgkmcnt(0)
	v_mfma_f32_16x16x32_bf16 v[12:15], v[12:15], v[28:31], v[16:19]
	s_nop 2
	global_load_dwordx2 v[16:17], v[36:37], off offset:32
	global_load_dwordx2 v[18:19], v[36:37], off offset:64
	s_nop 0
	global_load_dwordx2 v[36:37], v[36:37], off offset:96
	s_and_b32 s90, s35, 0xc0
	s_cmpk_lt_i32 s81, 0x80
	v_mfma_f32_16x16x32_bf16 v[6:9], v[24:27], v[28:31], v[8:11]
	s_waitcnt vmcnt(4)
	v_lshlrev_b32_e32 v26, 16, v39
	v_and_b32_e32 v27, 0xffff0000, v39
	v_or_b32_e32 v30, s1, v33
	v_lshlrev_b32_e32 v10, 16, v38
	v_and_b32_e32 v11, 0xffff0000, v38
	v_mul_f32_e32 v1, 0x3d372713, v10
	v_fma_f32 v1, v1, v10, 1.0
	v_mul_f32_e32 v24, 0x3d372713, v11
	v_mul_f32_e32 v1, v1, v10
	v_fma_f32 v24, v24, v11, 1.0
	v_mul_f32_e32 v1, 0xc0135761, v1
	v_mul_f32_e32 v24, v24, v11
	v_exp_f32_e32 v1, v1
	v_mul_f32_e32 v24, 0xc0135761, v24
	v_exp_f32_e32 v25, v24
	v_lshlrev_b32_e32 v70, 1, v30
	v_add_f32_e32 v1, 1.0, v1
	v_rcp_f32_e32 v24, v1
	v_add_f32_e32 v1, 1.0, v25
	v_mul_f32_e32 v25, 0x3d372713, v26
	v_fma_f32 v25, v25, v26, 1.0
	v_mul_f32_e32 v25, v25, v26
	v_mul_f32_e32 v25, 0xc0135761, v25
	v_exp_f32_e32 v28, v25
	v_mul_f32_e32 v25, 0x3d372713, v27
	v_fma_f32 v25, v25, v27, 1.0
	v_mul_f32_e32 v25, v25, v27
	v_mul_f32_e32 v25, 0xc0135761, v25
	v_exp_f32_e32 v29, v25
	v_rcp_f32_e32 v25, v1
	v_add_f32_e32 v1, 1.0, v28
	v_rcp_f32_e32 v28, v1
	v_add_f32_e32 v1, 1.0, v29
	v_rcp_f32_e32 v29, v1
	v_pk_mul_f32 v[10:11], v[24:25], v[10:11]
	s_cselect_b64 s[4:5], -1, 0
	s_and_b64 vcc, s[4:5], exec
	s_cselect_b32 s20, s90, s93
	s_waitcnt vmcnt(3)
	v_pk_add_f32 v[20:21], v[0:1], v[20:21] op_sel_hi:[0,1]
	v_pk_mul_f32 v[10:11], v[10:11], v[20:21]
	v_pk_mul_f32 v[20:21], v[28:29], v[26:27]
	v_pk_add_f32 v[22:23], v[0:1], v[22:23] op_sel_hi:[0,1]
	v_pk_mul_f32 v[20:21], v[20:21], v[22:23]
	v_cvt_pk_bf16_f32 v10, v10, v11
	v_cvt_pk_bf16_f32 v11, v20, v21
	v_lshl_add_u64 v[20:21], v[34:35], 0, v[70:71]
	global_store_dwordx2 v[20:21], v[10:11], off
	s_waitcnt vmcnt(3)
	v_lshlrev_b32_e32 v22, 16, v16
	v_and_b32_e32 v23, 0xffff0000, v16
	v_mul_f32_e32 v1, 0x3d372713, v22
	v_fma_f32 v1, v1, v22, 1.0
	v_mul_f32_e32 v16, 0x3d372713, v23
	v_mul_f32_e32 v1, v1, v22
	v_fma_f32 v16, v16, v23, 1.0
	v_mul_f32_e32 v1, 0xc0135761, v1
	v_mul_f32_e32 v16, v16, v23
	v_exp_f32_e32 v1, v1
	v_mul_f32_e32 v16, 0xc0135761, v16
	v_exp_f32_e32 v16, v16
	v_add_f32_e32 v1, 1.0, v1
	v_rcp_f32_e32 v10, v1
	v_add_f32_e32 v1, 1.0, v16
	v_lshlrev_b32_e32 v16, 16, v17
	v_mul_f32_e32 v11, 0x3d372713, v16
	v_fma_f32 v11, v11, v16, 1.0
	v_mul_f32_e32 v11, v11, v16
	v_and_b32_e32 v17, 0xffff0000, v17
	v_mul_f32_e32 v11, 0xc0135761, v11
	v_exp_f32_e32 v24, v11
	v_mul_f32_e32 v11, 0x3d372713, v17
	v_fma_f32 v11, v11, v17, 1.0
	v_mul_f32_e32 v11, v11, v17
	v_mul_f32_e32 v11, 0xc0135761, v11
	v_exp_f32_e32 v25, v11
	v_rcp_f32_e32 v11, v1
	v_add_f32_e32 v1, 1.0, v24
	v_rcp_f32_e32 v24, v1
	v_add_f32_e32 v1, 1.0, v25
	v_rcp_f32_e32 v25, v1
	v_pk_mul_f32 v[10:11], v[10:11], v[22:23]
	v_pk_add_f32 v[2:3], v[0:1], v[2:3] op_sel_hi:[0,1]
	v_pk_mul_f32 v[2:3], v[10:11], v[2:3]
	v_pk_mul_f32 v[10:11], v[24:25], v[16:17]
	v_pk_add_f32 v[4:5], v[0:1], v[4:5] op_sel_hi:[0,1]
	v_pk_mul_f32 v[4:5], v[10:11], v[4:5]
	v_cvt_pk_bf16_f32 v2, v2, v3
	v_cvt_pk_bf16_f32 v3, v4, v5
	s_waitcnt vmcnt(2)
	v_lshlrev_b32_e32 v4, 16, v18
	v_and_b32_e32 v5, 0xffff0000, v18
	v_mul_f32_e32 v1, 0x3d372713, v4
	v_fma_f32 v1, v1, v4, 1.0
	v_mul_f32_e32 v10, 0x3d372713, v5
	v_mul_f32_e32 v1, v1, v4
	v_fma_f32 v10, v10, v5, 1.0
	v_mul_f32_e32 v1, 0xc0135761, v1
	v_mul_f32_e32 v10, v10, v5
	v_exp_f32_e32 v1, v1
	v_mul_f32_e32 v10, 0xc0135761, v10
	v_exp_f32_e32 v10, v10
	global_store_dwordx2 v[20:21], v[2:3], off offset:32
	v_add_f32_e32 v1, 1.0, v1
	v_rcp_f32_e32 v2, v1
	v_add_f32_e32 v1, 1.0, v10
	v_lshlrev_b32_e32 v10, 16, v19
	v_mul_f32_e32 v3, 0x3d372713, v10
	v_fma_f32 v3, v3, v10, 1.0
	v_mul_f32_e32 v3, v3, v10
	v_and_b32_e32 v11, 0xffff0000, v19
	v_mul_f32_e32 v3, 0xc0135761, v3
	v_exp_f32_e32 v16, v3
	v_mul_f32_e32 v3, 0x3d372713, v11
	v_fma_f32 v3, v3, v11, 1.0
	v_mul_f32_e32 v3, v3, v11
	v_mul_f32_e32 v3, 0xc0135761, v3
	v_exp_f32_e32 v17, v3
	v_rcp_f32_e32 v3, v1
	v_add_f32_e32 v1, 1.0, v16
	v_rcp_f32_e32 v16, v1
	v_add_f32_e32 v1, 1.0, v17
	v_rcp_f32_e32 v17, v1
	v_pk_mul_f32 v[2:3], v[2:3], v[4:5]
	v_pk_add_f32 v[4:5], v[0:1], v[12:13] op_sel_hi:[0,1]
	v_pk_mul_f32 v[2:3], v[2:3], v[4:5]
	v_pk_mul_f32 v[4:5], v[16:17], v[10:11]
	v_pk_add_f32 v[10:11], v[0:1], v[14:15] op_sel_hi:[0,1]
	v_pk_mul_f32 v[4:5], v[4:5], v[10:11]
	v_cvt_pk_bf16_f32 v2, v2, v3
	v_cvt_pk_bf16_f32 v3, v4, v5
	s_waitcnt vmcnt(2)
	v_lshlrev_b32_e32 v4, 16, v36
	v_and_b32_e32 v5, 0xffff0000, v36
	v_mul_f32_e32 v1, 0x3d372713, v4
	v_fma_f32 v1, v1, v4, 1.0
	v_mul_f32_e32 v10, 0x3d372713, v5
	v_mul_f32_e32 v1, v1, v4
	v_fma_f32 v10, v10, v5, 1.0
	v_mul_f32_e32 v1, 0xc0135761, v1
	v_mul_f32_e32 v10, v10, v5
	v_exp_f32_e32 v1, v1
	v_mul_f32_e32 v10, 0xc0135761, v10
	v_exp_f32_e32 v10, v10
	global_store_dwordx2 v[20:21], v[2:3], off offset:64
	v_add_f32_e32 v1, 1.0, v1
	v_rcp_f32_e32 v2, v1
	v_add_f32_e32 v1, 1.0, v10
	v_lshlrev_b32_e32 v10, 16, v37
	v_mul_f32_e32 v3, 0x3d372713, v10
	v_fma_f32 v3, v3, v10, 1.0
	v_mul_f32_e32 v3, v3, v10
	v_and_b32_e32 v11, 0xffff0000, v37
	v_mul_f32_e32 v3, 0xc0135761, v3
	v_exp_f32_e32 v12, v3
	v_mul_f32_e32 v3, 0x3d372713, v11
	v_fma_f32 v3, v3, v11, 1.0
	v_mul_f32_e32 v3, v3, v11
	v_mul_f32_e32 v3, 0xc0135761, v3
	v_exp_f32_e32 v13, v3
	v_rcp_f32_e32 v3, v1
	v_add_f32_e32 v1, 1.0, v12
	v_rcp_f32_e32 v12, v1
	v_add_f32_e32 v1, 1.0, v13
	v_rcp_f32_e32 v13, v1
	v_pk_mul_f32 v[2:3], v[2:3], v[4:5]
	v_pk_add_f32 v[4:5], v[0:1], v[6:7] op_sel_hi:[0,1]
	v_pk_mul_f32 v[2:3], v[2:3], v[4:5]
	v_pk_mul_f32 v[4:5], v[12:13], v[10:11]
	v_pk_add_f32 v[0:1], v[0:1], v[8:9] op_sel_hi:[0,1]
	v_pk_mul_f32 v[0:1], v[4:5], v[0:1]
	v_cvt_pk_bf16_f32 v2, v2, v3
	v_cvt_pk_bf16_f32 v3, v0, v1
	global_store_dwordx2 v[20:21], v[2:3], off offset:96
	s_barrier
	s_barrier
	v_mov_b32_e32 v9, v71
	v_ashrrev_i32_e32 v78, 3, v134
	v_ashrrev_i32_e32 v79, 7, v134
	v_add_u32_e32 v115, 64, v78
	v_add_u32_e32 v86, s35, v79
	v_lshlrev_b32_e32 v2, 7, v78
	v_ashrrev_i32_e32 v116, 4, v115
	v_and_b32_e32 v135, 7, v134
	v_mad_i64_i32 v[0:1], s[0:1], v86, s33, v[76:77]
	v_and_b32_e32 v70, 0x780, v2
	v_add_u32_e32 v114, s35, v116
	v_lshl_add_u64 v[0:1], v[0:1], 0, v[70:71]
	v_lshlrev_b32_e32 v8, 4, v135
	v_mad_i64_i32 v[2:3], s[0:1], v114, s33, v[76:77]
	v_lshl_add_u64 v[0:1], v[0:1], 0, v[8:9]
	v_lshl_add_u64 v[2:3], v[2:3], 0, v[70:71]
	v_lshl_add_u64 v[4:5], v[2:3], 0, v[8:9]
	global_load_dwordx4 v[0:3], v[0:1], off offset:3072
	s_nop 0
	global_load_dwordx4 v[64:67], v[4:5], off offset:3072
	v_add_u32_e32 v113, 0x80, v78
	v_ashrrev_i32_e32 v152, 4, v113
	v_add_u32_e32 v111, 0xc0, v78
	v_add_u32_e32 v112, s35, v152
	v_ashrrev_i32_e32 v151, 4, v111
	v_mad_i64_i32 v[4:5], s[0:1], v112, s33, v[76:77]
	v_add_u32_e32 v110, s35, v151
	v_add_u32_e32 v109, 0x100, v78
	v_lshl_add_u64 v[4:5], v[4:5], 0, v[70:71]
	v_mad_i64_i32 v[6:7], s[0:1], v110, s33, v[76:77]
	v_ashrrev_i32_e32 v150, 4, v109
	v_add_u32_e32 v107, 0x140, v78
	v_lshl_add_u64 v[4:5], v[4:5], 0, v[8:9]
	v_lshl_add_u64 v[6:7], v[6:7], 0, v[70:71]
	v_add_u32_e32 v108, s35, v150
	v_ashrrev_i32_e32 v149, 4, v107
	v_lshl_add_u64 v[6:7], v[6:7], 0, v[8:9]
	global_load_dwordx4 v[60:63], v[4:5], off offset:3072
	global_load_dwordx4 v[56:59], v[6:7], off offset:3072
	v_mad_i64_i32 v[4:5], s[0:1], v108, s33, v[76:77]
	v_add_u32_e32 v106, s35, v149
	v_add_u32_e32 v105, 0x180, v78
	v_lshl_add_u64 v[4:5], v[4:5], 0, v[70:71]
	v_mad_i64_i32 v[6:7], s[0:1], v106, s33, v[76:77]
	v_ashrrev_i32_e32 v148, 4, v105
	v_add_u32_e32 v103, 0x1c0, v78
	v_lshl_add_u64 v[4:5], v[4:5], 0, v[8:9]
	v_lshl_add_u64 v[6:7], v[6:7], 0, v[70:71]
	v_add_u32_e32 v104, s35, v148
	v_ashrrev_i32_e32 v147, 4, v103
	v_lshl_add_u64 v[6:7], v[6:7], 0, v[8:9]
	global_load_dwordx4 v[52:55], v[4:5], off offset:3072
	global_load_dwordx4 v[48:51], v[6:7], off offset:3072
	v_mad_i64_i32 v[4:5], s[0:1], v104, s33, v[76:77]
	v_add_u32_e32 v102, s35, v147
	v_add_u32_e32 v101, 0x200, v78
	v_lshl_add_u64 v[4:5], v[4:5], 0, v[70:71]
	v_mad_i64_i32 v[6:7], s[0:1], v102, s33, v[76:77]
	v_ashrrev_i32_e32 v146, 4, v101
	v_add_u32_e32 v99, 0x240, v78
	v_lshl_add_u64 v[4:5], v[4:5], 0, v[8:9]
	v_lshl_add_u64 v[6:7], v[6:7], 0, v[70:71]
	v_add_u32_e32 v100, s35, v146
	v_ashrrev_i32_e32 v145, 4, v99
	v_lshl_add_u64 v[6:7], v[6:7], 0, v[8:9]
	global_load_dwordx4 v[44:47], v[4:5], off offset:3072
	global_load_dwordx4 v[40:43], v[6:7], off offset:3072
	v_mad_i64_i32 v[4:5], s[0:1], v100, s33, v[76:77]
	v_add_u32_e32 v98, s35, v145
	v_add_u32_e32 v97, 0x280, v78
	v_lshl_add_u64 v[4:5], v[4:5], 0, v[70:71]
	v_mad_i64_i32 v[6:7], s[0:1], v98, s33, v[76:77]
	v_ashrrev_i32_e32 v144, 4, v97
	v_lshl_add_u64 v[4:5], v[4:5], 0, v[8:9]
	v_lshl_add_u64 v[6:7], v[6:7], 0, v[70:71]
	v_add_u32_e32 v96, s35, v144
	v_add_u32_e32 v95, 0x2c0, v78
	v_lshl_add_u64 v[6:7], v[6:7], 0, v[8:9]
	global_load_dwordx4 v[36:39], v[4:5], off offset:3072
	global_load_dwordx4 v[32:35], v[6:7], off offset:3072
	v_mad_i64_i32 v[4:5], s[0:1], v96, s33, v[76:77]
	v_ashrrev_i32_e32 v143, 4, v95
	v_lshl_add_u64 v[4:5], v[4:5], 0, v[70:71]
	v_add_u32_e32 v94, s35, v143
	v_add_u32_e32 v93, 0x300, v78
	v_lshl_add_u64 v[10:11], v[4:5], 0, v[8:9]
	v_mad_i64_i32 v[4:5], s[0:1], v94, s33, v[76:77]
	v_ashrrev_i32_e32 v142, 4, v93
	v_add_u32_e32 v91, 0x340, v78
	v_lshl_add_u64 v[4:5], v[4:5], 0, v[70:71]
	v_add_u32_e32 v92, s35, v142
	v_ashrrev_i32_e32 v141, 4, v91
	v_add_u32_e32 v89, 0x380, v78
	v_lshl_add_u64 v[12:13], v[4:5], 0, v[8:9]
	v_mad_i64_i32 v[4:5], s[0:1], v92, s33, v[76:77]
	v_add_u32_e32 v90, s35, v141
	v_ashrrev_i32_e32 v140, 4, v89
	v_add_u32_e32 v137, 0x3c0, v78
	v_lshl_add_u64 v[14:15], v[4:5], 0, v[70:71]
	v_mad_i64_i32 v[4:5], s[0:1], v90, s33, v[76:77]
	v_add_u32_e32 v88, s35, v140
	v_ashrrev_i32_e32 v139, 4, v137
	v_lshl_add_u64 v[16:17], v[4:5], 0, v[70:71]
	v_mad_i64_i32 v[4:5], s[0:1], v88, s33, v[76:77]
	v_add_u32_e32 v74, s35, v139
	v_lshl_add_u64 v[84:85], v[4:5], 0, v[70:71]
	v_mad_i64_i32 v[4:5], s[0:1], v74, s33, v[76:77]
	v_and_b32_e32 v87, 15, v78
	v_lshl_add_u64 v[118:119], v[4:5], 0, v[70:71]
	v_mov_b32_e32 v4, s43
	v_mov_b32_e32 v5, s41
	v_subrev_co_u32_e64 v76, s[0:1], 8, v87
	v_mov_b32_e32 v6, s40
	s_nop 0
	v_cndmask_b32_e64 v5, v4, v5, s[0:1]
	v_mov_b32_e32 v4, s42
	v_cndmask_b32_e64 v4, v4, v6, s[0:1]
	v_lshlrev_b32_e32 v70, 5, v135
	v_lshl_add_u64 v[18:19], v[4:5], 0, v[70:71]
	global_load_dwordx4 v[4:7], v[18:19], off offset:16
	global_load_dwordx4 v[80:83], v[18:19], off
	global_load_dwordx4 v[28:31], v[10:11], off offset:3072
	global_load_dwordx4 v[24:27], v[12:13], off offset:3072
	v_lshl_add_u64 v[10:11], v[14:15], 0, v[8:9]
	v_lshl_add_u64 v[12:13], v[16:17], 0, v[8:9]
	global_load_dwordx4 v[20:23], v[10:11], off offset:3072
	global_load_dwordx4 v[16:19], v[12:13], off offset:3072
	v_lshl_add_u64 v[10:11], v[84:85], 0, v[8:9]
	v_lshl_add_u64 v[8:9], v[118:119], 0, v[8:9]
	global_load_dwordx4 v[12:15], v[10:11], off offset:3072
	s_nop 0
	global_load_dwordx4 v[8:11], v[8:9], off offset:3072
	s_waitcnt vmcnt(17)
	v_lshlrev_b32_e32 v118, 16, v0
	v_and_b32_e32 v119, 0xffff0000, v0
	v_pk_mul_f32 v[84:85], v[118:119], v[118:119]
	v_lshlrev_b32_e32 v154, 16, v1
	v_and_b32_e32 v155, 0xffff0000, v1
	v_pk_mul_f32 v[0:1], v[154:155], v[154:155]
	v_add_f32_e32 v70, v84, v85
	v_lshlrev_b32_e32 v156, 16, v2
	v_and_b32_e32 v157, 0xffff0000, v2
	v_add_f32_e32 v0, v0, v70
	v_pk_mul_f32 v[158:159], v[156:157], v[156:157]
	v_add_f32_e32 v0, v1, v0
	v_lshlrev_b32_e32 v160, 16, v3
	v_and_b32_e32 v161, 0xffff0000, v3
	v_add_f32_e32 v0, v158, v0
	v_pk_mul_f32 v[2:3], v[160:161], v[160:161]
	v_add_f32_e32 v0, v159, v0
	v_add_f32_e32 v0, v2, v0
	v_add_f32_e32 v0, v3, v0
	ds_bpermute_b32 v1, v132, v0
	v_lshlrev_b32_e32 v136, 4, v134
	v_cmp_gt_u32_e64 s[8:9], 4, v135
	v_and_b32_e32 v138, 16, v136
	v_add_u32_e32 v84, s20, v79
	s_waitcnt lgkmcnt(0)
	v_add_f32_e32 v0, v0, v1
	ds_bpermute_b32 v1, v75, v0
	s_waitcnt lgkmcnt(0)
	v_add_f32_e32 v0, v0, v1
	ds_bpermute_b32 v1, v133, v0
	s_waitcnt lgkmcnt(0)
	v_add_f32_e32 v0, v0, v1
	v_fmamk_f32 v0, v0, 0x3c800000, v127
	v_mul_f32_e32 v1, 0x4b800000, v0
	v_cmp_gt_f32_e64 s[10:11], s82, v0
	s_nop 1
	v_cndmask_b32_e64 v0, v0, v1, s[10:11]
	v_rsq_f32_e32 v0, v0
	v_and_b32_e32 v1, 2, v134
	v_cmp_eq_u32_e64 s[6:7], 0, v1
	v_mul_f32_e32 v1, 0x45800000, v0
	v_cndmask_b32_e64 v70, v0, v1, s[10:11]
	v_pk_mul_f32 v[0:1], v[70:71], v[118:119] op_sel_hi:[0,1]
	v_pk_mul_f32 v[2:3], v[70:71], v[154:155] op_sel_hi:[0,1]
	s_waitcnt vmcnt(6)
	v_mov_b32_e32 v168, v80
	v_mov_b32_e32 v169, v81
	v_mov_b32_e32 v170, v82
	v_mov_b32_e32 v171, v83
	v_mov_b32_e32 v172, v4
	v_mov_b32_e32 v173, v5
	v_mov_b32_e32 v174, v6
	v_mov_b32_e32 v175, v7
	v_pk_mul_f32 v[0:1], v[80:81], v[0:1]
	v_pk_mul_f32 v[80:81], v[70:71], v[156:157] op_sel_hi:[0,1]
	v_pk_mul_f32 v[4:5], v[4:5], v[80:81]
	v_pk_mul_f32 v[80:81], v[70:71], v[160:161] op_sel_hi:[0,1]
	v_pk_mul_f32 v[2:3], v[82:83], v[2:3]
	v_pk_mul_f32 v[6:7], v[6:7], v[80:81]
	s_cbranch_vccnz .LBB0_371
	v_ashrrev_i32_e32 v70, 6, v84
	v_bfe_u32 v77, v134, 7, 6
	v_cndmask_b32_e64 v70, v77, v70, s[8:9]
	v_lshl_or_b32 v80, v70, 5, v138
	v_ashrrev_i32_e32 v81, 31, v80
	v_lshl_add_u64 v[118:119], v[80:81], 2, s[56:57]
	v_mov_b32_e32 v194, 0x200
	v_mov_b32_e32 v195, 0
	v_cndmask_b32_e64 v194, v194, 0, s[8:9]
	v_mov_b32_e32 v192, v118
	v_mov_b32_e32 v193, v119
	global_load_dwordx4 v[80:83], v[118:119], off offset:48
	global_load_dwordx4 v[154:157], v[118:119], off offset:32
	global_load_dwordx4 v[158:161], v[118:119], off offset:16
	global_load_dwordx4 v[162:165], v[118:119], off
	ds_bpermute_b32 v166, v75, v0
	ds_bpermute_b32 v167, v75, v1
	s_waitcnt vmcnt(0)
	v_lshl_add_u64 v[192:193], v[192:193], 0, v[194:195]
	global_load_dwordx4 v[188:191], v[192:193], off offset:48
	global_load_dwordx4 v[184:187], v[192:193], off offset:32
	global_load_dwordx4 v[180:183], v[192:193], off offset:16
	global_load_dwordx4 v[176:179], v[192:193], off
	v_mov_b32_e32 v119, v164
	v_mov_b32_e32 v164, v163
	v_mov_b32_e32 v118, v162
	s_waitcnt lgkmcnt(0)
	v_pk_mul_f32 v[162:163], v[164:165], v[166:167]
	s_nop 0
	v_cndmask_b32_e64 v163, v163, -v163, s[6:7]
	v_cndmask_b32_e64 v162, v162, -v162, s[6:7]
	v_pk_fma_f32 v[0:1], v[0:1], v[118:119], v[162:163]
	ds_bpermute_b32 v118, v75, v2
	ds_bpermute_b32 v119, v75, v3
	v_mov_b32_e32 v163, v160
	v_mov_b32_e32 v160, v159
	v_mov_b32_e32 v162, v158
	v_mov_b32_e32 v159, v156
	s_waitcnt lgkmcnt(0)
	v_pk_mul_f32 v[118:119], v[160:161], v[118:119]
	v_mov_b32_e32 v156, v155
	v_cndmask_b32_e64 v119, v119, -v119, s[6:7]
	v_cndmask_b32_e64 v118, v118, -v118, s[6:7]
	v_pk_fma_f32 v[2:3], v[2:3], v[162:163], v[118:119]
	ds_bpermute_b32 v118, v75, v4
	ds_bpermute_b32 v119, v75, v5
	v_mov_b32_e32 v158, v154
	v_mov_b32_e32 v155, v82
	v_mov_b32_e32 v82, v81
	v_mov_b32_e32 v154, v80
	s_waitcnt lgkmcnt(0)
	v_pk_mul_f32 v[118:119], v[156:157], v[118:119]
	s_nop 0
	v_cndmask_b32_e64 v119, v119, -v119, s[6:7]
	v_cndmask_b32_e64 v118, v118, -v118, s[6:7]
	v_pk_fma_f32 v[4:5], v[4:5], v[158:159], v[118:119]
	ds_bpermute_b32 v118, v75, v6
	ds_bpermute_b32 v119, v75, v7
	s_waitcnt lgkmcnt(0)
	v_pk_mul_f32 v[80:81], v[82:83], v[118:119]
	s_nop 0
	v_cndmask_b32_e64 v81, v81, -v81, s[6:7]
	v_cndmask_b32_e64 v80, v80, -v80, s[6:7]
	v_pk_fma_f32 v[6:7], v[6:7], v[154:155], v[80:81]

.LBB0_377:
	s_or_b64 exec, exec, s[0:1]
	v_lshlrev_b32_e32 v86, 2, v117
	v_mov_b32_e32 v87, v71
	v_lshl_add_u64 v[0:1], v[118:119], 0, v[86:87]
	v_mov_b32_e32 v4, v172
	v_mov_b32_e32 v5, v173
	v_mov_b32_e32 v6, v174
	v_mov_b32_e32 v7, v175
	s_nop 0
	v_mov_b32_e32 v0, v168
	v_mov_b32_e32 v1, v169
	v_mov_b32_e32 v2, v170
	v_mov_b32_e32 v3, v171
	v_lshlrev_b32_e32 v118, 16, v64
	v_and_b32_e32 v119, 0xffff0000, v64
	v_pk_mul_f32 v[154:155], v[118:119], v[118:119]
	v_lshlrev_b32_e32 v64, 16, v65
	v_and_b32_e32 v65, 0xffff0000, v65
	v_pk_mul_f32 v[156:157], v[64:65], v[64:65]
	v_add_f32_e32 v79, v154, v155
	v_lshlrev_b32_e32 v158, 16, v66
	v_and_b32_e32 v159, 0xffff0000, v66
	v_add_f32_e32 v79, v156, v79
	v_pk_mul_f32 v[160:161], v[158:159], v[158:159]
	v_add_f32_e32 v79, v157, v79
	v_lshlrev_b32_e32 v66, 16, v67
	v_and_b32_e32 v67, 0xffff0000, v67
	v_add_f32_e32 v79, v160, v79
	v_pk_mul_f32 v[162:163], v[66:67], v[66:67]
	v_add_f32_e32 v79, v161, v79
	v_add_f32_e32 v79, v162, v79
	v_add_f32_e32 v79, v163, v79
	ds_bpermute_b32 v87, v132, v79
	v_add_u32_e32 v116, s20, v116
	s_waitcnt lgkmcnt(0)
	v_add_f32_e32 v79, v79, v87
	ds_bpermute_b32 v87, v75, v79
	s_waitcnt lgkmcnt(0)
	v_add_f32_e32 v79, v79, v87
	ds_bpermute_b32 v87, v133, v79
	s_waitcnt lgkmcnt(0)
	v_add_f32_e32 v79, v79, v87
	v_fmamk_f32 v79, v79, 0x3c800000, v127
	v_cmp_gt_f32_e32 vcc, s82, v79
	v_mul_f32_e32 v87, 0x4b800000, v79
	s_nop 0
	v_cndmask_b32_e32 v79, v79, v87, vcc
	v_rsq_f32_e32 v79, v79
	s_nop 0
	v_mul_f32_e32 v87, 0x45800000, v79
	v_cndmask_b32_e32 v154, v79, v87, vcc
	v_pk_mul_f32 v[64:65], v[154:155], v[64:65] op_sel_hi:[0,1]
	v_pk_mul_f32 v[118:119], v[154:155], v[118:119] op_sel_hi:[0,1]
	s_andn2_b64 vcc, exec, s[86:87]
	s_waitcnt vmcnt(0)
	v_pk_mul_f32 v[2:3], v[2:3], v[64:65]
	v_pk_mul_f32 v[64:65], v[154:155], v[158:159] op_sel_hi:[0,1]
	v_pk_mul_f32 v[4:5], v[4:5], v[64:65]
	v_pk_mul_f32 v[64:65], v[154:155], v[66:67] op_sel_hi:[0,1]
	v_pk_mul_f32 v[6:7], v[6:7], v[64:65]
	v_cndmask_b32_e64 v64, 0, 1, s[86:87]
	v_pk_mul_f32 v[0:1], v[0:1], v[118:119]
	v_cmp_ne_u32_e64 s[0:1], 1, v64
	s_cbranch_vccnz .LBB0_466
	v_ashrrev_i32_e32 v64, 6, v116
	v_bfe_u32 v65, v115, 4, 6
	v_cndmask_b32_e64 v64, v65, v64, s[8:9]
	v_lshl_or_b32 v64, v64, 5, v138
	v_ashrrev_i32_e32 v65, 31, v64
	v_lshl_add_u64 v[118:119], v[64:65], 2, s[56:57]
	s_waitcnt vmcnt(1)
	v_mov_b32_e32 v64, v188
	v_mov_b32_e32 v65, v189
	v_mov_b32_e32 v66, v190
	v_mov_b32_e32 v67, v191
	v_mov_b32_e32 v154, v184
	v_mov_b32_e32 v155, v185
	v_mov_b32_e32 v156, v186
	v_mov_b32_e32 v157, v187
	v_mov_b32_e32 v158, v180
	v_mov_b32_e32 v159, v181
	v_mov_b32_e32 v160, v182
	v_mov_b32_e32 v161, v183
	v_mov_b32_e32 v162, v176
	v_mov_b32_e32 v163, v177
	v_mov_b32_e32 v164, v178
	v_mov_b32_e32 v165, v179
	v_lshl_add_u64 v[192:193], v[192:193], 0, v[194:195]
	global_load_dwordx4 v[188:191], v[192:193], off offset:48
	global_load_dwordx4 v[184:187], v[192:193], off offset:32
	global_load_dwordx4 v[180:183], v[192:193], off offset:16
	global_load_dwordx4 v[176:179], v[192:193], off
	ds_bpermute_b32 v166, v75, v0
	ds_bpermute_b32 v167, v75, v1
	v_mov_b32_e32 v119, v164
	v_mov_b32_e32 v164, v163
	v_mov_b32_e32 v118, v162
	s_waitcnt lgkmcnt(0)
	v_pk_mul_f32 v[162:163], v[164:165], v[166:167]
	s_nop 0
	v_cndmask_b32_e64 v163, v163, -v163, s[6:7]
	v_cndmask_b32_e64 v162, v162, -v162, s[6:7]
	v_pk_fma_f32 v[0:1], v[0:1], v[118:119], v[162:163]
	ds_bpermute_b32 v118, v75, v2
	ds_bpermute_b32 v119, v75, v3
	v_mov_b32_e32 v163, v160
	v_mov_b32_e32 v160, v159
	v_mov_b32_e32 v162, v158
	v_mov_b32_e32 v159, v156
	s_waitcnt lgkmcnt(0)
	v_pk_mul_f32 v[118:119], v[160:161], v[118:119]
	v_mov_b32_e32 v156, v155
	v_cndmask_b32_e64 v119, v119, -v119, s[6:7]
	v_cndmask_b32_e64 v118, v118, -v118, s[6:7]
	v_pk_fma_f32 v[2:3], v[2:3], v[162:163], v[118:119]
	ds_bpermute_b32 v118, v75, v4
	ds_bpermute_b32 v119, v75, v5
	v_mov_b32_e32 v158, v154
	v_mov_b32_e32 v155, v66
	v_mov_b32_e32 v66, v65
	v_mov_b32_e32 v154, v64
	s_waitcnt lgkmcnt(0)
	v_pk_mul_f32 v[118:119], v[156:157], v[118:119]
	s_nop 0
	v_cndmask_b32_e64 v119, v119, -v119, s[6:7]
	v_cndmask_b32_e64 v118, v118, -v118, s[6:7]
	v_pk_fma_f32 v[4:5], v[4:5], v[158:159], v[118:119]
	ds_bpermute_b32 v118, v75, v6
	ds_bpermute_b32 v119, v75, v7
	s_waitcnt lgkmcnt(0)
	v_pk_mul_f32 v[64:65], v[66:67], v[118:119]
	s_nop 0
	v_cndmask_b32_e64 v65, v65, -v65, s[6:7]
	v_cndmask_b32_e64 v64, v64, -v64, s[6:7]
	v_pk_fma_f32 v[6:7], v[6:7], v[154:155], v[64:65]
	v_mov_b64_e32 v[64:65], s[40:41]
	s_and_saveexec_b64 s[12:13], s[54:55]
	s_xor_b64 s[12:13], exec, s[12:13]
	s_cbranch_execnz .LBB0_467

.LBB0_381:
	s_or_b64 exec, exec, s[12:13]
	v_mov_b32_e32 v87, v71
	v_lshl_add_u64 v[4:5], v[64:65], 0, v[86:87]
	v_mov_b32_e32 v0, v168
	v_mov_b32_e32 v1, v169
	v_mov_b32_e32 v2, v170
	v_mov_b32_e32 v3, v171
	s_nop 0
	v_mov_b32_e32 v4, v172
	v_mov_b32_e32 v5, v173
	v_mov_b32_e32 v6, v174
	v_mov_b32_e32 v7, v175
	v_lshlrev_b32_e32 v64, 16, v60
	v_and_b32_e32 v65, 0xffff0000, v60
	v_lshlrev_b32_e32 v66, 16, v61
	v_and_b32_e32 v67, 0xffff0000, v61
	v_pk_mul_f32 v[60:61], v[64:65], v[64:65]
	v_pk_mul_f32 v[116:117], v[66:67], v[66:67]
	v_add_f32_e32 v60, v60, v61
	v_lshlrev_b32_e32 v114, 16, v62
	v_and_b32_e32 v115, 0xffff0000, v62
	v_add_f32_e32 v60, v116, v60
	v_pk_mul_f32 v[118:119], v[114:115], v[114:115]
	v_add_f32_e32 v60, v117, v60
	v_lshlrev_b32_e32 v62, 16, v63
	v_and_b32_e32 v63, 0xffff0000, v63
	v_add_f32_e32 v60, v118, v60
	v_pk_mul_f32 v[154:155], v[62:63], v[62:63]
	v_add_f32_e32 v60, v119, v60
	v_add_f32_e32 v60, v154, v60
	v_add_f32_e32 v60, v155, v60
	ds_bpermute_b32 v61, v132, v60
	s_and_b64 vcc, exec, s[0:1]
	s_waitcnt lgkmcnt(0)
	v_add_f32_e32 v60, v60, v61
	ds_bpermute_b32 v61, v75, v60
	s_waitcnt lgkmcnt(0)
	v_add_f32_e32 v60, v60, v61
	ds_bpermute_b32 v61, v133, v60
	s_waitcnt lgkmcnt(0)
	v_add_f32_e32 v60, v60, v61
	v_fmamk_f32 v60, v60, 0x3c800000, v127
	v_mul_f32_e32 v61, 0x4b800000, v60
	v_cmp_gt_f32_e64 s[12:13], s82, v60
	s_nop 1
	v_cndmask_b32_e64 v60, v60, v61, s[12:13]
	v_rsq_f32_e32 v61, v60
	v_add_u32_e32 v60, s20, v152
	v_mul_f32_e32 v79, 0x45800000, v61
	v_cndmask_b32_e64 v116, v61, v79, s[12:13]
	v_pk_mul_f32 v[64:65], v[116:117], v[64:65] op_sel_hi:[0,1]
	v_pk_mul_f32 v[66:67], v[116:117], v[66:67] op_sel_hi:[0,1]
	v_pk_mul_f32 v[114:115], v[116:117], v[114:115] op_sel_hi:[0,1]
	v_pk_mul_f32 v[62:63], v[116:117], v[62:63] op_sel_hi:[0,1]
	v_pk_mul_f32 v[0:1], v[0:1], v[64:65]
	v_pk_mul_f32 v[2:3], v[2:3], v[66:67]
	v_pk_mul_f32 v[4:5], v[4:5], v[114:115]
	v_pk_mul_f32 v[6:7], v[6:7], v[62:63]
	s_cbranch_vccnz .LBB0_470
	v_ashrrev_i32_e32 v61, 6, v60
	v_bfe_u32 v62, v113, 4, 6
	v_cndmask_b32_e64 v61, v62, v61, s[8:9]
	v_lshl_or_b32 v62, v61, 5, v138
	v_ashrrev_i32_e32 v63, 31, v62
	v_lshl_add_u64 v[66:67], v[62:63], 2, s[56:57]
	s_waitcnt vmcnt(1)
	v_mov_b32_e32 v62, v188
	v_mov_b32_e32 v63, v189
	v_mov_b32_e32 v64, v190
	v_mov_b32_e32 v65, v191
	v_mov_b32_e32 v114, v184
	v_mov_b32_e32 v115, v185
	v_mov_b32_e32 v116, v186
	v_mov_b32_e32 v117, v187
	v_mov_b32_e32 v152, v180
	v_mov_b32_e32 v153, v181
	v_mov_b32_e32 v154, v182
	v_mov_b32_e32 v155, v183
	v_mov_b32_e32 v156, v176
	v_mov_b32_e32 v157, v177
	v_mov_b32_e32 v158, v178
	v_mov_b32_e32 v159, v179
	v_lshl_add_u64 v[192:193], v[192:193], 0, v[194:195]
	global_load_dwordx4 v[188:191], v[192:193], off offset:48
	global_load_dwordx4 v[184:187], v[192:193], off offset:32
	global_load_dwordx4 v[180:183], v[192:193], off offset:16
	global_load_dwordx4 v[176:179], v[192:193], off
	ds_bpermute_b32 v118, v75, v0
	ds_bpermute_b32 v119, v75, v1
	v_mov_b32_e32 v67, v158
	v_mov_b32_e32 v158, v157
	s_waitcnt lgkmcnt(0)
	v_pk_mul_f32 v[118:119], v[158:159], v[118:119]
	v_mov_b32_e32 v66, v156
	v_cndmask_b32_e64 v119, v119, -v119, s[6:7]
	v_cndmask_b32_e64 v118, v118, -v118, s[6:7]
	v_pk_fma_f32 v[0:1], v[0:1], v[66:67], v[118:119]
	ds_bpermute_b32 v66, v75, v2
	ds_bpermute_b32 v67, v75, v3
	v_mov_b32_e32 v119, v154
	v_mov_b32_e32 v154, v153
	v_mov_b32_e32 v118, v152
	s_waitcnt lgkmcnt(0)
	v_pk_mul_f32 v[66:67], v[154:155], v[66:67]
	s_nop 0
	v_cndmask_b32_e64 v67, v67, -v67, s[6:7]
	v_cndmask_b32_e64 v66, v66, -v66, s[6:7]
	v_pk_fma_f32 v[2:3], v[2:3], v[118:119], v[66:67]
	ds_bpermute_b32 v66, v75, v4
	ds_bpermute_b32 v67, v75, v5
	v_mov_b32_e32 v119, v116
	v_mov_b32_e32 v116, v115
	v_mov_b32_e32 v118, v114
	v_mov_b32_e32 v115, v64
	s_waitcnt lgkmcnt(0)
	v_pk_mul_f32 v[66:67], v[116:117], v[66:67]
	v_mov_b32_e32 v64, v63
	v_cndmask_b32_e64 v67, v67, -v67, s[6:7]
	v_cndmask_b32_e64 v66, v66, -v66, s[6:7]
	v_pk_fma_f32 v[4:5], v[4:5], v[118:119], v[66:67]
	ds_bpermute_b32 v66, v75, v6
	ds_bpermute_b32 v67, v75, v7
	v_mov_b32_e32 v114, v62
	s_waitcnt lgkmcnt(0)
	v_pk_mul_f32 v[62:63], v[64:65], v[66:67]
	s_nop 0
	v_cndmask_b32_e64 v63, v63, -v63, s[6:7]
	v_cndmask_b32_e64 v62, v62, -v62, s[6:7]
	v_pk_fma_f32 v[6:7], v[6:7], v[114:115], v[62:63]
	v_mov_b64_e32 v[62:63], s[40:41]
	s_and_saveexec_b64 s[12:13], s[54:55]
	s_xor_b64 s[12:13], exec, s[12:13]
	s_cbranch_execnz .LBB0_471

.LBB0_385:
	s_or_b64 exec, exec, s[12:13]
	v_mov_b32_e32 v87, v71
	v_lshl_add_u64 v[4:5], v[62:63], 0, v[86:87]
	v_mov_b32_e32 v0, v168
	v_mov_b32_e32 v1, v169
	v_mov_b32_e32 v2, v170
	v_mov_b32_e32 v3, v171
	s_nop 0
	v_mov_b32_e32 v4, v172
	v_mov_b32_e32 v5, v173
	v_mov_b32_e32 v6, v174
	v_mov_b32_e32 v7, v175
	v_lshlrev_b32_e32 v60, 16, v56
	v_and_b32_e32 v61, 0xffff0000, v56
	v_lshlrev_b32_e32 v62, 16, v57
	v_and_b32_e32 v63, 0xffff0000, v57
	v_pk_mul_f32 v[56:57], v[60:61], v[60:61]
	v_pk_mul_f32 v[66:67], v[62:63], v[62:63]
	v_add_f32_e32 v56, v56, v57
	v_lshlrev_b32_e32 v64, 16, v58
	v_and_b32_e32 v65, 0xffff0000, v58
	v_add_f32_e32 v56, v66, v56
	v_pk_mul_f32 v[112:113], v[64:65], v[64:65]
	v_add_f32_e32 v56, v67, v56
	v_lshlrev_b32_e32 v58, 16, v59
	v_and_b32_e32 v59, 0xffff0000, v59
	v_add_f32_e32 v56, v112, v56
	v_pk_mul_f32 v[114:115], v[58:59], v[58:59]
	v_add_f32_e32 v56, v113, v56
	v_add_f32_e32 v56, v114, v56
	v_add_f32_e32 v56, v115, v56
	ds_bpermute_b32 v57, v132, v56
	s_and_b64 vcc, exec, s[0:1]
	s_waitcnt lgkmcnt(0)
	v_add_f32_e32 v56, v56, v57
	ds_bpermute_b32 v57, v75, v56
	s_waitcnt lgkmcnt(0)
	v_add_f32_e32 v56, v56, v57
	ds_bpermute_b32 v57, v133, v56
	s_waitcnt lgkmcnt(0)
	v_add_f32_e32 v56, v56, v57
	v_fmamk_f32 v56, v56, 0x3c800000, v127
	v_mul_f32_e32 v57, 0x4b800000, v56
	v_cmp_gt_f32_e64 s[12:13], s82, v56
	s_nop 1
	v_cndmask_b32_e64 v56, v56, v57, s[12:13]
	v_rsq_f32_e32 v57, v56
	v_add_u32_e32 v56, s20, v151
	v_mul_f32_e32 v66, 0x45800000, v57
	v_cndmask_b32_e64 v66, v57, v66, s[12:13]
	v_pk_mul_f32 v[60:61], v[66:67], v[60:61] op_sel_hi:[0,1]
	v_pk_mul_f32 v[62:63], v[66:67], v[62:63] op_sel_hi:[0,1]
	v_pk_mul_f32 v[64:65], v[66:67], v[64:65] op_sel_hi:[0,1]
	v_pk_mul_f32 v[58:59], v[66:67], v[58:59] op_sel_hi:[0,1]
	v_pk_mul_f32 v[0:1], v[0:1], v[60:61]
	v_pk_mul_f32 v[2:3], v[2:3], v[62:63]
	v_pk_mul_f32 v[4:5], v[4:5], v[64:65]
	v_pk_mul_f32 v[6:7], v[6:7], v[58:59]
	s_cbranch_vccnz .LBB0_474
	v_ashrrev_i32_e32 v57, 6, v56
	v_bfe_u32 v58, v111, 4, 6
	v_cndmask_b32_e64 v57, v58, v57, s[8:9]
	v_lshl_or_b32 v58, v57, 5, v138
	v_ashrrev_i32_e32 v59, 31, v58
	v_lshl_add_u64 v[66:67], v[58:59], 2, s[56:57]
	s_waitcnt vmcnt(1)
	v_mov_b32_e32 v58, v188
	v_mov_b32_e32 v59, v189
	v_mov_b32_e32 v60, v190
	v_mov_b32_e32 v61, v191
	v_mov_b32_e32 v62, v184
	v_mov_b32_e32 v63, v185
	v_mov_b32_e32 v64, v186
	v_mov_b32_e32 v65, v187
	v_mov_b32_e32 v112, v180
	v_mov_b32_e32 v113, v181
	v_mov_b32_e32 v114, v182
	v_mov_b32_e32 v115, v183
	v_mov_b32_e32 v116, v176
	v_mov_b32_e32 v117, v177
	v_mov_b32_e32 v118, v178
	v_mov_b32_e32 v119, v179
	v_lshl_add_u64 v[192:193], v[192:193], 0, v[194:195]
	global_load_dwordx4 v[188:191], v[192:193], off offset:48
	global_load_dwordx4 v[184:187], v[192:193], off offset:32
	global_load_dwordx4 v[180:183], v[192:193], off offset:16
	global_load_dwordx4 v[176:179], v[192:193], off
	ds_bpermute_b32 v152, v75, v0
	ds_bpermute_b32 v153, v75, v1
	v_mov_b32_e32 v67, v118
	v_mov_b32_e32 v118, v117
	v_mov_b32_e32 v66, v116
	s_waitcnt lgkmcnt(0)
	v_pk_mul_f32 v[116:117], v[118:119], v[152:153]
	s_nop 0
	v_cndmask_b32_e64 v117, v117, -v117, s[6:7]
	v_cndmask_b32_e64 v116, v116, -v116, s[6:7]
	v_pk_fma_f32 v[0:1], v[0:1], v[66:67], v[116:117]
	ds_bpermute_b32 v66, v75, v2
	ds_bpermute_b32 v67, v75, v3
	v_mov_b32_e32 v117, v114
	v_mov_b32_e32 v114, v113
	v_mov_b32_e32 v116, v112
	v_mov_b32_e32 v113, v64
	s_waitcnt lgkmcnt(0)
	v_pk_mul_f32 v[66:67], v[114:115], v[66:67]
	v_mov_b32_e32 v64, v63
	v_cndmask_b32_e64 v67, v67, -v67, s[6:7]
	v_cndmask_b32_e64 v66, v66, -v66, s[6:7]
	v_pk_fma_f32 v[2:3], v[2:3], v[116:117], v[66:67]
	ds_bpermute_b32 v66, v75, v4
	ds_bpermute_b32 v67, v75, v5
	v_mov_b32_e32 v112, v62
	s_waitcnt lgkmcnt(0)
	v_pk_mul_f32 v[62:63], v[64:65], v[66:67]
	s_nop 0
	v_cndmask_b32_e64 v63, v63, -v63, s[6:7]
	v_cndmask_b32_e64 v62, v62, -v62, s[6:7]
	v_pk_fma_f32 v[4:5], v[4:5], v[112:113], v[62:63]
	ds_bpermute_b32 v62, v75, v6
	ds_bpermute_b32 v63, v75, v7
	v_mov_b32_e32 v65, v60
	v_mov_b32_e32 v60, v59
	v_mov_b32_e32 v64, v58
	s_waitcnt lgkmcnt(0)
	v_pk_mul_f32 v[58:59], v[60:61], v[62:63]
	s_nop 0
	v_cndmask_b32_e64 v59, v59, -v59, s[6:7]
	v_cndmask_b32_e64 v58, v58, -v58, s[6:7]
	v_pk_fma_f32 v[6:7], v[6:7], v[64:65], v[58:59]
	v_mov_b64_e32 v[58:59], s[40:41]
	s_and_saveexec_b64 s[12:13], s[54:55]
	s_xor_b64 s[12:13], exec, s[12:13]
	s_cbranch_execnz .LBB0_475

.LBB0_389:
	s_or_b64 exec, exec, s[12:13]
	v_mov_b32_e32 v87, v71
	v_lshl_add_u64 v[4:5], v[58:59], 0, v[86:87]
	v_mov_b32_e32 v0, v168
	v_mov_b32_e32 v1, v169
	v_mov_b32_e32 v2, v170
	v_mov_b32_e32 v3, v171
	s_nop 0
	v_mov_b32_e32 v4, v172
	v_mov_b32_e32 v5, v173
	v_mov_b32_e32 v6, v174
	v_mov_b32_e32 v7, v175
	v_lshlrev_b32_e32 v56, 16, v52
	v_and_b32_e32 v57, 0xffff0000, v52
	v_lshlrev_b32_e32 v58, 16, v53
	v_and_b32_e32 v59, 0xffff0000, v53
	v_pk_mul_f32 v[52:53], v[56:57], v[56:57]
	v_pk_mul_f32 v[62:63], v[58:59], v[58:59]
	v_add_f32_e32 v52, v52, v53
	v_lshlrev_b32_e32 v60, 16, v54
	v_and_b32_e32 v61, 0xffff0000, v54
	v_add_f32_e32 v52, v62, v52
	v_pk_mul_f32 v[64:65], v[60:61], v[60:61]
	v_add_f32_e32 v52, v63, v52
	v_lshlrev_b32_e32 v54, 16, v55
	v_and_b32_e32 v55, 0xffff0000, v55
	v_add_f32_e32 v52, v64, v52
	v_pk_mul_f32 v[66:67], v[54:55], v[54:55]
	v_add_f32_e32 v52, v65, v52
	v_add_f32_e32 v52, v66, v52
	v_add_f32_e32 v52, v67, v52
	ds_bpermute_b32 v53, v132, v52
	s_and_b64 vcc, exec, s[0:1]
	s_waitcnt lgkmcnt(0)
	v_add_f32_e32 v52, v52, v53
	ds_bpermute_b32 v53, v75, v52
	s_waitcnt lgkmcnt(0)
	v_add_f32_e32 v52, v52, v53
	ds_bpermute_b32 v53, v133, v52
	s_waitcnt lgkmcnt(0)
	v_add_f32_e32 v52, v52, v53
	v_fmamk_f32 v52, v52, 0x3c800000, v127
	v_mul_f32_e32 v53, 0x4b800000, v52
	v_cmp_gt_f32_e64 s[12:13], s82, v52
	s_nop 1
	v_cndmask_b32_e64 v52, v52, v53, s[12:13]
	v_rsq_f32_e32 v53, v52
	v_add_u32_e32 v52, s20, v150
	v_mul_f32_e32 v62, 0x45800000, v53
	v_cndmask_b32_e64 v62, v53, v62, s[12:13]
	v_pk_mul_f32 v[56:57], v[62:63], v[56:57] op_sel_hi:[0,1]
	v_pk_mul_f32 v[58:59], v[62:63], v[58:59] op_sel_hi:[0,1]
	v_pk_mul_f32 v[60:61], v[62:63], v[60:61] op_sel_hi:[0,1]
	v_pk_mul_f32 v[54:55], v[62:63], v[54:55] op_sel_hi:[0,1]
	v_pk_mul_f32 v[0:1], v[0:1], v[56:57]
	v_pk_mul_f32 v[2:3], v[2:3], v[58:59]
	v_pk_mul_f32 v[4:5], v[4:5], v[60:61]
	v_pk_mul_f32 v[6:7], v[6:7], v[54:55]
	s_cbranch_vccnz .LBB0_478
	v_ashrrev_i32_e32 v53, 6, v52
	v_bfe_u32 v54, v109, 4, 6
	v_cndmask_b32_e64 v53, v54, v53, s[8:9]
	v_lshl_or_b32 v54, v53, 5, v138
	v_ashrrev_i32_e32 v55, 31, v54
	v_lshl_add_u64 v[66:67], v[54:55], 2, s[56:57]
	s_waitcnt vmcnt(1)
	v_mov_b32_e32 v54, v188
	v_mov_b32_e32 v55, v189
	v_mov_b32_e32 v56, v190
	v_mov_b32_e32 v57, v191
	v_mov_b32_e32 v58, v184
	v_mov_b32_e32 v59, v185
	v_mov_b32_e32 v60, v186
	v_mov_b32_e32 v61, v187
	v_mov_b32_e32 v62, v180
	v_mov_b32_e32 v63, v181
	v_mov_b32_e32 v64, v182
	v_mov_b32_e32 v65, v183
	v_mov_b32_e32 v110, v176
	v_mov_b32_e32 v111, v177
	v_mov_b32_e32 v112, v178
	v_mov_b32_e32 v113, v179
	v_lshl_add_u64 v[192:193], v[192:193], 0, v[194:195]
	global_load_dwordx4 v[188:191], v[192:193], off offset:48
	global_load_dwordx4 v[184:187], v[192:193], off offset:32
	global_load_dwordx4 v[180:183], v[192:193], off offset:16
	global_load_dwordx4 v[176:179], v[192:193], off
	ds_bpermute_b32 v114, v75, v0
	ds_bpermute_b32 v115, v75, v1
	v_mov_b32_e32 v67, v112
	v_mov_b32_e32 v112, v111
	v_mov_b32_e32 v66, v110
	s_waitcnt lgkmcnt(0)
	v_pk_mul_f32 v[110:111], v[112:113], v[114:115]
	s_nop 0
	v_cndmask_b32_e64 v111, v111, -v111, s[6:7]
	v_cndmask_b32_e64 v110, v110, -v110, s[6:7]
	v_pk_fma_f32 v[0:1], v[0:1], v[66:67], v[110:111]
	ds_bpermute_b32 v66, v75, v2
	ds_bpermute_b32 v67, v75, v3
	v_mov_b32_e32 v111, v64
	v_mov_b32_e32 v64, v63
	v_mov_b32_e32 v110, v62
	s_waitcnt lgkmcnt(0)
	v_pk_mul_f32 v[62:63], v[64:65], v[66:67]
	s_nop 0
	v_cndmask_b32_e64 v63, v63, -v63, s[6:7]
	v_cndmask_b32_e64 v62, v62, -v62, s[6:7]
	v_pk_fma_f32 v[2:3], v[2:3], v[110:111], v[62:63]
	ds_bpermute_b32 v62, v75, v4
	ds_bpermute_b32 v63, v75, v5
	v_mov_b32_e32 v65, v60
	v_mov_b32_e32 v60, v59
	v_mov_b32_e32 v64, v58
	s_waitcnt lgkmcnt(0)
	v_pk_mul_f32 v[58:59], v[60:61], v[62:63]
	s_nop 0
	v_cndmask_b32_e64 v59, v59, -v59, s[6:7]
	v_cndmask_b32_e64 v58, v58, -v58, s[6:7]
	v_pk_fma_f32 v[4:5], v[4:5], v[64:65], v[58:59]
	ds_bpermute_b32 v58, v75, v6
	ds_bpermute_b32 v59, v75, v7
	v_mov_b32_e32 v61, v56
	v_mov_b32_e32 v56, v55
	v_mov_b32_e32 v60, v54
	s_waitcnt lgkmcnt(0)
	v_pk_mul_f32 v[54:55], v[56:57], v[58:59]
	s_nop 0
	v_cndmask_b32_e64 v55, v55, -v55, s[6:7]
	v_cndmask_b32_e64 v54, v54, -v54, s[6:7]
	v_pk_fma_f32 v[6:7], v[6:7], v[60:61], v[54:55]
	v_mov_b64_e32 v[54:55], s[40:41]
	s_and_saveexec_b64 s[12:13], s[54:55]
	s_xor_b64 s[12:13], exec, s[12:13]
	s_cbranch_execnz .LBB0_479

.LBB0_393:
	s_or_b64 exec, exec, s[12:13]
	v_mov_b32_e32 v87, v71
	v_lshl_add_u64 v[4:5], v[54:55], 0, v[86:87]
	v_mov_b32_e32 v0, v168
	v_mov_b32_e32 v1, v169
	v_mov_b32_e32 v2, v170
	v_mov_b32_e32 v3, v171
	s_nop 0
	v_mov_b32_e32 v4, v172
	v_mov_b32_e32 v5, v173
	v_mov_b32_e32 v6, v174
	v_mov_b32_e32 v7, v175
	v_lshlrev_b32_e32 v52, 16, v48
	v_and_b32_e32 v53, 0xffff0000, v48
	v_lshlrev_b32_e32 v54, 16, v49
	v_and_b32_e32 v55, 0xffff0000, v49
	v_pk_mul_f32 v[48:49], v[52:53], v[52:53]
	v_pk_mul_f32 v[58:59], v[54:55], v[54:55]
	v_add_f32_e32 v48, v48, v49
	v_lshlrev_b32_e32 v56, 16, v50
	v_and_b32_e32 v57, 0xffff0000, v50
	v_add_f32_e32 v48, v58, v48
	v_pk_mul_f32 v[60:61], v[56:57], v[56:57]
	v_add_f32_e32 v48, v59, v48
	v_lshlrev_b32_e32 v50, 16, v51
	v_and_b32_e32 v51, 0xffff0000, v51
	v_add_f32_e32 v48, v60, v48
	v_pk_mul_f32 v[62:63], v[50:51], v[50:51]
	v_add_f32_e32 v48, v61, v48
	v_add_f32_e32 v48, v62, v48
	v_add_f32_e32 v48, v63, v48
	ds_bpermute_b32 v49, v132, v48
	s_and_b64 vcc, exec, s[0:1]
	s_waitcnt lgkmcnt(0)
	v_add_f32_e32 v48, v48, v49
	ds_bpermute_b32 v49, v75, v48
	s_waitcnt lgkmcnt(0)
	v_add_f32_e32 v48, v48, v49
	ds_bpermute_b32 v49, v133, v48
	s_waitcnt lgkmcnt(0)
	v_add_f32_e32 v48, v48, v49
	v_fmamk_f32 v48, v48, 0x3c800000, v127
	v_mul_f32_e32 v49, 0x4b800000, v48
	v_cmp_gt_f32_e64 s[12:13], s82, v48
	s_nop 1
	v_cndmask_b32_e64 v48, v48, v49, s[12:13]
	v_rsq_f32_e32 v49, v48
	v_add_u32_e32 v48, s20, v149
	v_mul_f32_e32 v58, 0x45800000, v49
	v_cndmask_b32_e64 v58, v49, v58, s[12:13]
	v_pk_mul_f32 v[52:53], v[58:59], v[52:53] op_sel_hi:[0,1]
	v_pk_mul_f32 v[54:55], v[58:59], v[54:55] op_sel_hi:[0,1]
	v_pk_mul_f32 v[56:57], v[58:59], v[56:57] op_sel_hi:[0,1]
	v_pk_mul_f32 v[50:51], v[58:59], v[50:51] op_sel_hi:[0,1]
	v_pk_mul_f32 v[0:1], v[0:1], v[52:53]
	v_pk_mul_f32 v[2:3], v[2:3], v[54:55]
	v_pk_mul_f32 v[4:5], v[4:5], v[56:57]
	v_pk_mul_f32 v[6:7], v[6:7], v[50:51]
	s_cbranch_vccnz .LBB0_482
	v_ashrrev_i32_e32 v49, 6, v48
	v_bfe_u32 v50, v107, 4, 6
	v_cndmask_b32_e64 v49, v50, v49, s[8:9]
	v_lshl_or_b32 v50, v49, 5, v138
	v_ashrrev_i32_e32 v51, 31, v50
	v_lshl_add_u64 v[62:63], v[50:51], 2, s[56:57]
	s_waitcnt vmcnt(1)
	v_mov_b32_e32 v50, v188
	v_mov_b32_e32 v51, v189
	v_mov_b32_e32 v52, v190
	v_mov_b32_e32 v53, v191
	v_mov_b32_e32 v54, v184
	v_mov_b32_e32 v55, v185
	v_mov_b32_e32 v56, v186
	v_mov_b32_e32 v57, v187
	v_mov_b32_e32 v58, v180
	v_mov_b32_e32 v59, v181
	v_mov_b32_e32 v60, v182
	v_mov_b32_e32 v61, v183
	v_mov_b32_e32 v62, v176
	v_mov_b32_e32 v63, v177
	v_mov_b32_e32 v64, v178
	v_mov_b32_e32 v65, v179
	v_lshl_add_u64 v[192:193], v[192:193], 0, v[194:195]
	global_load_dwordx4 v[188:191], v[192:193], off offset:48
	global_load_dwordx4 v[184:187], v[192:193], off offset:32
	global_load_dwordx4 v[180:183], v[192:193], off offset:16
	global_load_dwordx4 v[176:179], v[192:193], off
	ds_bpermute_b32 v66, v75, v0
	ds_bpermute_b32 v67, v75, v1
	v_mov_b32_e32 v109, v64
	v_mov_b32_e32 v64, v63
	v_mov_b32_e32 v108, v62
	s_waitcnt lgkmcnt(0)
	v_pk_mul_f32 v[62:63], v[64:65], v[66:67]
	v_mov_b32_e32 v65, v60
	v_cndmask_b32_e64 v63, v63, -v63, s[6:7]
	v_cndmask_b32_e64 v62, v62, -v62, s[6:7]
	v_pk_fma_f32 v[0:1], v[0:1], v[108:109], v[62:63]
	ds_bpermute_b32 v62, v75, v2
	ds_bpermute_b32 v63, v75, v3
	v_mov_b32_e32 v60, v59
	v_mov_b32_e32 v64, v58
	s_waitcnt lgkmcnt(0)
	v_pk_mul_f32 v[58:59], v[60:61], v[62:63]
	s_nop 0
	v_cndmask_b32_e64 v59, v59, -v59, s[6:7]
	v_cndmask_b32_e64 v58, v58, -v58, s[6:7]
	v_pk_fma_f32 v[2:3], v[2:3], v[64:65], v[58:59]
	ds_bpermute_b32 v58, v75, v4
	ds_bpermute_b32 v59, v75, v5
	v_mov_b32_e32 v61, v56
	v_mov_b32_e32 v56, v55
	v_mov_b32_e32 v60, v54
	s_waitcnt lgkmcnt(0)
	v_pk_mul_f32 v[54:55], v[56:57], v[58:59]
	s_nop 0
	v_cndmask_b32_e64 v55, v55, -v55, s[6:7]
	v_cndmask_b32_e64 v54, v54, -v54, s[6:7]
	v_pk_fma_f32 v[4:5], v[4:5], v[60:61], v[54:55]
	ds_bpermute_b32 v54, v75, v6
	ds_bpermute_b32 v55, v75, v7
	v_mov_b32_e32 v57, v52
	v_mov_b32_e32 v52, v51
	v_mov_b32_e32 v56, v50
	s_waitcnt lgkmcnt(0)
	v_pk_mul_f32 v[50:51], v[52:53], v[54:55]
	s_nop 0
	v_cndmask_b32_e64 v51, v51, -v51, s[6:7]
	v_cndmask_b32_e64 v50, v50, -v50, s[6:7]
	v_pk_fma_f32 v[6:7], v[6:7], v[56:57], v[50:51]
	v_mov_b64_e32 v[50:51], s[40:41]
	s_and_saveexec_b64 s[12:13], s[54:55]
	s_xor_b64 s[12:13], exec, s[12:13]
	s_cbranch_execnz .LBB0_483

.LBB0_397:
	s_or_b64 exec, exec, s[12:13]
	v_mov_b32_e32 v87, v71
	v_lshl_add_u64 v[4:5], v[50:51], 0, v[86:87]
	v_mov_b32_e32 v0, v168
	v_mov_b32_e32 v1, v169
	v_mov_b32_e32 v2, v170
	v_mov_b32_e32 v3, v171
	s_nop 0
	v_mov_b32_e32 v4, v172
	v_mov_b32_e32 v5, v173
	v_mov_b32_e32 v6, v174
	v_mov_b32_e32 v7, v175
	v_lshlrev_b32_e32 v48, 16, v44
	v_and_b32_e32 v49, 0xffff0000, v44
	v_lshlrev_b32_e32 v50, 16, v45
	v_and_b32_e32 v51, 0xffff0000, v45
	v_pk_mul_f32 v[44:45], v[48:49], v[48:49]
	v_pk_mul_f32 v[54:55], v[50:51], v[50:51]
	v_add_f32_e32 v44, v44, v45
	v_lshlrev_b32_e32 v52, 16, v46
	v_and_b32_e32 v53, 0xffff0000, v46
	v_add_f32_e32 v44, v54, v44
	v_pk_mul_f32 v[56:57], v[52:53], v[52:53]
	v_add_f32_e32 v44, v55, v44
	v_lshlrev_b32_e32 v46, 16, v47
	v_and_b32_e32 v47, 0xffff0000, v47
	v_add_f32_e32 v44, v56, v44
	v_pk_mul_f32 v[58:59], v[46:47], v[46:47]
	v_add_f32_e32 v44, v57, v44
	v_add_f32_e32 v44, v58, v44
	v_add_f32_e32 v44, v59, v44
	ds_bpermute_b32 v45, v132, v44
	s_and_b64 vcc, exec, s[0:1]
	s_waitcnt lgkmcnt(0)
	v_add_f32_e32 v44, v44, v45
	ds_bpermute_b32 v45, v75, v44
	s_waitcnt lgkmcnt(0)
	v_add_f32_e32 v44, v44, v45
	ds_bpermute_b32 v45, v133, v44
	s_waitcnt lgkmcnt(0)
	v_add_f32_e32 v44, v44, v45
	v_fmamk_f32 v44, v44, 0x3c800000, v127
	v_mul_f32_e32 v45, 0x4b800000, v44
	v_cmp_gt_f32_e64 s[12:13], s82, v44
	s_nop 1
	v_cndmask_b32_e64 v44, v44, v45, s[12:13]
	v_rsq_f32_e32 v45, v44
	v_add_u32_e32 v44, s20, v148
	v_mul_f32_e32 v54, 0x45800000, v45
	v_cndmask_b32_e64 v54, v45, v54, s[12:13]
	v_pk_mul_f32 v[48:49], v[54:55], v[48:49] op_sel_hi:[0,1]
	v_pk_mul_f32 v[50:51], v[54:55], v[50:51] op_sel_hi:[0,1]
	v_pk_mul_f32 v[52:53], v[54:55], v[52:53] op_sel_hi:[0,1]
	v_pk_mul_f32 v[46:47], v[54:55], v[46:47] op_sel_hi:[0,1]
	v_pk_mul_f32 v[0:1], v[0:1], v[48:49]
	v_pk_mul_f32 v[2:3], v[2:3], v[50:51]
	v_pk_mul_f32 v[4:5], v[4:5], v[52:53]
	v_pk_mul_f32 v[6:7], v[6:7], v[46:47]
	s_cbranch_vccnz .LBB0_486
	v_ashrrev_i32_e32 v45, 6, v44
	v_bfe_u32 v46, v105, 4, 6
	v_cndmask_b32_e64 v45, v46, v45, s[8:9]
	v_lshl_or_b32 v46, v45, 5, v138
	v_ashrrev_i32_e32 v47, 31, v46
	v_lshl_add_u64 v[58:59], v[46:47], 2, s[56:57]
	s_waitcnt vmcnt(1)
	v_mov_b32_e32 v46, v188
	v_mov_b32_e32 v47, v189
	v_mov_b32_e32 v48, v190
	v_mov_b32_e32 v49, v191
	v_mov_b32_e32 v50, v184
	v_mov_b32_e32 v51, v185
	v_mov_b32_e32 v52, v186
	v_mov_b32_e32 v53, v187
	v_mov_b32_e32 v54, v180
	v_mov_b32_e32 v55, v181
	v_mov_b32_e32 v56, v182
	v_mov_b32_e32 v57, v183
	v_mov_b32_e32 v58, v176
	v_mov_b32_e32 v59, v177
	v_mov_b32_e32 v60, v178
	v_mov_b32_e32 v61, v179
	v_lshl_add_u64 v[192:193], v[192:193], 0, v[194:195]
	global_load_dwordx4 v[188:191], v[192:193], off offset:48
	global_load_dwordx4 v[184:187], v[192:193], off offset:32
	global_load_dwordx4 v[180:183], v[192:193], off offset:16
	global_load_dwordx4 v[176:179], v[192:193], off
	ds_bpermute_b32 v62, v75, v0
	ds_bpermute_b32 v63, v75, v1
	v_mov_b32_e32 v65, v60
	v_mov_b32_e32 v60, v59
	v_mov_b32_e32 v64, v58
	s_waitcnt lgkmcnt(0)
	v_pk_mul_f32 v[58:59], v[60:61], v[62:63]
	v_mov_b32_e32 v61, v56
	v_cndmask_b32_e64 v59, v59, -v59, s[6:7]
	v_cndmask_b32_e64 v58, v58, -v58, s[6:7]
	v_pk_fma_f32 v[0:1], v[0:1], v[64:65], v[58:59]
	ds_bpermute_b32 v58, v75, v2
	ds_bpermute_b32 v59, v75, v3
	v_mov_b32_e32 v56, v55
	v_mov_b32_e32 v60, v54
	s_waitcnt lgkmcnt(0)
	v_pk_mul_f32 v[54:55], v[56:57], v[58:59]
	s_nop 0
	v_cndmask_b32_e64 v55, v55, -v55, s[6:7]
	v_cndmask_b32_e64 v54, v54, -v54, s[6:7]
	v_pk_fma_f32 v[2:3], v[2:3], v[60:61], v[54:55]
	ds_bpermute_b32 v54, v75, v4
	ds_bpermute_b32 v55, v75, v5
	v_mov_b32_e32 v57, v52
	v_mov_b32_e32 v52, v51
	v_mov_b32_e32 v56, v50
	s_waitcnt lgkmcnt(0)
	v_pk_mul_f32 v[50:51], v[52:53], v[54:55]
	s_nop 0
	v_cndmask_b32_e64 v51, v51, -v51, s[6:7]
	v_cndmask_b32_e64 v50, v50, -v50, s[6:7]
	v_pk_fma_f32 v[4:5], v[4:5], v[56:57], v[50:51]
	ds_bpermute_b32 v50, v75, v6
	ds_bpermute_b32 v51, v75, v7
	v_mov_b32_e32 v53, v48
	v_mov_b32_e32 v48, v47
	v_mov_b32_e32 v52, v46
	s_waitcnt lgkmcnt(0)
	v_pk_mul_f32 v[46:47], v[48:49], v[50:51]
	s_nop 0
	v_cndmask_b32_e64 v47, v47, -v47, s[6:7]
	v_cndmask_b32_e64 v46, v46, -v46, s[6:7]
	v_pk_fma_f32 v[6:7], v[6:7], v[52:53], v[46:47]
	v_mov_b64_e32 v[46:47], s[40:41]
	s_and_saveexec_b64 s[12:13], s[54:55]
	s_xor_b64 s[12:13], exec, s[12:13]
	s_cbranch_execnz .LBB0_487

.LBB0_401:
	s_or_b64 exec, exec, s[12:13]
	v_mov_b32_e32 v87, v71
	v_lshl_add_u64 v[4:5], v[46:47], 0, v[86:87]
	v_mov_b32_e32 v0, v168
	v_mov_b32_e32 v1, v169
	v_mov_b32_e32 v2, v170
	v_mov_b32_e32 v3, v171
	s_nop 0
	v_mov_b32_e32 v4, v172
	v_mov_b32_e32 v5, v173
	v_mov_b32_e32 v6, v174
	v_mov_b32_e32 v7, v175
	v_lshlrev_b32_e32 v44, 16, v40
	v_and_b32_e32 v45, 0xffff0000, v40
	v_lshlrev_b32_e32 v46, 16, v41
	v_and_b32_e32 v47, 0xffff0000, v41
	v_pk_mul_f32 v[40:41], v[44:45], v[44:45]
	v_pk_mul_f32 v[50:51], v[46:47], v[46:47]
	v_add_f32_e32 v40, v40, v41
	v_lshlrev_b32_e32 v48, 16, v42
	v_and_b32_e32 v49, 0xffff0000, v42
	v_add_f32_e32 v40, v50, v40
	v_pk_mul_f32 v[52:53], v[48:49], v[48:49]
	v_add_f32_e32 v40, v51, v40
	v_lshlrev_b32_e32 v42, 16, v43
	v_and_b32_e32 v43, 0xffff0000, v43
	v_add_f32_e32 v40, v52, v40
	v_pk_mul_f32 v[54:55], v[42:43], v[42:43]
	v_add_f32_e32 v40, v53, v40
	v_add_f32_e32 v40, v54, v40
	v_add_f32_e32 v40, v55, v40
	ds_bpermute_b32 v41, v132, v40
	s_and_b64 vcc, exec, s[0:1]
	s_waitcnt lgkmcnt(0)
	v_add_f32_e32 v40, v40, v41
	ds_bpermute_b32 v41, v75, v40
	s_waitcnt lgkmcnt(0)
	v_add_f32_e32 v40, v40, v41
	ds_bpermute_b32 v41, v133, v40
	s_waitcnt lgkmcnt(0)
	v_add_f32_e32 v40, v40, v41
	v_fmamk_f32 v40, v40, 0x3c800000, v127
	v_mul_f32_e32 v41, 0x4b800000, v40
	v_cmp_gt_f32_e64 s[12:13], s82, v40
	s_nop 1
	v_cndmask_b32_e64 v40, v40, v41, s[12:13]
	v_rsq_f32_e32 v41, v40
	v_add_u32_e32 v40, s20, v147
	v_mul_f32_e32 v50, 0x45800000, v41
	v_cndmask_b32_e64 v50, v41, v50, s[12:13]
	v_pk_mul_f32 v[44:45], v[50:51], v[44:45] op_sel_hi:[0,1]
	v_pk_mul_f32 v[46:47], v[50:51], v[46:47] op_sel_hi:[0,1]
	v_pk_mul_f32 v[48:49], v[50:51], v[48:49] op_sel_hi:[0,1]
	v_pk_mul_f32 v[42:43], v[50:51], v[42:43] op_sel_hi:[0,1]
	v_pk_mul_f32 v[0:1], v[0:1], v[44:45]
	v_pk_mul_f32 v[2:3], v[2:3], v[46:47]
	v_pk_mul_f32 v[4:5], v[4:5], v[48:49]
	v_pk_mul_f32 v[6:7], v[6:7], v[42:43]
	s_cbranch_vccnz .LBB0_490
	v_ashrrev_i32_e32 v41, 6, v40
	v_bfe_u32 v42, v103, 4, 6
	v_cndmask_b32_e64 v41, v42, v41, s[8:9]
	v_lshl_or_b32 v42, v41, 5, v138
	v_ashrrev_i32_e32 v43, 31, v42
	v_lshl_add_u64 v[54:55], v[42:43], 2, s[56:57]
	s_waitcnt vmcnt(1)
	v_mov_b32_e32 v42, v188
	v_mov_b32_e32 v43, v189
	v_mov_b32_e32 v44, v190
	v_mov_b32_e32 v45, v191
	v_mov_b32_e32 v46, v184
	v_mov_b32_e32 v47, v185
	v_mov_b32_e32 v48, v186
	v_mov_b32_e32 v49, v187
	v_mov_b32_e32 v50, v180
	v_mov_b32_e32 v51, v181
	v_mov_b32_e32 v52, v182
	v_mov_b32_e32 v53, v183
	v_mov_b32_e32 v54, v176
	v_mov_b32_e32 v55, v177
	v_mov_b32_e32 v56, v178
	v_mov_b32_e32 v57, v179
	v_lshl_add_u64 v[192:193], v[192:193], 0, v[194:195]
	global_load_dwordx4 v[188:191], v[192:193], off offset:48
	global_load_dwordx4 v[184:187], v[192:193], off offset:32
	global_load_dwordx4 v[180:183], v[192:193], off offset:16
	global_load_dwordx4 v[176:179], v[192:193], off
	ds_bpermute_b32 v58, v75, v0
	ds_bpermute_b32 v59, v75, v1
	v_mov_b32_e32 v61, v56
	v_mov_b32_e32 v56, v55
	v_mov_b32_e32 v60, v54
	s_waitcnt lgkmcnt(0)
	v_pk_mul_f32 v[54:55], v[56:57], v[58:59]
	v_mov_b32_e32 v57, v52
	v_cndmask_b32_e64 v55, v55, -v55, s[6:7]
	v_cndmask_b32_e64 v54, v54, -v54, s[6:7]
	v_pk_fma_f32 v[0:1], v[0:1], v[60:61], v[54:55]
	ds_bpermute_b32 v54, v75, v2
	ds_bpermute_b32 v55, v75, v3
	v_mov_b32_e32 v52, v51
	v_mov_b32_e32 v56, v50
	s_waitcnt lgkmcnt(0)
	v_pk_mul_f32 v[50:51], v[52:53], v[54:55]
	s_nop 0
	v_cndmask_b32_e64 v51, v51, -v51, s[6:7]
	v_cndmask_b32_e64 v50, v50, -v50, s[6:7]
	v_pk_fma_f32 v[2:3], v[2:3], v[56:57], v[50:51]
	ds_bpermute_b32 v50, v75, v4
	ds_bpermute_b32 v51, v75, v5
	v_mov_b32_e32 v53, v48
	v_mov_b32_e32 v48, v47
	v_mov_b32_e32 v52, v46
	s_waitcnt lgkmcnt(0)
	v_pk_mul_f32 v[46:47], v[48:49], v[50:51]
	s_nop 0
	v_cndmask_b32_e64 v47, v47, -v47, s[6:7]
	v_cndmask_b32_e64 v46, v46, -v46, s[6:7]
	v_pk_fma_f32 v[4:5], v[4:5], v[52:53], v[46:47]
	ds_bpermute_b32 v46, v75, v6
	ds_bpermute_b32 v47, v75, v7
	v_mov_b32_e32 v49, v44
	v_mov_b32_e32 v44, v43
	v_mov_b32_e32 v48, v42
	s_waitcnt lgkmcnt(0)
	v_pk_mul_f32 v[42:43], v[44:45], v[46:47]
	s_nop 0
	v_cndmask_b32_e64 v43, v43, -v43, s[6:7]
	v_cndmask_b32_e64 v42, v42, -v42, s[6:7]
	v_pk_fma_f32 v[6:7], v[6:7], v[48:49], v[42:43]
	v_mov_b64_e32 v[42:43], s[40:41]
	s_and_saveexec_b64 s[12:13], s[54:55]
	s_xor_b64 s[12:13], exec, s[12:13]
	s_cbranch_execnz .LBB0_491

.LBB0_405:
	s_or_b64 exec, exec, s[12:13]
	v_mov_b32_e32 v87, v71
	v_lshl_add_u64 v[4:5], v[42:43], 0, v[86:87]
	v_mov_b32_e32 v0, v168
	v_mov_b32_e32 v1, v169
	v_mov_b32_e32 v2, v170
	v_mov_b32_e32 v3, v171
	s_nop 0
	v_mov_b32_e32 v4, v172
	v_mov_b32_e32 v5, v173
	v_mov_b32_e32 v6, v174
	v_mov_b32_e32 v7, v175
	v_lshlrev_b32_e32 v40, 16, v36
	v_and_b32_e32 v41, 0xffff0000, v36
	v_lshlrev_b32_e32 v42, 16, v37
	v_and_b32_e32 v43, 0xffff0000, v37
	v_pk_mul_f32 v[36:37], v[40:41], v[40:41]
	v_pk_mul_f32 v[46:47], v[42:43], v[42:43]
	v_add_f32_e32 v36, v36, v37
	v_lshlrev_b32_e32 v44, 16, v38
	v_and_b32_e32 v45, 0xffff0000, v38
	v_add_f32_e32 v36, v46, v36
	v_pk_mul_f32 v[48:49], v[44:45], v[44:45]
	v_add_f32_e32 v36, v47, v36
	v_lshlrev_b32_e32 v38, 16, v39
	v_and_b32_e32 v39, 0xffff0000, v39
	v_add_f32_e32 v36, v48, v36
	v_pk_mul_f32 v[50:51], v[38:39], v[38:39]
	v_add_f32_e32 v36, v49, v36
	v_add_f32_e32 v36, v50, v36
	v_add_f32_e32 v36, v51, v36
	ds_bpermute_b32 v37, v132, v36
	s_and_b64 vcc, exec, s[0:1]
	s_waitcnt lgkmcnt(0)
	v_add_f32_e32 v36, v36, v37
	ds_bpermute_b32 v37, v75, v36
	s_waitcnt lgkmcnt(0)
	v_add_f32_e32 v36, v36, v37
	ds_bpermute_b32 v37, v133, v36
	s_waitcnt lgkmcnt(0)
	v_add_f32_e32 v36, v36, v37
	v_fmamk_f32 v36, v36, 0x3c800000, v127
	v_mul_f32_e32 v37, 0x4b800000, v36
	v_cmp_gt_f32_e64 s[12:13], s82, v36
	s_nop 1
	v_cndmask_b32_e64 v36, v36, v37, s[12:13]
	v_rsq_f32_e32 v37, v36
	v_add_u32_e32 v36, s20, v146
	v_mul_f32_e32 v46, 0x45800000, v37
	v_cndmask_b32_e64 v46, v37, v46, s[12:13]
	v_pk_mul_f32 v[40:41], v[46:47], v[40:41] op_sel_hi:[0,1]
	v_pk_mul_f32 v[42:43], v[46:47], v[42:43] op_sel_hi:[0,1]
	v_pk_mul_f32 v[44:45], v[46:47], v[44:45] op_sel_hi:[0,1]
	v_pk_mul_f32 v[38:39], v[46:47], v[38:39] op_sel_hi:[0,1]
	v_pk_mul_f32 v[0:1], v[0:1], v[40:41]
	v_pk_mul_f32 v[2:3], v[2:3], v[42:43]
	v_pk_mul_f32 v[4:5], v[4:5], v[44:45]
	v_pk_mul_f32 v[6:7], v[6:7], v[38:39]
	s_cbranch_vccnz .LBB0_494
	v_ashrrev_i32_e32 v37, 6, v36
	v_bfe_u32 v38, v101, 4, 6
	v_cndmask_b32_e64 v37, v38, v37, s[8:9]
	v_lshl_or_b32 v38, v37, 5, v138
	v_ashrrev_i32_e32 v39, 31, v38
	v_lshl_add_u64 v[50:51], v[38:39], 2, s[56:57]
	s_waitcnt vmcnt(1)
	v_mov_b32_e32 v38, v188
	v_mov_b32_e32 v39, v189
	v_mov_b32_e32 v40, v190
	v_mov_b32_e32 v41, v191
	v_mov_b32_e32 v42, v184
	v_mov_b32_e32 v43, v185
	v_mov_b32_e32 v44, v186
	v_mov_b32_e32 v45, v187
	v_mov_b32_e32 v46, v180
	v_mov_b32_e32 v47, v181
	v_mov_b32_e32 v48, v182
	v_mov_b32_e32 v49, v183
	v_mov_b32_e32 v50, v176
	v_mov_b32_e32 v51, v177
	v_mov_b32_e32 v52, v178
	v_mov_b32_e32 v53, v179
	v_lshl_add_u64 v[192:193], v[192:193], 0, v[194:195]
	global_load_dwordx4 v[188:191], v[192:193], off offset:48
	global_load_dwordx4 v[184:187], v[192:193], off offset:32
	global_load_dwordx4 v[180:183], v[192:193], off offset:16
	global_load_dwordx4 v[176:179], v[192:193], off
	ds_bpermute_b32 v54, v75, v0
	ds_bpermute_b32 v55, v75, v1
	v_mov_b32_e32 v57, v52
	v_mov_b32_e32 v52, v51
	v_mov_b32_e32 v56, v50
	s_waitcnt lgkmcnt(0)
	v_pk_mul_f32 v[50:51], v[52:53], v[54:55]
	v_mov_b32_e32 v53, v48
	v_cndmask_b32_e64 v51, v51, -v51, s[6:7]
	v_cndmask_b32_e64 v50, v50, -v50, s[6:7]
	v_pk_fma_f32 v[0:1], v[0:1], v[56:57], v[50:51]
	ds_bpermute_b32 v50, v75, v2
	ds_bpermute_b32 v51, v75, v3
	v_mov_b32_e32 v48, v47
	v_mov_b32_e32 v52, v46
	s_waitcnt lgkmcnt(0)
	v_pk_mul_f32 v[46:47], v[48:49], v[50:51]
	s_nop 0
	v_cndmask_b32_e64 v47, v47, -v47, s[6:7]
	v_cndmask_b32_e64 v46, v46, -v46, s[6:7]
	v_pk_fma_f32 v[2:3], v[2:3], v[52:53], v[46:47]
	ds_bpermute_b32 v46, v75, v4
	ds_bpermute_b32 v47, v75, v5
	v_mov_b32_e32 v49, v44
	v_mov_b32_e32 v44, v43
	v_mov_b32_e32 v48, v42
	s_waitcnt lgkmcnt(0)
	v_pk_mul_f32 v[42:43], v[44:45], v[46:47]
	s_nop 0
	v_cndmask_b32_e64 v43, v43, -v43, s[6:7]
	v_cndmask_b32_e64 v42, v42, -v42, s[6:7]
	v_pk_fma_f32 v[4:5], v[4:5], v[48:49], v[42:43]
	ds_bpermute_b32 v42, v75, v6
	ds_bpermute_b32 v43, v75, v7
	v_mov_b32_e32 v45, v40
	v_mov_b32_e32 v40, v39
	v_mov_b32_e32 v44, v38
	s_waitcnt lgkmcnt(0)
	v_pk_mul_f32 v[38:39], v[40:41], v[42:43]
	s_nop 0
	v_cndmask_b32_e64 v39, v39, -v39, s[6:7]
	v_cndmask_b32_e64 v38, v38, -v38, s[6:7]
	v_pk_fma_f32 v[6:7], v[6:7], v[44:45], v[38:39]
	v_mov_b64_e32 v[38:39], s[40:41]
	s_and_saveexec_b64 s[12:13], s[54:55]
	s_xor_b64 s[12:13], exec, s[12:13]
	s_cbranch_execnz .LBB0_495

.LBB0_409:
	s_or_b64 exec, exec, s[12:13]
	v_mov_b32_e32 v87, v71
	v_lshl_add_u64 v[4:5], v[38:39], 0, v[86:87]
	v_mov_b32_e32 v0, v168
	v_mov_b32_e32 v1, v169
	v_mov_b32_e32 v2, v170
	v_mov_b32_e32 v3, v171
	s_nop 0
	v_mov_b32_e32 v4, v172
	v_mov_b32_e32 v5, v173
	v_mov_b32_e32 v6, v174
	v_mov_b32_e32 v7, v175
	v_lshlrev_b32_e32 v36, 16, v32
	v_and_b32_e32 v37, 0xffff0000, v32
	v_lshlrev_b32_e32 v38, 16, v33
	v_and_b32_e32 v39, 0xffff0000, v33
	v_pk_mul_f32 v[32:33], v[36:37], v[36:37]
	v_pk_mul_f32 v[42:43], v[38:39], v[38:39]
	v_add_f32_e32 v32, v32, v33
	v_lshlrev_b32_e32 v40, 16, v34
	v_and_b32_e32 v41, 0xffff0000, v34
	v_add_f32_e32 v32, v42, v32
	v_pk_mul_f32 v[44:45], v[40:41], v[40:41]
	v_add_f32_e32 v32, v43, v32
	v_lshlrev_b32_e32 v34, 16, v35
	v_and_b32_e32 v35, 0xffff0000, v35
	v_add_f32_e32 v32, v44, v32
	v_pk_mul_f32 v[46:47], v[34:35], v[34:35]
	v_add_f32_e32 v32, v45, v32
	v_add_f32_e32 v32, v46, v32
	v_add_f32_e32 v32, v47, v32
	ds_bpermute_b32 v33, v132, v32
	s_and_b64 vcc, exec, s[0:1]
	s_waitcnt lgkmcnt(0)
	v_add_f32_e32 v32, v32, v33
	ds_bpermute_b32 v33, v75, v32
	s_waitcnt lgkmcnt(0)
	v_add_f32_e32 v32, v32, v33
	ds_bpermute_b32 v33, v133, v32
	s_waitcnt lgkmcnt(0)
	v_add_f32_e32 v32, v32, v33
	v_fmamk_f32 v32, v32, 0x3c800000, v127
	v_mul_f32_e32 v33, 0x4b800000, v32
	v_cmp_gt_f32_e64 s[12:13], s82, v32
	s_nop 1
	v_cndmask_b32_e64 v32, v32, v33, s[12:13]
	v_rsq_f32_e32 v33, v32
	v_add_u32_e32 v32, s20, v145
	v_mul_f32_e32 v42, 0x45800000, v33
	v_cndmask_b32_e64 v42, v33, v42, s[12:13]
	v_pk_mul_f32 v[36:37], v[42:43], v[36:37] op_sel_hi:[0,1]
	v_pk_mul_f32 v[38:39], v[42:43], v[38:39] op_sel_hi:[0,1]
	v_pk_mul_f32 v[40:41], v[42:43], v[40:41] op_sel_hi:[0,1]
	v_pk_mul_f32 v[34:35], v[42:43], v[34:35] op_sel_hi:[0,1]
	v_pk_mul_f32 v[0:1], v[0:1], v[36:37]
	v_pk_mul_f32 v[2:3], v[2:3], v[38:39]
	v_pk_mul_f32 v[4:5], v[4:5], v[40:41]
	v_pk_mul_f32 v[6:7], v[6:7], v[34:35]
	s_cbranch_vccnz .LBB0_498
	v_ashrrev_i32_e32 v33, 6, v32
	v_bfe_u32 v34, v99, 4, 6
	v_cndmask_b32_e64 v33, v34, v33, s[8:9]
	v_lshl_or_b32 v34, v33, 5, v138
	v_ashrrev_i32_e32 v35, 31, v34
	v_lshl_add_u64 v[46:47], v[34:35], 2, s[56:57]
	s_waitcnt vmcnt(1)
	v_mov_b32_e32 v34, v188
	v_mov_b32_e32 v35, v189
	v_mov_b32_e32 v36, v190
	v_mov_b32_e32 v37, v191
	v_mov_b32_e32 v38, v184
	v_mov_b32_e32 v39, v185
	v_mov_b32_e32 v40, v186
	v_mov_b32_e32 v41, v187
	v_mov_b32_e32 v42, v180
	v_mov_b32_e32 v43, v181
	v_mov_b32_e32 v44, v182
	v_mov_b32_e32 v45, v183
	v_mov_b32_e32 v46, v176
	v_mov_b32_e32 v47, v177
	v_mov_b32_e32 v48, v178
	v_mov_b32_e32 v49, v179
	v_lshl_add_u64 v[192:193], v[192:193], 0, v[194:195]
	global_load_dwordx4 v[188:191], v[192:193], off offset:48
	global_load_dwordx4 v[184:187], v[192:193], off offset:32
	global_load_dwordx4 v[180:183], v[192:193], off offset:16
	global_load_dwordx4 v[176:179], v[192:193], off
	ds_bpermute_b32 v50, v75, v0
	ds_bpermute_b32 v51, v75, v1
	v_mov_b32_e32 v53, v48
	v_mov_b32_e32 v48, v47
	v_mov_b32_e32 v52, v46
	s_waitcnt lgkmcnt(0)
	v_pk_mul_f32 v[46:47], v[48:49], v[50:51]
	v_mov_b32_e32 v49, v44
	v_cndmask_b32_e64 v47, v47, -v47, s[6:7]
	v_cndmask_b32_e64 v46, v46, -v46, s[6:7]
	v_pk_fma_f32 v[0:1], v[0:1], v[52:53], v[46:47]
	ds_bpermute_b32 v46, v75, v2
	ds_bpermute_b32 v47, v75, v3
	v_mov_b32_e32 v44, v43
	v_mov_b32_e32 v48, v42
	s_waitcnt lgkmcnt(0)
	v_pk_mul_f32 v[42:43], v[44:45], v[46:47]
	s_nop 0
	v_cndmask_b32_e64 v43, v43, -v43, s[6:7]
	v_cndmask_b32_e64 v42, v42, -v42, s[6:7]
	v_pk_fma_f32 v[2:3], v[2:3], v[48:49], v[42:43]
	ds_bpermute_b32 v42, v75, v4
	ds_bpermute_b32 v43, v75, v5
	v_mov_b32_e32 v45, v40
	v_mov_b32_e32 v40, v39
	v_mov_b32_e32 v44, v38
	s_waitcnt lgkmcnt(0)
	v_pk_mul_f32 v[38:39], v[40:41], v[42:43]
	s_nop 0
	v_cndmask_b32_e64 v39, v39, -v39, s[6:7]
	v_cndmask_b32_e64 v38, v38, -v38, s[6:7]
	v_pk_fma_f32 v[4:5], v[4:5], v[44:45], v[38:39]
	ds_bpermute_b32 v38, v75, v6
	ds_bpermute_b32 v39, v75, v7
	v_mov_b32_e32 v41, v36
	v_mov_b32_e32 v36, v35
	v_mov_b32_e32 v40, v34
	s_waitcnt lgkmcnt(0)
	v_pk_mul_f32 v[34:35], v[36:37], v[38:39]
	s_nop 0
	v_cndmask_b32_e64 v35, v35, -v35, s[6:7]
	v_cndmask_b32_e64 v34, v34, -v34, s[6:7]
	v_pk_fma_f32 v[6:7], v[6:7], v[40:41], v[34:35]
	v_mov_b64_e32 v[34:35], s[40:41]
	s_and_saveexec_b64 s[12:13], s[54:55]
	s_xor_b64 s[12:13], exec, s[12:13]
	s_cbranch_execnz .LBB0_499

.LBB0_413:
	s_or_b64 exec, exec, s[12:13]
	v_mov_b32_e32 v87, v71
	v_lshl_add_u64 v[4:5], v[34:35], 0, v[86:87]
	v_mov_b32_e32 v0, v168
	v_mov_b32_e32 v1, v169
	v_mov_b32_e32 v2, v170
	v_mov_b32_e32 v3, v171
	s_nop 0
	v_mov_b32_e32 v4, v172
	v_mov_b32_e32 v5, v173
	v_mov_b32_e32 v6, v174
	v_mov_b32_e32 v7, v175
	v_lshlrev_b32_e32 v32, 16, v28
	v_and_b32_e32 v33, 0xffff0000, v28
	v_lshlrev_b32_e32 v34, 16, v29
	v_and_b32_e32 v35, 0xffff0000, v29
	v_pk_mul_f32 v[28:29], v[32:33], v[32:33]
	v_pk_mul_f32 v[38:39], v[34:35], v[34:35]
	v_add_f32_e32 v28, v28, v29
	v_lshlrev_b32_e32 v36, 16, v30
	v_and_b32_e32 v37, 0xffff0000, v30
	v_add_f32_e32 v28, v38, v28
	v_pk_mul_f32 v[40:41], v[36:37], v[36:37]
	v_add_f32_e32 v28, v39, v28
	v_lshlrev_b32_e32 v30, 16, v31
	v_and_b32_e32 v31, 0xffff0000, v31
	v_add_f32_e32 v28, v40, v28
	v_pk_mul_f32 v[42:43], v[30:31], v[30:31]
	v_add_f32_e32 v28, v41, v28
	v_add_f32_e32 v28, v42, v28
	v_add_f32_e32 v28, v43, v28
	ds_bpermute_b32 v29, v132, v28
	s_and_b64 vcc, exec, s[0:1]
	s_waitcnt lgkmcnt(0)
	v_add_f32_e32 v28, v28, v29
	ds_bpermute_b32 v29, v75, v28
	s_waitcnt lgkmcnt(0)
	v_add_f32_e32 v28, v28, v29
	ds_bpermute_b32 v29, v133, v28
	s_waitcnt lgkmcnt(0)
	v_add_f32_e32 v28, v28, v29
	v_fmamk_f32 v28, v28, 0x3c800000, v127
	v_mul_f32_e32 v29, 0x4b800000, v28
	v_cmp_gt_f32_e64 s[12:13], s82, v28
	s_nop 1
	v_cndmask_b32_e64 v28, v28, v29, s[12:13]
	v_rsq_f32_e32 v29, v28
	v_add_u32_e32 v28, s20, v144
	v_mul_f32_e32 v38, 0x45800000, v29
	v_cndmask_b32_e64 v38, v29, v38, s[12:13]
	v_pk_mul_f32 v[32:33], v[38:39], v[32:33] op_sel_hi:[0,1]
	v_pk_mul_f32 v[34:35], v[38:39], v[34:35] op_sel_hi:[0,1]
	v_pk_mul_f32 v[36:37], v[38:39], v[36:37] op_sel_hi:[0,1]
	v_pk_mul_f32 v[30:31], v[38:39], v[30:31] op_sel_hi:[0,1]
	v_pk_mul_f32 v[0:1], v[0:1], v[32:33]
	v_pk_mul_f32 v[2:3], v[2:3], v[34:35]
	v_pk_mul_f32 v[4:5], v[4:5], v[36:37]
	v_pk_mul_f32 v[6:7], v[6:7], v[30:31]
	s_cbranch_vccnz .LBB0_502
	v_ashrrev_i32_e32 v29, 6, v28
	v_bfe_u32 v30, v97, 4, 6
	v_cndmask_b32_e64 v29, v30, v29, s[8:9]
	v_lshl_or_b32 v30, v29, 5, v138
	v_ashrrev_i32_e32 v31, 31, v30
	v_lshl_add_u64 v[42:43], v[30:31], 2, s[56:57]
	s_waitcnt vmcnt(1)
	v_mov_b32_e32 v30, v188
	v_mov_b32_e32 v31, v189
	v_mov_b32_e32 v32, v190
	v_mov_b32_e32 v33, v191
	v_mov_b32_e32 v34, v184
	v_mov_b32_e32 v35, v185
	v_mov_b32_e32 v36, v186
	v_mov_b32_e32 v37, v187
	v_mov_b32_e32 v38, v180
	v_mov_b32_e32 v39, v181
	v_mov_b32_e32 v40, v182
	v_mov_b32_e32 v41, v183
	v_mov_b32_e32 v42, v176
	v_mov_b32_e32 v43, v177
	v_mov_b32_e32 v44, v178
	v_mov_b32_e32 v45, v179
	v_lshl_add_u64 v[192:193], v[192:193], 0, v[194:195]
	global_load_dwordx4 v[188:191], v[192:193], off offset:48
	global_load_dwordx4 v[184:187], v[192:193], off offset:32
	global_load_dwordx4 v[180:183], v[192:193], off offset:16
	global_load_dwordx4 v[176:179], v[192:193], off
	ds_bpermute_b32 v46, v75, v0
	ds_bpermute_b32 v47, v75, v1
	v_mov_b32_e32 v49, v44
	v_mov_b32_e32 v44, v43
	v_mov_b32_e32 v48, v42
	s_waitcnt lgkmcnt(0)
	v_pk_mul_f32 v[42:43], v[44:45], v[46:47]
	v_mov_b32_e32 v45, v40
	v_cndmask_b32_e64 v43, v43, -v43, s[6:7]
	v_cndmask_b32_e64 v42, v42, -v42, s[6:7]
	v_pk_fma_f32 v[0:1], v[0:1], v[48:49], v[42:43]
	ds_bpermute_b32 v42, v75, v2
	ds_bpermute_b32 v43, v75, v3
	v_mov_b32_e32 v40, v39
	v_mov_b32_e32 v44, v38
	s_waitcnt lgkmcnt(0)
	v_pk_mul_f32 v[38:39], v[40:41], v[42:43]
	s_nop 0
	v_cndmask_b32_e64 v39, v39, -v39, s[6:7]
	v_cndmask_b32_e64 v38, v38, -v38, s[6:7]
	v_pk_fma_f32 v[2:3], v[2:3], v[44:45], v[38:39]
	ds_bpermute_b32 v38, v75, v4
	ds_bpermute_b32 v39, v75, v5
	v_mov_b32_e32 v41, v36
	v_mov_b32_e32 v36, v35
	v_mov_b32_e32 v40, v34
	s_waitcnt lgkmcnt(0)
	v_pk_mul_f32 v[34:35], v[36:37], v[38:39]
	s_nop 0
	v_cndmask_b32_e64 v35, v35, -v35, s[6:7]
	v_cndmask_b32_e64 v34, v34, -v34, s[6:7]
	v_pk_fma_f32 v[4:5], v[4:5], v[40:41], v[34:35]
	ds_bpermute_b32 v34, v75, v6
	ds_bpermute_b32 v35, v75, v7
	v_mov_b32_e32 v37, v32
	v_mov_b32_e32 v32, v31
	v_mov_b32_e32 v36, v30
	s_waitcnt lgkmcnt(0)
	v_pk_mul_f32 v[30:31], v[32:33], v[34:35]
	s_nop 0
	v_cndmask_b32_e64 v31, v31, -v31, s[6:7]
	v_cndmask_b32_e64 v30, v30, -v30, s[6:7]
	v_pk_fma_f32 v[6:7], v[6:7], v[36:37], v[30:31]
	v_mov_b64_e32 v[30:31], s[40:41]
	s_and_saveexec_b64 s[12:13], s[54:55]
	s_xor_b64 s[12:13], exec, s[12:13]
	s_cbranch_execnz .LBB0_503

.LBB0_417:
	s_or_b64 exec, exec, s[12:13]
	v_mov_b32_e32 v87, v71
	v_lshl_add_u64 v[4:5], v[30:31], 0, v[86:87]
	v_mov_b32_e32 v0, v168
	v_mov_b32_e32 v1, v169
	v_mov_b32_e32 v2, v170
	v_mov_b32_e32 v3, v171
	s_nop 0
	v_mov_b32_e32 v4, v172
	v_mov_b32_e32 v5, v173
	v_mov_b32_e32 v6, v174
	v_mov_b32_e32 v7, v175
	v_lshlrev_b32_e32 v28, 16, v24
	v_and_b32_e32 v29, 0xffff0000, v24
	v_lshlrev_b32_e32 v30, 16, v25
	v_and_b32_e32 v31, 0xffff0000, v25
	v_pk_mul_f32 v[24:25], v[28:29], v[28:29]
	v_pk_mul_f32 v[34:35], v[30:31], v[30:31]
	v_add_f32_e32 v24, v24, v25
	v_lshlrev_b32_e32 v32, 16, v26
	v_and_b32_e32 v33, 0xffff0000, v26
	v_add_f32_e32 v24, v34, v24
	v_pk_mul_f32 v[36:37], v[32:33], v[32:33]
	v_add_f32_e32 v24, v35, v24
	v_lshlrev_b32_e32 v26, 16, v27
	v_and_b32_e32 v27, 0xffff0000, v27
	v_add_f32_e32 v24, v36, v24
	v_pk_mul_f32 v[38:39], v[26:27], v[26:27]
	v_add_f32_e32 v24, v37, v24
	v_add_f32_e32 v24, v38, v24
	v_add_f32_e32 v24, v39, v24
	ds_bpermute_b32 v25, v132, v24
	s_and_b64 vcc, exec, s[0:1]
	s_waitcnt lgkmcnt(0)
	v_add_f32_e32 v24, v24, v25
	ds_bpermute_b32 v25, v75, v24
	s_waitcnt lgkmcnt(0)
	v_add_f32_e32 v24, v24, v25
	ds_bpermute_b32 v25, v133, v24
	s_waitcnt lgkmcnt(0)
	v_add_f32_e32 v24, v24, v25
	v_fmamk_f32 v24, v24, 0x3c800000, v127
	v_mul_f32_e32 v25, 0x4b800000, v24
	v_cmp_gt_f32_e64 s[12:13], s82, v24
	s_nop 1
	v_cndmask_b32_e64 v24, v24, v25, s[12:13]
	v_rsq_f32_e32 v25, v24
	v_add_u32_e32 v24, s20, v143
	v_mul_f32_e32 v34, 0x45800000, v25
	v_cndmask_b32_e64 v34, v25, v34, s[12:13]
	v_pk_mul_f32 v[28:29], v[34:35], v[28:29] op_sel_hi:[0,1]
	v_pk_mul_f32 v[30:31], v[34:35], v[30:31] op_sel_hi:[0,1]
	v_pk_mul_f32 v[32:33], v[34:35], v[32:33] op_sel_hi:[0,1]
	v_pk_mul_f32 v[26:27], v[34:35], v[26:27] op_sel_hi:[0,1]
	v_pk_mul_f32 v[0:1], v[0:1], v[28:29]
	v_pk_mul_f32 v[2:3], v[2:3], v[30:31]
	v_pk_mul_f32 v[4:5], v[4:5], v[32:33]
	v_pk_mul_f32 v[6:7], v[6:7], v[26:27]
	s_cbranch_vccnz .LBB0_506
	v_ashrrev_i32_e32 v25, 6, v24
	v_bfe_u32 v26, v95, 4, 6
	v_cndmask_b32_e64 v25, v26, v25, s[8:9]
	v_lshl_or_b32 v26, v25, 5, v138
	v_ashrrev_i32_e32 v27, 31, v26
	v_lshl_add_u64 v[38:39], v[26:27], 2, s[56:57]
	s_waitcnt vmcnt(1)
	v_mov_b32_e32 v26, v188
	v_mov_b32_e32 v27, v189
	v_mov_b32_e32 v28, v190
	v_mov_b32_e32 v29, v191
	v_mov_b32_e32 v30, v184
	v_mov_b32_e32 v31, v185
	v_mov_b32_e32 v32, v186
	v_mov_b32_e32 v33, v187
	v_mov_b32_e32 v34, v180
	v_mov_b32_e32 v35, v181
	v_mov_b32_e32 v36, v182
	v_mov_b32_e32 v37, v183
	v_mov_b32_e32 v38, v176
	v_mov_b32_e32 v39, v177
	v_mov_b32_e32 v40, v178
	v_mov_b32_e32 v41, v179
	v_lshl_add_u64 v[192:193], v[192:193], 0, v[194:195]
	global_load_dwordx4 v[188:191], v[192:193], off offset:48
	global_load_dwordx4 v[184:187], v[192:193], off offset:32
	global_load_dwordx4 v[180:183], v[192:193], off offset:16
	global_load_dwordx4 v[176:179], v[192:193], off
	ds_bpermute_b32 v42, v75, v0
	ds_bpermute_b32 v43, v75, v1
	v_mov_b32_e32 v45, v40
	v_mov_b32_e32 v40, v39
	v_mov_b32_e32 v44, v38
	s_waitcnt lgkmcnt(0)
	v_pk_mul_f32 v[38:39], v[40:41], v[42:43]
	v_mov_b32_e32 v41, v36
	v_cndmask_b32_e64 v39, v39, -v39, s[6:7]
	v_cndmask_b32_e64 v38, v38, -v38, s[6:7]
	v_pk_fma_f32 v[0:1], v[0:1], v[44:45], v[38:39]
	ds_bpermute_b32 v38, v75, v2
	ds_bpermute_b32 v39, v75, v3
	v_mov_b32_e32 v36, v35
	v_mov_b32_e32 v40, v34
	s_waitcnt lgkmcnt(0)
	v_pk_mul_f32 v[34:35], v[36:37], v[38:39]
	s_nop 0
	v_cndmask_b32_e64 v35, v35, -v35, s[6:7]
	v_cndmask_b32_e64 v34, v34, -v34, s[6:7]
	v_pk_fma_f32 v[2:3], v[2:3], v[40:41], v[34:35]
	ds_bpermute_b32 v34, v75, v4
	ds_bpermute_b32 v35, v75, v5
	v_mov_b32_e32 v37, v32
	v_mov_b32_e32 v32, v31
	v_mov_b32_e32 v36, v30
	s_waitcnt lgkmcnt(0)
	v_pk_mul_f32 v[30:31], v[32:33], v[34:35]
	s_nop 0
	v_cndmask_b32_e64 v31, v31, -v31, s[6:7]
	v_cndmask_b32_e64 v30, v30, -v30, s[6:7]
	v_pk_fma_f32 v[4:5], v[4:5], v[36:37], v[30:31]
	ds_bpermute_b32 v30, v75, v6
	ds_bpermute_b32 v31, v75, v7
	v_mov_b32_e32 v33, v28
	v_mov_b32_e32 v28, v27
	v_mov_b32_e32 v32, v26
	s_waitcnt lgkmcnt(0)
	v_pk_mul_f32 v[26:27], v[28:29], v[30:31]
	s_nop 0
	v_cndmask_b32_e64 v27, v27, -v27, s[6:7]
	v_cndmask_b32_e64 v26, v26, -v26, s[6:7]
	v_pk_fma_f32 v[6:7], v[6:7], v[32:33], v[26:27]
	v_mov_b64_e32 v[26:27], s[40:41]
	s_and_saveexec_b64 s[12:13], s[54:55]
	s_xor_b64 s[12:13], exec, s[12:13]
	s_cbranch_execnz .LBB0_507

.LBB0_421:
	s_or_b64 exec, exec, s[12:13]
	v_mov_b32_e32 v87, v71
	v_lshl_add_u64 v[4:5], v[26:27], 0, v[86:87]
	v_mov_b32_e32 v0, v168
	v_mov_b32_e32 v1, v169
	v_mov_b32_e32 v2, v170
	v_mov_b32_e32 v3, v171
	s_nop 0
	v_mov_b32_e32 v4, v172
	v_mov_b32_e32 v5, v173
	v_mov_b32_e32 v6, v174
	v_mov_b32_e32 v7, v175
	v_lshlrev_b32_e32 v24, 16, v20
	v_and_b32_e32 v25, 0xffff0000, v20
	v_lshlrev_b32_e32 v26, 16, v21
	v_and_b32_e32 v27, 0xffff0000, v21
	v_pk_mul_f32 v[20:21], v[24:25], v[24:25]
	v_pk_mul_f32 v[30:31], v[26:27], v[26:27]
	v_add_f32_e32 v20, v20, v21
	v_lshlrev_b32_e32 v28, 16, v22
	v_and_b32_e32 v29, 0xffff0000, v22
	v_add_f32_e32 v20, v30, v20
	v_pk_mul_f32 v[32:33], v[28:29], v[28:29]
	v_add_f32_e32 v20, v31, v20
	v_lshlrev_b32_e32 v22, 16, v23
	v_and_b32_e32 v23, 0xffff0000, v23
	v_add_f32_e32 v20, v32, v20
	v_pk_mul_f32 v[34:35], v[22:23], v[22:23]
	v_add_f32_e32 v20, v33, v20
	v_add_f32_e32 v20, v34, v20
	v_add_f32_e32 v20, v35, v20
	ds_bpermute_b32 v21, v132, v20
	s_and_b64 vcc, exec, s[0:1]
	s_waitcnt lgkmcnt(0)
	v_add_f32_e32 v20, v20, v21
	ds_bpermute_b32 v21, v75, v20
	s_waitcnt lgkmcnt(0)
	v_add_f32_e32 v20, v20, v21
	ds_bpermute_b32 v21, v133, v20
	s_waitcnt lgkmcnt(0)
	v_add_f32_e32 v20, v20, v21
	v_fmamk_f32 v20, v20, 0x3c800000, v127
	v_mul_f32_e32 v21, 0x4b800000, v20
	v_cmp_gt_f32_e64 s[12:13], s82, v20
	s_nop 1
	v_cndmask_b32_e64 v20, v20, v21, s[12:13]
	v_rsq_f32_e32 v21, v20
	v_add_u32_e32 v20, s20, v142
	v_mul_f32_e32 v30, 0x45800000, v21
	v_cndmask_b32_e64 v30, v21, v30, s[12:13]
	v_pk_mul_f32 v[24:25], v[30:31], v[24:25] op_sel_hi:[0,1]
	v_pk_mul_f32 v[26:27], v[30:31], v[26:27] op_sel_hi:[0,1]
	v_pk_mul_f32 v[28:29], v[30:31], v[28:29] op_sel_hi:[0,1]
	v_pk_mul_f32 v[22:23], v[30:31], v[22:23] op_sel_hi:[0,1]
	v_pk_mul_f32 v[0:1], v[0:1], v[24:25]
	v_pk_mul_f32 v[2:3], v[2:3], v[26:27]
	v_pk_mul_f32 v[4:5], v[4:5], v[28:29]
	v_pk_mul_f32 v[6:7], v[6:7], v[22:23]
	s_cbranch_vccnz .LBB0_510
	v_ashrrev_i32_e32 v21, 6, v20
	v_bfe_u32 v22, v93, 4, 6
	v_cndmask_b32_e64 v21, v22, v21, s[8:9]
	v_lshl_or_b32 v22, v21, 5, v138
	v_ashrrev_i32_e32 v23, 31, v22
	v_lshl_add_u64 v[34:35], v[22:23], 2, s[56:57]
	s_waitcnt vmcnt(1)
	v_mov_b32_e32 v22, v188
	v_mov_b32_e32 v23, v189
	v_mov_b32_e32 v24, v190
	v_mov_b32_e32 v25, v191
	v_mov_b32_e32 v26, v184
	v_mov_b32_e32 v27, v185
	v_mov_b32_e32 v28, v186
	v_mov_b32_e32 v29, v187
	v_mov_b32_e32 v30, v180
	v_mov_b32_e32 v31, v181
	v_mov_b32_e32 v32, v182
	v_mov_b32_e32 v33, v183
	v_mov_b32_e32 v34, v176
	v_mov_b32_e32 v35, v177
	v_mov_b32_e32 v36, v178
	v_mov_b32_e32 v37, v179
	v_lshl_add_u64 v[192:193], v[192:193], 0, v[194:195]
	global_load_dwordx4 v[188:191], v[192:193], off offset:48
	global_load_dwordx4 v[184:187], v[192:193], off offset:32
	global_load_dwordx4 v[180:183], v[192:193], off offset:16
	global_load_dwordx4 v[176:179], v[192:193], off
	ds_bpermute_b32 v38, v75, v0
	ds_bpermute_b32 v39, v75, v1
	v_mov_b32_e32 v41, v36
	v_mov_b32_e32 v36, v35
	v_mov_b32_e32 v40, v34
	s_waitcnt lgkmcnt(0)
	v_pk_mul_f32 v[34:35], v[36:37], v[38:39]
	v_mov_b32_e32 v37, v32
	v_cndmask_b32_e64 v35, v35, -v35, s[6:7]
	v_cndmask_b32_e64 v34, v34, -v34, s[6:7]
	v_pk_fma_f32 v[0:1], v[0:1], v[40:41], v[34:35]
	ds_bpermute_b32 v34, v75, v2
	ds_bpermute_b32 v35, v75, v3
	v_mov_b32_e32 v32, v31
	v_mov_b32_e32 v36, v30
	s_waitcnt lgkmcnt(0)
	v_pk_mul_f32 v[30:31], v[32:33], v[34:35]
	s_nop 0
	v_cndmask_b32_e64 v31, v31, -v31, s[6:7]
	v_cndmask_b32_e64 v30, v30, -v30, s[6:7]
	v_pk_fma_f32 v[2:3], v[2:3], v[36:37], v[30:31]
	ds_bpermute_b32 v30, v75, v4
	ds_bpermute_b32 v31, v75, v5
	v_mov_b32_e32 v33, v28
	v_mov_b32_e32 v28, v27
	v_mov_b32_e32 v32, v26
	s_waitcnt lgkmcnt(0)
	v_pk_mul_f32 v[26:27], v[28:29], v[30:31]
	s_nop 0
	v_cndmask_b32_e64 v27, v27, -v27, s[6:7]
	v_cndmask_b32_e64 v26, v26, -v26, s[6:7]
	v_pk_fma_f32 v[4:5], v[4:5], v[32:33], v[26:27]
	ds_bpermute_b32 v26, v75, v6
	ds_bpermute_b32 v27, v75, v7
	v_mov_b32_e32 v29, v24
	v_mov_b32_e32 v24, v23
	v_mov_b32_e32 v28, v22
	s_waitcnt lgkmcnt(0)
	v_pk_mul_f32 v[22:23], v[24:25], v[26:27]
	s_nop 0
	v_cndmask_b32_e64 v23, v23, -v23, s[6:7]
	v_cndmask_b32_e64 v22, v22, -v22, s[6:7]
	v_pk_fma_f32 v[6:7], v[6:7], v[28:29], v[22:23]
	v_mov_b64_e32 v[22:23], s[40:41]
	s_and_saveexec_b64 s[12:13], s[54:55]
	s_xor_b64 s[12:13], exec, s[12:13]
	s_cbranch_execnz .LBB0_511

.LBB0_425:
	s_or_b64 exec, exec, s[12:13]
	v_mov_b32_e32 v87, v71
	v_lshl_add_u64 v[4:5], v[22:23], 0, v[86:87]
	v_mov_b32_e32 v0, v168
	v_mov_b32_e32 v1, v169
	v_mov_b32_e32 v2, v170
	v_mov_b32_e32 v3, v171
	s_nop 0
	v_mov_b32_e32 v4, v172
	v_mov_b32_e32 v5, v173
	v_mov_b32_e32 v6, v174
	v_mov_b32_e32 v7, v175
	v_lshlrev_b32_e32 v20, 16, v16
	v_and_b32_e32 v21, 0xffff0000, v16
	v_lshlrev_b32_e32 v22, 16, v17
	v_and_b32_e32 v23, 0xffff0000, v17
	v_pk_mul_f32 v[16:17], v[20:21], v[20:21]
	v_pk_mul_f32 v[26:27], v[22:23], v[22:23]
	v_add_f32_e32 v16, v16, v17
	v_lshlrev_b32_e32 v24, 16, v18
	v_and_b32_e32 v25, 0xffff0000, v18
	v_add_f32_e32 v16, v26, v16
	v_pk_mul_f32 v[28:29], v[24:25], v[24:25]
	v_add_f32_e32 v16, v27, v16
	v_lshlrev_b32_e32 v18, 16, v19
	v_and_b32_e32 v19, 0xffff0000, v19
	v_add_f32_e32 v16, v28, v16
	v_pk_mul_f32 v[30:31], v[18:19], v[18:19]
	v_add_f32_e32 v16, v29, v16
	v_add_f32_e32 v16, v30, v16
	v_add_f32_e32 v16, v31, v16
	ds_bpermute_b32 v17, v132, v16
	s_and_b64 vcc, exec, s[0:1]
	s_waitcnt lgkmcnt(0)
	v_add_f32_e32 v16, v16, v17
	ds_bpermute_b32 v17, v75, v16
	s_waitcnt lgkmcnt(0)
	v_add_f32_e32 v16, v16, v17
	ds_bpermute_b32 v17, v133, v16
	s_waitcnt lgkmcnt(0)
	v_add_f32_e32 v16, v16, v17
	v_fmamk_f32 v16, v16, 0x3c800000, v127
	v_mul_f32_e32 v17, 0x4b800000, v16
	v_cmp_gt_f32_e64 s[12:13], s82, v16
	s_nop 1
	v_cndmask_b32_e64 v16, v16, v17, s[12:13]
	v_rsq_f32_e32 v17, v16
	v_add_u32_e32 v16, s20, v141
	v_mul_f32_e32 v26, 0x45800000, v17
	v_cndmask_b32_e64 v26, v17, v26, s[12:13]
	v_pk_mul_f32 v[20:21], v[26:27], v[20:21] op_sel_hi:[0,1]
	v_pk_mul_f32 v[22:23], v[26:27], v[22:23] op_sel_hi:[0,1]
	v_pk_mul_f32 v[24:25], v[26:27], v[24:25] op_sel_hi:[0,1]
	v_pk_mul_f32 v[18:19], v[26:27], v[18:19] op_sel_hi:[0,1]
	v_pk_mul_f32 v[0:1], v[0:1], v[20:21]
	v_pk_mul_f32 v[2:3], v[2:3], v[22:23]
	v_pk_mul_f32 v[4:5], v[4:5], v[24:25]
	v_pk_mul_f32 v[6:7], v[6:7], v[18:19]
	s_cbranch_vccnz .LBB0_514
	v_ashrrev_i32_e32 v17, 6, v16
	v_bfe_u32 v18, v91, 4, 6
	v_cndmask_b32_e64 v17, v18, v17, s[8:9]
	v_lshl_or_b32 v18, v17, 5, v138
	v_ashrrev_i32_e32 v19, 31, v18
	v_lshl_add_u64 v[30:31], v[18:19], 2, s[56:57]
	s_waitcnt vmcnt(1)
	v_mov_b32_e32 v18, v188
	v_mov_b32_e32 v19, v189
	v_mov_b32_e32 v20, v190
	v_mov_b32_e32 v21, v191
	v_mov_b32_e32 v22, v184
	v_mov_b32_e32 v23, v185
	v_mov_b32_e32 v24, v186
	v_mov_b32_e32 v25, v187
	v_mov_b32_e32 v26, v180
	v_mov_b32_e32 v27, v181
	v_mov_b32_e32 v28, v182
	v_mov_b32_e32 v29, v183
	v_mov_b32_e32 v30, v176
	v_mov_b32_e32 v31, v177
	v_mov_b32_e32 v32, v178
	v_mov_b32_e32 v33, v179
	v_lshl_add_u64 v[192:193], v[192:193], 0, v[194:195]
	global_load_dwordx4 v[188:191], v[192:193], off offset:48
	global_load_dwordx4 v[184:187], v[192:193], off offset:32
	global_load_dwordx4 v[180:183], v[192:193], off offset:16
	global_load_dwordx4 v[176:179], v[192:193], off
	ds_bpermute_b32 v34, v75, v0
	ds_bpermute_b32 v35, v75, v1
	v_mov_b32_e32 v37, v32
	v_mov_b32_e32 v32, v31
	v_mov_b32_e32 v36, v30
	s_waitcnt lgkmcnt(0)
	v_pk_mul_f32 v[30:31], v[32:33], v[34:35]
	v_mov_b32_e32 v33, v28
	v_cndmask_b32_e64 v31, v31, -v31, s[6:7]
	v_cndmask_b32_e64 v30, v30, -v30, s[6:7]
	v_pk_fma_f32 v[0:1], v[0:1], v[36:37], v[30:31]
	ds_bpermute_b32 v30, v75, v2
	ds_bpermute_b32 v31, v75, v3
	v_mov_b32_e32 v28, v27
	v_mov_b32_e32 v32, v26
	s_waitcnt lgkmcnt(0)
	v_pk_mul_f32 v[26:27], v[28:29], v[30:31]
	s_nop 0
	v_cndmask_b32_e64 v27, v27, -v27, s[6:7]
	v_cndmask_b32_e64 v26, v26, -v26, s[6:7]
	v_pk_fma_f32 v[2:3], v[2:3], v[32:33], v[26:27]
	ds_bpermute_b32 v26, v75, v4
	ds_bpermute_b32 v27, v75, v5
	v_mov_b32_e32 v29, v24
	v_mov_b32_e32 v24, v23
	v_mov_b32_e32 v28, v22
	s_waitcnt lgkmcnt(0)
	v_pk_mul_f32 v[22:23], v[24:25], v[26:27]
	s_nop 0
	v_cndmask_b32_e64 v23, v23, -v23, s[6:7]
	v_cndmask_b32_e64 v22, v22, -v22, s[6:7]
	v_pk_fma_f32 v[4:5], v[4:5], v[28:29], v[22:23]
	ds_bpermute_b32 v22, v75, v6
	ds_bpermute_b32 v23, v75, v7
	v_mov_b32_e32 v25, v20
	v_mov_b32_e32 v20, v19
	v_mov_b32_e32 v24, v18
	s_waitcnt lgkmcnt(0)
	v_pk_mul_f32 v[18:19], v[20:21], v[22:23]
	s_nop 0
	v_cndmask_b32_e64 v19, v19, -v19, s[6:7]
	v_cndmask_b32_e64 v18, v18, -v18, s[6:7]
	v_pk_fma_f32 v[6:7], v[6:7], v[24:25], v[18:19]
	v_mov_b64_e32 v[18:19], s[40:41]
	s_and_saveexec_b64 s[12:13], s[54:55]
	s_xor_b64 s[12:13], exec, s[12:13]
	s_cbranch_execnz .LBB0_515

.LBB0_429:
	s_or_b64 exec, exec, s[12:13]
	v_mov_b32_e32 v87, v71
	v_lshl_add_u64 v[4:5], v[18:19], 0, v[86:87]
	v_mov_b32_e32 v0, v168
	v_mov_b32_e32 v1, v169
	v_mov_b32_e32 v2, v170
	v_mov_b32_e32 v3, v171
	s_nop 0
	v_mov_b32_e32 v4, v172
	v_mov_b32_e32 v5, v173
	v_mov_b32_e32 v6, v174
	v_mov_b32_e32 v7, v175
	v_lshlrev_b32_e32 v16, 16, v12
	v_and_b32_e32 v17, 0xffff0000, v12
	v_lshlrev_b32_e32 v18, 16, v13
	v_and_b32_e32 v19, 0xffff0000, v13
	v_pk_mul_f32 v[12:13], v[16:17], v[16:17]
	v_pk_mul_f32 v[22:23], v[18:19], v[18:19]
	v_add_f32_e32 v12, v12, v13
	v_lshlrev_b32_e32 v20, 16, v14
	v_and_b32_e32 v21, 0xffff0000, v14
	v_add_f32_e32 v12, v22, v12
	v_pk_mul_f32 v[24:25], v[20:21], v[20:21]
	v_add_f32_e32 v12, v23, v12
	v_lshlrev_b32_e32 v14, 16, v15
	v_and_b32_e32 v15, 0xffff0000, v15
	v_add_f32_e32 v12, v24, v12
	v_pk_mul_f32 v[26:27], v[14:15], v[14:15]
	v_add_f32_e32 v12, v25, v12
	v_add_f32_e32 v12, v26, v12
	v_add_f32_e32 v12, v27, v12
	ds_bpermute_b32 v13, v132, v12
	s_and_b64 vcc, exec, s[0:1]
	s_waitcnt lgkmcnt(0)
	v_add_f32_e32 v12, v12, v13
	ds_bpermute_b32 v13, v75, v12
	s_waitcnt lgkmcnt(0)
	v_add_f32_e32 v12, v12, v13
	ds_bpermute_b32 v13, v133, v12
	s_waitcnt lgkmcnt(0)
	v_add_f32_e32 v12, v12, v13
	v_fmamk_f32 v12, v12, 0x3c800000, v127
	v_mul_f32_e32 v13, 0x4b800000, v12
	v_cmp_gt_f32_e64 s[12:13], s82, v12
	s_nop 1
	v_cndmask_b32_e64 v12, v12, v13, s[12:13]
	v_rsq_f32_e32 v13, v12
	v_add_u32_e32 v12, s20, v140
	v_mul_f32_e32 v22, 0x45800000, v13
	v_cndmask_b32_e64 v22, v13, v22, s[12:13]
	v_pk_mul_f32 v[16:17], v[22:23], v[16:17] op_sel_hi:[0,1]
	v_pk_mul_f32 v[18:19], v[22:23], v[18:19] op_sel_hi:[0,1]
	v_pk_mul_f32 v[20:21], v[22:23], v[20:21] op_sel_hi:[0,1]
	v_pk_mul_f32 v[14:15], v[22:23], v[14:15] op_sel_hi:[0,1]
	v_pk_mul_f32 v[0:1], v[0:1], v[16:17]
	v_pk_mul_f32 v[2:3], v[2:3], v[18:19]
	v_pk_mul_f32 v[4:5], v[4:5], v[20:21]
	v_pk_mul_f32 v[6:7], v[6:7], v[14:15]
	s_cbranch_vccnz .LBB0_518
	v_ashrrev_i32_e32 v13, 6, v12
	v_bfe_u32 v14, v89, 4, 6
	v_cndmask_b32_e64 v13, v14, v13, s[8:9]
	v_lshl_or_b32 v14, v13, 5, v138
	v_ashrrev_i32_e32 v15, 31, v14
	v_lshl_add_u64 v[26:27], v[14:15], 2, s[56:57]
	s_waitcnt vmcnt(1)
	v_mov_b32_e32 v14, v188
	v_mov_b32_e32 v15, v189
	v_mov_b32_e32 v16, v190
	v_mov_b32_e32 v17, v191
	v_mov_b32_e32 v18, v184
	v_mov_b32_e32 v19, v185
	v_mov_b32_e32 v20, v186
	v_mov_b32_e32 v21, v187
	v_mov_b32_e32 v22, v180
	v_mov_b32_e32 v23, v181
	v_mov_b32_e32 v24, v182
	v_mov_b32_e32 v25, v183
	v_mov_b32_e32 v26, v176
	v_mov_b32_e32 v27, v177
	v_mov_b32_e32 v28, v178
	v_mov_b32_e32 v29, v179
	v_lshl_add_u64 v[192:193], v[192:193], 0, v[194:195]
	global_load_dwordx4 v[188:191], v[192:193], off offset:48
	global_load_dwordx4 v[184:187], v[192:193], off offset:32
	global_load_dwordx4 v[180:183], v[192:193], off offset:16
	global_load_dwordx4 v[176:179], v[192:193], off
	ds_bpermute_b32 v30, v75, v0
	ds_bpermute_b32 v31, v75, v1
	v_mov_b32_e32 v33, v28
	v_mov_b32_e32 v28, v27
	v_mov_b32_e32 v32, v26
	s_waitcnt lgkmcnt(0)
	v_pk_mul_f32 v[26:27], v[28:29], v[30:31]
	v_mov_b32_e32 v29, v24
	v_cndmask_b32_e64 v27, v27, -v27, s[6:7]
	v_cndmask_b32_e64 v26, v26, -v26, s[6:7]
	v_pk_fma_f32 v[0:1], v[0:1], v[32:33], v[26:27]
	ds_bpermute_b32 v26, v75, v2
	ds_bpermute_b32 v27, v75, v3
	v_mov_b32_e32 v24, v23
	v_mov_b32_e32 v28, v22
	s_waitcnt lgkmcnt(0)
	v_pk_mul_f32 v[22:23], v[24:25], v[26:27]
	s_nop 0
	v_cndmask_b32_e64 v23, v23, -v23, s[6:7]
	v_cndmask_b32_e64 v22, v22, -v22, s[6:7]
	v_pk_fma_f32 v[2:3], v[2:3], v[28:29], v[22:23]
	ds_bpermute_b32 v22, v75, v4
	ds_bpermute_b32 v23, v75, v5
	v_mov_b32_e32 v25, v20
	v_mov_b32_e32 v20, v19
	v_mov_b32_e32 v24, v18
	s_waitcnt lgkmcnt(0)
	v_pk_mul_f32 v[18:19], v[20:21], v[22:23]
	s_nop 0
	v_cndmask_b32_e64 v19, v19, -v19, s[6:7]
	v_cndmask_b32_e64 v18, v18, -v18, s[6:7]
	v_pk_fma_f32 v[4:5], v[4:5], v[24:25], v[18:19]
	ds_bpermute_b32 v18, v75, v6
	ds_bpermute_b32 v19, v75, v7
	v_mov_b32_e32 v21, v16
	v_mov_b32_e32 v16, v15
	v_mov_b32_e32 v20, v14
	s_waitcnt lgkmcnt(0)
	v_pk_mul_f32 v[14:15], v[16:17], v[18:19]
	s_nop 0
	v_cndmask_b32_e64 v15, v15, -v15, s[6:7]
	v_cndmask_b32_e64 v14, v14, -v14, s[6:7]
	v_pk_fma_f32 v[6:7], v[6:7], v[20:21], v[14:15]
	v_mov_b64_e32 v[14:15], s[40:41]
	s_and_saveexec_b64 s[12:13], s[54:55]
	s_xor_b64 s[12:13], exec, s[12:13]
	s_cbranch_execnz .LBB0_519

.LBB0_433:
	s_or_b64 exec, exec, s[12:13]
	v_mov_b32_e32 v87, v71
	v_lshl_add_u64 v[0:1], v[14:15], 0, v[86:87]
	v_mov_b32_e32 v4, v172
	v_mov_b32_e32 v5, v173
	v_mov_b32_e32 v6, v174
	v_mov_b32_e32 v7, v175
	s_nop 0
	v_mov_b32_e32 v0, v168
	v_mov_b32_e32 v1, v169
	v_mov_b32_e32 v2, v170
	v_mov_b32_e32 v3, v171
	v_lshlrev_b32_e32 v14, 16, v8
	v_and_b32_e32 v15, 0xffff0000, v8
	v_pk_mul_f32 v[16:17], v[14:15], v[14:15]
	v_lshlrev_b32_e32 v8, 16, v9
	v_and_b32_e32 v9, 0xffff0000, v9
	v_pk_mul_f32 v[18:19], v[8:9], v[8:9]
	v_add_f32_e32 v13, v16, v17
	v_lshlrev_b32_e32 v20, 16, v10
	v_and_b32_e32 v21, 0xffff0000, v10
	v_add_f32_e32 v13, v18, v13
	v_pk_mul_f32 v[22:23], v[20:21], v[20:21]
	v_add_f32_e32 v13, v19, v13
	v_lshlrev_b32_e32 v10, 16, v11
	v_and_b32_e32 v11, 0xffff0000, v11
	v_add_f32_e32 v13, v22, v13
	v_pk_mul_f32 v[24:25], v[10:11], v[10:11]
	v_add_f32_e32 v13, v23, v13
	v_add_f32_e32 v13, v24, v13
	v_add_f32_e32 v13, v25, v13
	ds_bpermute_b32 v16, v132, v13
	v_add_u32_e32 v12, s20, v139
	s_waitcnt lgkmcnt(0)
	v_add_f32_e32 v13, v13, v16
	ds_bpermute_b32 v16, v75, v13
	s_waitcnt lgkmcnt(0)
	v_add_f32_e32 v13, v13, v16
	ds_bpermute_b32 v16, v133, v13
	s_waitcnt lgkmcnt(0)
	v_add_f32_e32 v13, v13, v16
	v_fmamk_f32 v13, v13, 0x3c800000, v127
	v_cmp_gt_f32_e32 vcc, s82, v13
	v_mul_f32_e32 v16, 0x4b800000, v13
	s_nop 0
	v_cndmask_b32_e32 v13, v13, v16, vcc
	v_rsq_f32_e32 v13, v13
	s_nop 0
	v_mul_f32_e32 v16, 0x45800000, v13
	v_cndmask_b32_e32 v16, v13, v16, vcc
	v_pk_mul_f32 v[8:9], v[16:17], v[8:9] op_sel_hi:[0,1]
	v_pk_mul_f32 v[14:15], v[16:17], v[14:15] op_sel_hi:[0,1]
	s_and_b64 vcc, exec, s[0:1]
	v_pk_mul_f32 v[2:3], v[2:3], v[8:9]
	v_pk_mul_f32 v[8:9], v[16:17], v[20:21] op_sel_hi:[0,1]
	v_pk_mul_f32 v[4:5], v[4:5], v[8:9]
	v_pk_mul_f32 v[8:9], v[16:17], v[10:11] op_sel_hi:[0,1]
	v_pk_mul_f32 v[0:1], v[0:1], v[14:15]
	v_pk_mul_f32 v[6:7], v[6:7], v[8:9]
	s_cbranch_vccnz .LBB0_435
	v_ashrrev_i32_e32 v8, 6, v12
	v_bfe_u32 v9, v137, 4, 6
	v_cndmask_b32_e64 v8, v9, v8, s[8:9]
	v_lshl_or_b32 v8, v8, 5, v138
	v_ashrrev_i32_e32 v9, 31, v8
	v_lshl_add_u64 v[22:23], v[8:9], 2, s[56:57]
	s_waitcnt vmcnt(1)
	v_mov_b32_e32 v8, v188
	v_mov_b32_e32 v9, v189
	v_mov_b32_e32 v10, v190
	v_mov_b32_e32 v11, v191
	v_mov_b32_e32 v14, v184
	v_mov_b32_e32 v15, v185
	v_mov_b32_e32 v16, v186
	v_mov_b32_e32 v17, v187
	v_mov_b32_e32 v18, v180
	v_mov_b32_e32 v19, v181
	v_mov_b32_e32 v20, v182
	v_mov_b32_e32 v21, v183
	v_mov_b32_e32 v22, v176
	v_mov_b32_e32 v23, v177
	v_mov_b32_e32 v24, v178
	v_mov_b32_e32 v25, v179
	ds_bpermute_b32 v26, v75, v0
	ds_bpermute_b32 v27, v75, v1
	v_mov_b32_e32 v29, v24
	v_mov_b32_e32 v24, v23
	v_mov_b32_e32 v28, v22
	s_waitcnt lgkmcnt(0)
	v_pk_mul_f32 v[22:23], v[24:25], v[26:27]
	v_mov_b32_e32 v25, v20
	v_cndmask_b32_e64 v23, v23, -v23, s[6:7]
	v_cndmask_b32_e64 v22, v22, -v22, s[6:7]
	v_pk_fma_f32 v[0:1], v[0:1], v[28:29], v[22:23]
	ds_bpermute_b32 v22, v75, v2
	ds_bpermute_b32 v23, v75, v3
	v_mov_b32_e32 v20, v19
	v_mov_b32_e32 v24, v18
	s_waitcnt lgkmcnt(0)
	v_pk_mul_f32 v[18:19], v[20:21], v[22:23]
	s_nop 0
	v_cndmask_b32_e64 v19, v19, -v19, s[6:7]
	v_cndmask_b32_e64 v18, v18, -v18, s[6:7]
	v_pk_fma_f32 v[2:3], v[2:3], v[24:25], v[18:19]
	ds_bpermute_b32 v18, v75, v4
	ds_bpermute_b32 v19, v75, v5
	v_mov_b32_e32 v21, v16
	v_mov_b32_e32 v16, v15
	v_mov_b32_e32 v20, v14
	s_waitcnt lgkmcnt(0)
	v_pk_mul_f32 v[14:15], v[16:17], v[18:19]
	s_nop 0
	v_cndmask_b32_e64 v15, v15, -v15, s[6:7]
	v_cndmask_b32_e64 v14, v14, -v14, s[6:7]
	v_pk_fma_f32 v[4:5], v[4:5], v[20:21], v[14:15]
	ds_bpermute_b32 v14, v75, v6
	ds_bpermute_b32 v15, v75, v7
	v_mov_b32_e32 v17, v10
	v_mov_b32_e32 v10, v9
	v_mov_b32_e32 v16, v8
	s_waitcnt lgkmcnt(0)
	v_pk_mul_f32 v[8:9], v[10:11], v[14:15]
	s_nop 0
	v_cndmask_b32_e64 v9, v9, -v9, s[6:7]
	v_cndmask_b32_e64 v8, v8, -v8, s[6:7]
	v_pk_fma_f32 v[6:7], v[6:7], v[16:17], v[8:9]

.LBB0_1296:
	s_or_b64 exec, exec, s[4:5]
	s_lshl_b32 s4, s16, 1
	s_or_b32 s17, s4, 4
	v_readlane_b32 s0, v254, 27
	s_lshl_b32 s27, s17, 16
	v_readlane_b32 s6, v254, 33
	v_readlane_b32 s10, v254, 37
	v_ashrrev_i32_e32 v37, 31, v36
	v_readlane_b32 s7, v254, 34
	v_readlane_b32 s11, v254, 38
	s_add_u32 s6, s10, s27
	v_lshlrev_b64 v[24:25], 4, v[36:37]
	v_readlane_b32 s5, v254, 32
	s_addc_u32 s7, s11, 0
	v_lshl_add_u64 v[30:31], s[6:7], 0, v[24:25]
	s_movk_i32 s5, 0x2000
	v_add_co_u32_e32 v4, vcc, s5, v30
	s_movk_i32 s5, 0x4000
	s_nop 0
	v_addc_co_u32_e32 v5, vcc, 0, v31, vcc
	v_add_co_u32_e32 v8, vcc, s5, v30
	s_movk_i32 s5, 0x6000
	s_nop 0
	v_addc_co_u32_e32 v9, vcc, 0, v31, vcc
	v_add_co_u32_e32 v12, vcc, s5, v30
	s_mov_b32 s5, 0x8000
	s_nop 0
	v_addc_co_u32_e32 v13, vcc, 0, v31, vcc
	v_add_co_u32_e32 v16, vcc, s5, v30
	s_mov_b32 s5, 0xa000
	s_waitcnt lgkmcnt(0)
	v_addc_co_u32_e32 v17, vcc, 0, v31, vcc
	global_load_dwordx4 v[0:3], v[30:31], off
	s_nop 0
	global_load_dwordx4 v[4:7], v[4:5], off
	v_add_co_u32_e32 v20, vcc, s5, v30
	global_load_dwordx4 v[8:11], v[8:9], off
	s_nop 0
	v_addc_co_u32_e32 v21, vcc, 0, v31, vcc
	s_mov_b32 s5, 0xc000
	global_load_dwordx4 v[12:15], v[12:13], off
	v_add_co_u32_e32 v26, vcc, s5, v30
	global_load_dwordx4 v[16:19], v[16:17], off
	s_nop 0
	v_addc_co_u32_e32 v27, vcc, 0, v31, vcc
	s_mov_b32 s5, 0xe000
	global_load_dwordx4 v[20:23], v[20:21], off
	v_add_co_u32_e32 v30, vcc, s5, v30
	global_load_dwordx4 v[26:29], v[26:27], off
	s_nop 0
	v_addc_co_u32_e32 v31, vcc, 0, v31, vcc
	global_load_dwordx4 v[52:55], v[30:31], off
	v_and_b32_e32 v32, 0xf8, v39
	v_readlane_b32 s8, v254, 35
	v_readlane_b32 s9, v254, 36
	v_bfe_u32 v63, v36, 4, 2
	v_add_u32_e32 v30, 0x200, v36
	v_add_u32_e32 v62, s49, v32
	v_add_u32_e32 v34, 0x400, v36
	v_ashrrev_i32_e32 v33, 2, v36
	v_ashrrev_i32_e32 v39, 5, v30
	v_mad_u64_u32 v[42:43], s[8:9], v38, s81, v[62:63]
	v_add_u32_e32 v66, 0x600, v36
	v_bfi_b32 v32, -16, v33, v36
	v_ashrrev_i32_e32 v40, 5, v34
	v_mad_u64_u32 v[38:39], s[8:9], v39, s81, v[62:63]
	v_add_u32_e32 v82, 0x800, v36
	v_mul_lo_u32 v44, v32, s81
	v_mad_u64_u32 v[40:41], s[8:9], v40, s81, v[62:63]
	v_add_u32_e32 v56, 0xa00, v36
	v_add_u32_e32 v39, s49, v44
	v_add_u32_e32 v58, 0xc00, v36
	v_add_u32_e32 v60, 0xe00, v36
	v_and_b32_e32 v37, 15, v36
	v_lshlrev_b32_e32 v70, 3, v63
	v_lshl_or_b32 v41, s16, 7, v37
	v_mad_u32_u24 v43, v41, s81, 0
	v_ashrrev_i32_e32 v33, 31, v32
	v_mov_b64_e32 v[76:77], s[22:23]
	v_lshl_add_u64 v[64:65], s[90:91], 0, v[32:33]
	v_mad_u64_u32 v[78:79], s[8:9], v64, s78, v[76:77]
	v_mad_i32_i24 v79, v65, s78, v79
	s_add_u32 s6, s6, 0x10000
	v_ashrrev_i32_e32 v59, 31, v58
	v_ashrrev_i32_e32 v61, 31, v60
	s_addc_u32 s7, s7, 0
	s_lshl_b32 s76, s16, 8
	v_ashrrev_i32_e32 v57, 31, v56
	v_lshl_add_u64 v[84:85], v[56:57], 4, s[6:7]
	v_ashrrev_i32_e32 v83, 31, v82
	v_readlane_b32 s12, v254, 39
	v_readlane_b32 s13, v254, 40
	v_lshl_add_u64 v[100:101], s[6:7], 0, v[24:25]
	v_ashrrev_i32_e32 v67, 31, v66
	v_ashrrev_i32_e32 v35, 31, v34
	v_lshl_add_u64 v[34:35], v[34:35], 4, s[6:7]
	v_ashrrev_i32_e32 v31, 31, v30
	v_mov_b32_e32 v134, v230
	s_lshl_b32 s87, s58, 6
	v_readlane_b32 s4, v254, 31
	v_readlane_b32 s14, v254, 41
	v_readlane_b32 s15, v254, 42
	s_cmpk_gt_i32 s58, 0x7f
	s_cselect_b64 s[92:93], -1, 0
	s_and_b32 s59, s87, 0x3c0
	v_readlane_b32 s1, v254, 28
	s_waitcnt vmcnt(7)
	v_cvt_pk_bf16_f32 v0, v0, v1
	v_cvt_pk_bf16_f32 v1, v2, v3
	ds_write_b64 v42, v[0:1]
	s_waitcnt vmcnt(6)
	v_cvt_pk_bf16_f32 v0, v4, v5
	v_cvt_pk_bf16_f32 v1, v6, v7
	s_waitcnt vmcnt(5)
	v_cvt_pk_bf16_f32 v2, v8, v9
	v_cvt_pk_bf16_f32 v3, v10, v11
	ds_write_b64 v38, v[0:1]
	ds_write_b64 v40, v[2:3]
	v_ashrrev_i32_e32 v2, 5, v66
	s_waitcnt vmcnt(4)
	v_cvt_pk_bf16_f32 v0, v12, v13
	v_cvt_pk_bf16_f32 v1, v14, v15
	v_mad_u64_u32 v[44:45], s[8:9], v2, s81, v[62:63]
	v_ashrrev_i32_e32 v2, 5, v82
	ds_write_b64 v44, v[0:1]
	s_waitcnt vmcnt(3)
	v_cvt_pk_bf16_f32 v0, v16, v17
	v_cvt_pk_bf16_f32 v1, v18, v19
	v_mad_u64_u32 v[46:47], s[8:9], v2, s81, v[62:63]
	v_ashrrev_i32_e32 v2, 5, v56
	ds_write_b64 v46, v[0:1]
	s_waitcnt vmcnt(2)
	v_cvt_pk_bf16_f32 v0, v20, v21
	v_cvt_pk_bf16_f32 v1, v22, v23
	v_mad_u64_u32 v[48:49], s[8:9], v2, s81, v[62:63]
	v_ashrrev_i32_e32 v2, 5, v58
	ds_write_b64 v48, v[0:1]
	s_waitcnt vmcnt(1)
	v_cvt_pk_bf16_f32 v0, v26, v27
	v_cvt_pk_bf16_f32 v1, v28, v29
	v_mad_u64_u32 v[50:51], s[8:9], v2, s81, v[62:63]
	v_ashrrev_i32_e32 v2, 5, v60
	ds_write_b64 v50, v[0:1]
	s_waitcnt vmcnt(0)
	v_cvt_pk_bf16_f32 v0, v52, v53
	v_cvt_pk_bf16_f32 v1, v54, v55
	v_mad_u64_u32 v[52:53], s[8:9], v2, s81, v[62:63]
	ds_write_b64 v52, v[0:1]
	v_bitop3_b32 v0, v70, v36, 8 bitop3:0x78
	v_lshlrev_b32_e32 v47, 1, v0
	v_lshl_add_u32 v45, v63, 4, v39
	v_add_u32_e32 v0, v43, v47
	s_waitcnt lgkmcnt(0)
	s_barrier
	ds_read_b128 v[8:11], v45
	ds_read_b128 v[0:3], v0
	v_and_b32_e32 v49, 8, v36
	s_waitcnt lgkmcnt(0)
	v_mfma_f32_16x16x32_bf16 v[16:19], v[0:3], v[8:11], 0
	v_bitop3_b32 v0, v70, v49, 16 bitop3:0x1e
	v_lshlrev_b32_e32 v51, 1, v0
	v_add_u32_e32 v0, v43, v51
	ds_read_b128 v[12:15], v0 offset:4352
	v_bitop3_b32 v0, v70, v49, 32 bitop3:0x1e
	v_lshl_add_u64 v[54:55], v[78:79], 0, v[70:71]
	v_lshlrev_b64 v[4:5], 11, v[64:65]
	v_lshlrev_b32_e32 v53, 1, v0
	v_lshl_add_u64 v[94:95], s[64:65], 0, v[4:5]
	v_lshl_add_u64 v[4:5], v[60:61], 4, s[6:7]
	v_lshl_add_u64 v[6:7], v[58:59], 4, s[6:7]
	v_add_u32_e32 v0, v43, v53
	v_lshl_add_u64 v[36:37], v[54:55], 0, s[76:77]
	ds_read_b128 v[20:23], v0 offset:8704
	global_load_dwordx4 v[0:3], v[4:5], off
	s_nop 0
	global_load_dwordx4 v[4:7], v[6:7], off
	s_waitcnt lgkmcnt(1)
	v_mfma_f32_16x16x32_bf16 v[26:29], v[12:15], v[8:11], 0
	global_load_dwordx2 v[96:97], v[36:37], off
	v_bitop3_b32 v12, v70, v49, 48 bitop3:0x1e
	v_bitop3_b32 v58, v70, v49, 32 bitop3:0x36
	v_or_b32_e32 v74, 16, v49
	v_lshlrev_b32_e32 v104, 1, v12
	v_lshlrev_b32_e32 v106, 1, v58
	v_add_u32_e32 v12, v43, v104
	v_or_b32_e32 v13, 32, v70
	v_add_u32_e32 v58, v43, v106
	v_bitop3_b32 v62, v70, v74, 32 bitop3:0x36
	v_lshl_add_u32 v105, v13, 1, v39
	ds_read_b128 v[12:15], v12 offset:13056
	ds_read_b128 v[54:57], v105
	ds_read_b128 v[58:61], v58
	v_lshlrev_b32_e32 v107, 1, v62
	v_add_u32_e32 v62, v43, v107
	ds_read_b128 v[62:65], v62 offset:4352
	v_or_b32_e32 v108, 48, v49
	s_waitcnt lgkmcnt(1)
	v_mfma_f32_16x16x32_bf16 v[16:19], v[58:61], v[54:57], v[16:19]
	v_bitop3_b32 v58, v70, v49, 32 bitop3:0x14
	v_bitop3_b32 v59, v70, v108, 32 bitop3:0x36
	v_lshlrev_b32_e32 v109, 1, v58
	v_lshlrev_b32_e32 v110, 1, v59
	v_mfma_f32_16x16x32_bf16 v[78:81], v[12:15], v[8:11], 0
	v_lshl_add_u64 v[12:13], v[82:83], 4, s[6:7]
	v_add_u32_e32 v58, v43, v109
	v_or_b32_e32 v82, 64, v70
	s_waitcnt lgkmcnt(0)
	v_mfma_f32_16x16x32_bf16 v[26:29], v[62:65], v[54:57], v[26:29]
	v_add_u32_e32 v62, v43, v110
	v_lshl_add_u32 v111, v82, 1, v39
	v_bitop3_b32 v82, v70, v49, 64 bitop3:0x36
	v_mfma_f32_16x16x32_bf16 v[20:23], v[20:23], v[8:11], 0
	global_load_dwordx4 v[8:11], v[84:85], off
	s_nop 0
	global_load_dwordx4 v[12:15], v[12:13], off
	ds_read_b128 v[58:61], v58 offset:8704
	ds_read_b128 v[62:65], v62 offset:13056
	v_lshlrev_b32_e32 v112, 1, v82
	v_add_u32_e32 v86, v43, v112
	ds_read_b128 v[82:85], v111
	ds_read_b128 v[86:89], v86
	s_waitcnt lgkmcnt(3)
	v_mfma_f32_16x16x32_bf16 v[58:61], v[58:61], v[54:57], v[20:23]
	v_bitop3_b32 v24, v70, v108, 64 bitop3:0x36
	v_lshlrev_b32_e32 v115, 1, v24
	v_lshl_add_u64 v[66:67], v[66:67], 4, s[6:7]
	v_lshl_add_u32 v20, s17, 7, v32
	v_ashrrev_i32_e32 v21, 31, v20
	v_lshl_add_u64 v[20:21], v[20:21], 2, s[12:13]
	s_waitcnt lgkmcnt(2)
	v_mfma_f32_16x16x32_bf16 v[62:65], v[62:65], v[54:57], v[78:81]
	global_load_dword v54, v[20:21], off
	global_load_dwordx2 v[98:99], v[36:37], off offset:32
	v_or_b32_e32 v55, 32, v49
	v_add_u32_e32 v24, v43, v115
	s_waitcnt lgkmcnt(0)
	v_mfma_f32_16x16x32_bf16 v[78:81], v[86:89], v[82:85], v[16:19]
	v_readlane_b32 s2, v254, 29
	v_readlane_b32 s3, v254, 30
	s_waitcnt vmcnt(6)
	v_cvt_pk_bf16_f32 v0, v0, v1
	v_bitop3_b32 v16, v70, v74, 64 bitop3:0x36
	v_lshlrev_b32_e32 v113, 1, v16
	v_add_u32_e32 v16, v43, v113
	ds_read_b128 v[86:89], v16 offset:4352
	v_bitop3_b32 v16, v70, v55, 64 bitop3:0x36
	v_lshlrev_b32_e32 v114, 1, v16
	v_add_u32_e32 v16, v43, v114
	ds_read_b128 v[90:93], v16 offset:8704
	global_load_dwordx4 v[16:19], v[66:67], off
	global_load_dwordx4 v[20:23], v[34:35], off
	s_waitcnt lgkmcnt(1)
	v_mfma_f32_16x16x32_bf16 v[86:89], v[86:89], v[82:85], v[26:29]
	s_nop 2
	ds_read_b128 v[24:27], v24 offset:13056
	v_bitop3_b32 v28, v70, v49, s83 bitop3:0x36
	v_lshlrev_b32_e32 v49, 1, v28
	v_add_u32_e32 v28, v43, v49
	v_lshl_add_u64 v[34:35], v[30:31], 4, s[6:7]
	ds_read_b128 v[28:31], v28
	s_waitcnt lgkmcnt(2)
	v_mfma_f32_16x16x32_bf16 v[56:59], v[90:93], v[82:85], v[58:61]
	s_waitcnt vmcnt(7)
	v_cvt_pk_bf16_f32 v4, v4, v5
	v_cvt_pk_bf16_f32 v5, v6, v7
	v_cvt_pk_bf16_f32 v1, v2, v3
	v_or_b32_e32 v60, 0x60, v70
	v_lshl_add_u32 v39, v60, 1, v39
	s_waitcnt lgkmcnt(1)
	v_mfma_f32_16x16x32_bf16 v[60:63], v[24:27], v[82:85], v[62:65]
	v_bitop3_b32 v24, v70, v74, s83 bitop3:0x36
	ds_read_b128 v[90:93], v39
	v_lshlrev_b32_e32 v74, 1, v24
	v_add_u32_e32 v24, v43, v74
	ds_read_b128 v[64:67], v24 offset:4352
	v_bitop3_b32 v24, v70, v55, s83 bitop3:0x36
	v_lshlrev_b32_e32 v116, 1, v24
	v_add_u32_e32 v24, v43, v116
	ds_read_b128 v[82:85], v24 offset:8704
	s_waitcnt lgkmcnt(2)
	v_mfma_f32_16x16x32_bf16 v[78:81], v[28:31], v[90:93], v[78:81]
	global_load_dwordx4 v[24:27], v[34:35], off
	global_load_dwordx4 v[28:31], v[100:101], off
	s_nop 0
	global_load_dwordx2 v[100:101], v[36:37], off offset:64
	global_load_dwordx2 v[102:103], v[36:37], off offset:96
	v_bitop3_b32 v34, v70, v108, s83 bitop3:0x36
	v_lshlrev_b32_e32 v108, 1, v34
	v_add_u32_e32 v34, v43, v108
	s_waitcnt lgkmcnt(1)
	v_mfma_f32_16x16x32_bf16 v[64:67], v[64:67], v[90:93], v[86:89]
	s_waitcnt vmcnt(10)
	v_and_b32_e32 v35, 0xffff0000, v96
	v_mul_f32_e32 v55, 0x3d372713, v35
	v_fma_f32 v55, v55, v35, 1.0
	ds_read_b128 v[86:89], v34 offset:13056
	v_lshlrev_b32_e32 v34, 16, v96
	v_mul_f32_e32 v43, 0x3d372713, v34
	v_fma_f32 v43, v43, v34, 1.0
	v_mul_f32_e32 v43, v43, v34
	v_mul_f32_e32 v43, 0xc0135761, v43
	v_mul_f32_e32 v55, v55, v35
	v_exp_f32_e32 v43, v43
	v_mul_f32_e32 v55, 0xc0135761, v55
	v_exp_f32_e32 v55, v55
	s_waitcnt lgkmcnt(1)
	v_mfma_f32_16x16x32_bf16 v[56:59], v[82:85], v[90:93], v[56:59]
	v_add_f32_e32 v43, 1.0, v43
	v_lshlrev_b32_e32 v84, 16, v97
	v_rcp_f32_e32 v82, v43
	v_add_f32_e32 v43, 1.0, v55
	v_and_b32_e32 v85, 0xffff0000, v97
	v_mul_f32_e32 v55, 0x3d372713, v84
	v_fma_f32 v55, v55, v84, 1.0
	v_mul_f32_e32 v83, 0x3d372713, v85
	v_mul_f32_e32 v55, v55, v84
	v_fma_f32 v83, v83, v85, 1.0
	v_mul_f32_e32 v55, 0xc0135761, v55
	v_mul_f32_e32 v83, v83, v85
	v_exp_f32_e32 v55, v55
	v_mul_f32_e32 v83, 0xc0135761, v83
	s_waitcnt lgkmcnt(0)
	v_mfma_f32_16x16x32_bf16 v[60:63], v[86:89], v[90:93], v[60:63]
	v_exp_f32_e32 v87, v83
	v_rcp_f32_e32 v83, v43
	v_add_f32_e32 v43, 1.0, v55
	v_rcp_f32_e32 v86, v43
	v_add_f32_e32 v43, 1.0, v87
	v_rcp_f32_e32 v87, v43
	v_pk_mul_f32 v[34:35], v[82:83], v[34:35]
	s_waitcnt vmcnt(7)
	v_pk_add_f32 v[78:79], v[54:55], v[78:79] op_sel_hi:[0,1]
	v_pk_mul_f32 v[34:35], v[34:35], v[78:79]
	v_pk_mul_f32 v[78:79], v[86:87], v[84:85]
	v_pk_add_f32 v[80:81], v[54:55], v[80:81] op_sel_hi:[0,1]
	v_pk_mul_f32 v[78:79], v[78:79], v[80:81]
	v_or_b32_e32 v70, s76, v70
	v_cvt_pk_bf16_f32 v81, v78, v79
	s_waitcnt vmcnt(6)
	v_lshlrev_b32_e32 v78, 16, v98
	v_and_b32_e32 v79, 0xffff0000, v98
	v_mul_f32_e32 v43, 0x3d372713, v78
	v_fma_f32 v43, v43, v78, 1.0
	v_mul_f32_e32 v55, 0x3d372713, v79
	v_mul_f32_e32 v43, v43, v78
	v_fma_f32 v55, v55, v79, 1.0
	v_mul_f32_e32 v43, 0xc0135761, v43
	v_mul_f32_e32 v55, v55, v79
	v_exp_f32_e32 v43, v43
	v_mul_f32_e32 v55, 0xc0135761, v55
	v_exp_f32_e32 v55, v55
	v_cvt_pk_bf16_f32 v80, v34, v35
	v_lshl_add_u64 v[34:35], v[94:95], 0, v[70:71]
	v_add_f32_e32 v43, 1.0, v43
	v_lshlrev_b32_e32 v82, 16, v99
	global_store_dwordx2 v[34:35], v[80:81], off
	v_rcp_f32_e32 v80, v43
	v_add_f32_e32 v43, 1.0, v55
	v_and_b32_e32 v83, 0xffff0000, v99
	v_mul_f32_e32 v55, 0x3d372713, v82
	v_fma_f32 v55, v55, v82, 1.0
	v_mul_f32_e32 v70, 0x3d372713, v83
	v_mul_f32_e32 v55, v55, v82
	v_fma_f32 v70, v70, v83, 1.0
	v_mul_f32_e32 v55, 0xc0135761, v55
	v_mul_f32_e32 v70, v70, v83
	v_exp_f32_e32 v55, v55
	v_mul_f32_e32 v70, 0xc0135761, v70
	v_exp_f32_e32 v70, v70
	v_rcp_f32_e32 v81, v43
	v_add_f32_e32 v43, 1.0, v55
	v_rcp_f32_e32 v84, v43
	v_add_f32_e32 v43, 1.0, v70
	v_rcp_f32_e32 v85, v43
	v_pk_mul_f32 v[78:79], v[80:81], v[78:79]
	v_pk_add_f32 v[64:65], v[54:55], v[64:65] op_sel_hi:[0,1]
	v_pk_mul_f32 v[64:65], v[78:79], v[64:65]
	v_pk_mul_f32 v[78:79], v[84:85], v[82:83]
	v_pk_add_f32 v[66:67], v[54:55], v[66:67] op_sel_hi:[0,1]
	v_pk_mul_f32 v[66:67], v[78:79], v[66:67]
	v_cvt_pk_bf16_f32 v64, v64, v65
	v_cvt_pk_bf16_f32 v65, v66, v67
	s_waitcnt vmcnt(2)
	v_lshlrev_b32_e32 v66, 16, v100
	v_and_b32_e32 v67, 0xffff0000, v100
	v_mul_f32_e32 v43, 0x3d372713, v66
	v_fma_f32 v43, v43, v66, 1.0
	v_mul_f32_e32 v55, 0x3d372713, v67
	v_mul_f32_e32 v43, v43, v66
	v_fma_f32 v55, v55, v67, 1.0
	v_mul_f32_e32 v43, 0xc0135761, v43
	v_mul_f32_e32 v55, v55, v67
	v_exp_f32_e32 v43, v43
	v_mul_f32_e32 v55, 0xc0135761, v55
	v_exp_f32_e32 v55, v55
	v_lshlrev_b32_e32 v78, 16, v101
	v_add_f32_e32 v43, 1.0, v43
	global_store_dwordx2 v[34:35], v[64:65], off offset:32
	v_rcp_f32_e32 v64, v43
	v_add_f32_e32 v43, 1.0, v55
	v_and_b32_e32 v79, 0xffff0000, v101
	v_mul_f32_e32 v55, 0x3d372713, v78
	v_fma_f32 v55, v55, v78, 1.0
	v_mul_f32_e32 v65, 0x3d372713, v79
	v_mul_f32_e32 v55, v55, v78
	v_fma_f32 v65, v65, v79, 1.0
	v_mul_f32_e32 v55, 0xc0135761, v55
	v_mul_f32_e32 v65, v65, v79
	v_exp_f32_e32 v55, v55
	v_mul_f32_e32 v65, 0xc0135761, v65
	v_exp_f32_e32 v70, v65
	v_rcp_f32_e32 v65, v43
	v_add_f32_e32 v43, 1.0, v55
	v_rcp_f32_e32 v80, v43
	v_add_f32_e32 v43, 1.0, v70
	v_rcp_f32_e32 v81, v43
	v_pk_mul_f32 v[64:65], v[64:65], v[66:67]
	v_pk_add_f32 v[56:57], v[54:55], v[56:57] op_sel_hi:[0,1]
	v_pk_mul_f32 v[56:57], v[64:65], v[56:57]
	v_pk_mul_f32 v[64:65], v[80:81], v[78:79]
	v_pk_add_f32 v[58:59], v[54:55], v[58:59] op_sel_hi:[0,1]
	v_pk_mul_f32 v[58:59], v[64:65], v[58:59]
	v_cvt_pk_bf16_f32 v56, v56, v57
	v_cvt_pk_bf16_f32 v57, v58, v59
	s_waitcnt vmcnt(2)
	v_lshlrev_b32_e32 v58, 16, v102
	v_and_b32_e32 v59, 0xffff0000, v102
	v_mul_f32_e32 v43, 0x3d372713, v58
	v_fma_f32 v43, v43, v58, 1.0
	v_mul_f32_e32 v55, 0x3d372713, v59
	v_mul_f32_e32 v43, v43, v58
	v_fma_f32 v55, v55, v59, 1.0
	v_mul_f32_e32 v43, 0xc0135761, v43
	v_mul_f32_e32 v55, v55, v59
	v_exp_f32_e32 v43, v43
	v_mul_f32_e32 v55, 0xc0135761, v55
	v_exp_f32_e32 v55, v55
	v_lshlrev_b32_e32 v64, 16, v103
	v_add_f32_e32 v43, 1.0, v43
	global_store_dwordx2 v[34:35], v[56:57], off offset:64
	v_rcp_f32_e32 v56, v43
	v_add_f32_e32 v43, 1.0, v55
	v_and_b32_e32 v65, 0xffff0000, v103
	v_mul_f32_e32 v55, 0x3d372713, v64
	v_fma_f32 v55, v55, v64, 1.0
	v_mul_f32_e32 v57, 0x3d372713, v65
	v_mul_f32_e32 v55, v55, v64
	v_fma_f32 v57, v57, v65, 1.0
	v_mul_f32_e32 v55, 0xc0135761, v55
	v_mul_f32_e32 v57, v57, v65
	v_exp_f32_e32 v55, v55
	v_mul_f32_e32 v57, 0xc0135761, v57
	v_exp_f32_e32 v67, v57
	v_rcp_f32_e32 v57, v43
	v_add_f32_e32 v43, 1.0, v55
	v_rcp_f32_e32 v66, v43
	v_add_f32_e32 v43, 1.0, v67
	v_rcp_f32_e32 v67, v43
	v_pk_mul_f32 v[56:57], v[56:57], v[58:59]
	v_pk_add_f32 v[58:59], v[54:55], v[60:61] op_sel_hi:[0,1]
	v_pk_mul_f32 v[56:57], v[56:57], v[58:59]
	v_pk_mul_f32 v[58:59], v[66:67], v[64:65]
	v_pk_add_f32 v[54:55], v[54:55], v[62:63] op_sel_hi:[0,1]
	v_pk_mul_f32 v[54:55], v[58:59], v[54:55]
	v_cvt_pk_bf16_f32 v56, v56, v57
	v_cvt_pk_bf16_f32 v57, v54, v55
	v_cvt_pk_bf16_f32 v28, v28, v29
	v_cvt_pk_bf16_f32 v29, v30, v31
	v_cvt_pk_bf16_f32 v24, v24, v25
	v_cvt_pk_bf16_f32 v25, v26, v27
	v_cvt_pk_bf16_f32 v20, v20, v21
	v_cvt_pk_bf16_f32 v21, v22, v23
	v_cvt_pk_bf16_f32 v16, v16, v17
	v_cvt_pk_bf16_f32 v17, v18, v19
	v_cvt_pk_bf16_f32 v12, v12, v13
	v_cvt_pk_bf16_f32 v13, v14, v15
	v_cvt_pk_bf16_f32 v8, v8, v9
	v_cvt_pk_bf16_f32 v9, v10, v11
	global_store_dwordx2 v[34:35], v[56:57], off offset:96
	s_barrier
	ds_write_b64 v42, v[28:29]
	ds_write_b64 v38, v[24:25]
	ds_write_b64 v40, v[20:21]
	ds_write_b64 v44, v[16:17]
	ds_write_b64 v46, v[12:13]
	ds_write_b64 v48, v[8:9]
	ds_write_b64 v50, v[4:5]
	ds_write_b64 v52, v[0:1]
	v_or_b32_e32 v0, 64, v41
	v_mad_u32_u24 v44, v0, s81, 0
	v_add_u32_e32 v0, v44, v47
	v_add_u32_e32 v24, v44, v106
	s_waitcnt lgkmcnt(0)
	s_barrier
	ds_read_b128 v[0:3], v0
	ds_read_b128 v[4:7], v45
	v_add_u32_e32 v8, v44, v51
	global_load_dwordx2 v[42:43], v[36:37], off offset:128
	ds_read_b128 v[12:15], v105
	ds_read_b128 v[24:27], v24
	v_add_u32_e32 v16, v44, v53
	v_add_u32_e32 v20, v44, v104
	ds_read_b128 v[8:11], v8 offset:4352
	ds_read_b128 v[16:19], v16 offset:8704
	ds_read_b128 v[20:23], v20 offset:13056
	s_waitcnt lgkmcnt(5)
	v_mfma_f32_16x16x32_bf16 v[0:3], v[0:3], v[4:7], 0
	s_waitcnt lgkmcnt(3)
	v_mfma_f32_16x16x32_bf16 v[24:27], v[24:27], v[12:15], v[0:3]
	s_waitcnt lgkmcnt(1)
	v_mfma_f32_16x16x32_bf16 v[16:19], v[16:19], v[4:7], 0
	s_nop 3
	v_add_u32_e32 v0, v44, v109
	ds_read_b128 v[28:31], v0 offset:8704
	v_add_u32_e32 v0, v44, v110
	v_mfma_f32_16x16x32_bf16 v[8:11], v[8:11], v[4:7], 0
	s_waitcnt lgkmcnt(1)
	v_mfma_f32_16x16x32_bf16 v[4:7], v[20:23], v[4:7], 0
	v_add_u32_e32 v20, v44, v107
	ds_read_b128 v[20:23], v20 offset:4352
	s_waitcnt lgkmcnt(0)
	v_mfma_f32_16x16x32_bf16 v[8:11], v[20:23], v[12:15], v[8:11]
	ds_read_b128 v[20:23], v0 offset:13056
	v_lshl_add_u64 v[0:1], s[76:77], 0, v[32:33]
	v_lshl_add_u64 v[0:1], v[0:1], 2, s[12:13]
	global_load_dword v0, v[0:1], off offset:2560
	v_add_u32_e32 v1, v44, v112
	global_load_dwordx2 v[32:33], v[36:37], off offset:160
	v_mfma_f32_16x16x32_bf16 v[16:19], v[28:31], v[12:15], v[16:19]
	ds_read_b128 v[28:31], v1
	s_and_b32 s76, s87, 0xc0
	s_cmpk_lt_i32 s58, 0x80
	s_waitcnt lgkmcnt(1)
	v_mfma_f32_16x16x32_bf16 v[2:5], v[20:23], v[12:15], v[4:7]
	ds_read_b128 v[12:15], v111
	v_add_u32_e32 v1, v44, v113
	ds_read_b128 v[20:23], v1 offset:4352
	ds_read_b128 v[38:41], v39
	v_add_u32_e32 v1, v44, v114
	s_waitcnt lgkmcnt(2)
	v_mfma_f32_16x16x32_bf16 v[24:27], v[28:31], v[12:15], v[24:27]
	ds_read_b128 v[28:31], v1 offset:8704
	v_add_u32_e32 v1, v44, v115
	s_cselect_b64 s[8:9], -1, 0
	s_waitcnt lgkmcnt(2)
	v_mfma_f32_16x16x32_bf16 v[6:9], v[20:23], v[12:15], v[8:11]
	ds_read_b128 v[20:23], v1 offset:13056
	v_add_u32_e32 v1, v44, v49
	s_and_b64 vcc, s[8:9], exec
	s_waitcnt lgkmcnt(1)
	v_mfma_f32_16x16x32_bf16 v[16:19], v[28:31], v[12:15], v[16:19]
	ds_read_b128 v[28:31], v1
	v_add_u32_e32 v1, v44, v74
	s_cselect_b32 s80, s76, s59
	s_waitcnt lgkmcnt(1)
	v_mfma_f32_16x16x32_bf16 v[2:5], v[20:23], v[12:15], v[2:5]
	ds_read_b128 v[10:13], v1 offset:4352
	v_add_u32_e32 v1, v44, v116
	s_waitcnt lgkmcnt(1)
	v_mfma_f32_16x16x32_bf16 v[20:23], v[28:31], v[38:41], v[24:27]
	s_nop 2
	ds_read_b128 v[24:27], v1 offset:8704
	global_load_dwordx2 v[28:29], v[36:37], off offset:192
	global_load_dwordx2 v[30:31], v[36:37], off offset:224
	v_add_u32_e32 v1, v44, v108
	s_waitcnt lgkmcnt(1)
	v_mfma_f32_16x16x32_bf16 v[6:9], v[10:13], v[38:41], v[6:9]
	ds_read_b128 v[10:13], v1 offset:13056
	s_waitcnt lgkmcnt(1)
	v_mfma_f32_16x16x32_bf16 v[14:17], v[24:27], v[38:41], v[16:19]
	s_waitcnt vmcnt(4)
	s_nop 1
	v_lshlrev_b32_e32 v18, 16, v42
	v_and_b32_e32 v19, 0xffff0000, v42
	v_mul_f32_e32 v1, 0x3d372713, v18
	v_fma_f32 v1, v1, v18, 1.0
	v_mul_f32_e32 v24, 0x3d372713, v19
	v_mul_f32_e32 v1, v1, v18
	v_fma_f32 v24, v24, v19, 1.0
	v_mul_f32_e32 v1, 0xc0135761, v1
	v_mul_f32_e32 v24, v24, v19
	v_exp_f32_e32 v1, v1
	v_mul_f32_e32 v24, 0xc0135761, v24
	s_waitcnt lgkmcnt(0)
	v_mfma_f32_16x16x32_bf16 v[2:5], v[10:13], v[38:41], v[2:5]
	v_lshlrev_b32_e32 v12, 16, v43
	v_exp_f32_e32 v24, v24
	v_mul_f32_e32 v11, 0x3d372713, v12
	v_fma_f32 v11, v11, v12, 1.0
	v_mul_f32_e32 v11, v11, v12
	v_add_f32_e32 v1, 1.0, v1
	v_and_b32_e32 v13, 0xffff0000, v43
	v_mul_f32_e32 v11, 0xc0135761, v11
	v_rcp_f32_e32 v10, v1
	v_add_f32_e32 v1, 1.0, v24
	v_exp_f32_e32 v24, v11
	v_mul_f32_e32 v11, 0x3d372713, v13
	v_fma_f32 v11, v11, v13, 1.0
	v_mul_f32_e32 v11, v11, v13
	v_mul_f32_e32 v11, 0xc0135761, v11
	v_exp_f32_e32 v25, v11
	v_rcp_f32_e32 v11, v1
	v_add_f32_e32 v1, 1.0, v24
	v_rcp_f32_e32 v24, v1
	v_add_f32_e32 v1, 1.0, v25
	v_rcp_f32_e32 v25, v1
	v_pk_mul_f32 v[10:11], v[10:11], v[18:19]
	s_waitcnt vmcnt(3)
	v_pk_add_f32 v[18:19], v[0:1], v[20:21] op_sel_hi:[0,1]
	v_pk_mul_f32 v[10:11], v[10:11], v[18:19]
	v_pk_mul_f32 v[12:13], v[24:25], v[12:13]
	v_pk_add_f32 v[18:19], v[0:1], v[22:23] op_sel_hi:[0,1]
	v_pk_mul_f32 v[12:13], v[12:13], v[18:19]
	v_cvt_pk_bf16_f32 v10, v10, v11
	v_cvt_pk_bf16_f32 v11, v12, v13
	s_waitcnt vmcnt(2)
	v_lshlrev_b32_e32 v12, 16, v32
	v_and_b32_e32 v13, 0xffff0000, v32
	v_mul_f32_e32 v1, 0x3d372713, v12
	v_fma_f32 v1, v1, v12, 1.0
	v_mul_f32_e32 v18, 0x3d372713, v13
	v_mul_f32_e32 v1, v1, v12
	v_fma_f32 v18, v18, v13, 1.0
	v_mul_f32_e32 v1, 0xc0135761, v1
	v_mul_f32_e32 v18, v18, v13
	v_exp_f32_e32 v1, v1
	v_mul_f32_e32 v18, 0xc0135761, v18
	v_exp_f32_e32 v18, v18
	global_store_dwordx2 v[34:35], v[10:11], off offset:128
	v_add_f32_e32 v1, 1.0, v1
	v_rcp_f32_e32 v10, v1
	v_add_f32_e32 v1, 1.0, v18
	v_lshlrev_b32_e32 v18, 16, v33
	v_mul_f32_e32 v11, 0x3d372713, v18
	v_fma_f32 v11, v11, v18, 1.0
	v_mul_f32_e32 v11, v11, v18
	v_and_b32_e32 v19, 0xffff0000, v33
	v_mul_f32_e32 v11, 0xc0135761, v11
	v_exp_f32_e32 v20, v11
	v_mul_f32_e32 v11, 0x3d372713, v19
	v_fma_f32 v11, v11, v19, 1.0
	v_mul_f32_e32 v11, v11, v19
	v_mul_f32_e32 v11, 0xc0135761, v11
	v_exp_f32_e32 v21, v11
	v_rcp_f32_e32 v11, v1
	v_add_f32_e32 v1, 1.0, v20
	v_rcp_f32_e32 v20, v1
	v_add_f32_e32 v1, 1.0, v21
	v_rcp_f32_e32 v21, v1
	v_pk_mul_f32 v[10:11], v[10:11], v[12:13]
	v_pk_add_f32 v[6:7], v[0:1], v[6:7] op_sel_hi:[0,1]
	v_pk_mul_f32 v[6:7], v[10:11], v[6:7]
	v_pk_mul_f32 v[10:11], v[20:21], v[18:19]
	v_pk_add_f32 v[8:9], v[0:1], v[8:9] op_sel_hi:[0,1]
	v_pk_mul_f32 v[8:9], v[10:11], v[8:9]
	v_cvt_pk_bf16_f32 v6, v6, v7
	v_cvt_pk_bf16_f32 v7, v8, v9
	s_waitcnt vmcnt(2)
	v_lshlrev_b32_e32 v8, 16, v28
	v_and_b32_e32 v9, 0xffff0000, v28
	v_mul_f32_e32 v1, 0x3d372713, v8
	v_fma_f32 v1, v1, v8, 1.0
	v_mul_f32_e32 v10, 0x3d372713, v9
	v_mul_f32_e32 v1, v1, v8
	v_fma_f32 v10, v10, v9, 1.0
	v_mul_f32_e32 v1, 0xc0135761, v1
	v_mul_f32_e32 v10, v10, v9
	v_exp_f32_e32 v1, v1
	v_mul_f32_e32 v10, 0xc0135761, v10
	v_exp_f32_e32 v10, v10
	global_store_dwordx2 v[34:35], v[6:7], off offset:160
	v_add_f32_e32 v1, 1.0, v1
	v_rcp_f32_e32 v6, v1
	v_add_f32_e32 v1, 1.0, v10
	v_lshlrev_b32_e32 v10, 16, v29
	v_mul_f32_e32 v7, 0x3d372713, v10
	v_fma_f32 v7, v7, v10, 1.0
	v_mul_f32_e32 v7, v7, v10
	v_and_b32_e32 v11, 0xffff0000, v29
	v_mul_f32_e32 v7, 0xc0135761, v7
	v_exp_f32_e32 v12, v7
	v_mul_f32_e32 v7, 0x3d372713, v11
	v_fma_f32 v7, v7, v11, 1.0
	v_mul_f32_e32 v7, v7, v11
	v_mul_f32_e32 v7, 0xc0135761, v7
	v_exp_f32_e32 v13, v7
	v_rcp_f32_e32 v7, v1
	v_add_f32_e32 v1, 1.0, v12
	v_rcp_f32_e32 v12, v1
	v_add_f32_e32 v1, 1.0, v13
	v_rcp_f32_e32 v13, v1
	v_pk_mul_f32 v[6:7], v[6:7], v[8:9]
	v_pk_add_f32 v[8:9], v[0:1], v[14:15] op_sel_hi:[0,1]
	v_pk_mul_f32 v[6:7], v[6:7], v[8:9]
	v_pk_mul_f32 v[8:9], v[12:13], v[10:11]
	v_pk_add_f32 v[10:11], v[0:1], v[16:17] op_sel_hi:[0,1]
	v_pk_mul_f32 v[8:9], v[8:9], v[10:11]
	v_cvt_pk_bf16_f32 v6, v6, v7
	v_cvt_pk_bf16_f32 v7, v8, v9
	s_waitcnt vmcnt(2)
	v_lshlrev_b32_e32 v8, 16, v30
	v_and_b32_e32 v9, 0xffff0000, v30
	v_mul_f32_e32 v1, 0x3d372713, v8
	v_fma_f32 v1, v1, v8, 1.0
	v_mul_f32_e32 v10, 0x3d372713, v9
	v_mul_f32_e32 v1, v1, v8
	v_fma_f32 v10, v10, v9, 1.0
	v_mul_f32_e32 v1, 0xc0135761, v1
	v_mul_f32_e32 v10, v10, v9
	v_exp_f32_e32 v1, v1
	v_mul_f32_e32 v10, 0xc0135761, v10
	v_exp_f32_e32 v10, v10
	global_store_dwordx2 v[34:35], v[6:7], off offset:192
	v_add_f32_e32 v1, 1.0, v1
	v_rcp_f32_e32 v6, v1
	v_add_f32_e32 v1, 1.0, v10
	v_lshlrev_b32_e32 v10, 16, v31
	v_mul_f32_e32 v7, 0x3d372713, v10
	v_fma_f32 v7, v7, v10, 1.0
	v_mul_f32_e32 v7, v7, v10
	v_and_b32_e32 v11, 0xffff0000, v31
	v_mul_f32_e32 v7, 0xc0135761, v7
	v_exp_f32_e32 v12, v7
	v_mul_f32_e32 v7, 0x3d372713, v11
	v_fma_f32 v7, v7, v11, 1.0
	v_mul_f32_e32 v7, v7, v11
	v_mul_f32_e32 v7, 0xc0135761, v7
	v_exp_f32_e32 v13, v7
	v_rcp_f32_e32 v7, v1
	v_add_f32_e32 v1, 1.0, v12
	v_rcp_f32_e32 v12, v1
	v_add_f32_e32 v1, 1.0, v13
	v_rcp_f32_e32 v13, v1
	v_pk_mul_f32 v[6:7], v[6:7], v[8:9]
	v_pk_add_f32 v[2:3], v[0:1], v[2:3] op_sel_hi:[0,1]
	v_pk_mul_f32 v[2:3], v[6:7], v[2:3]
	v_pk_mul_f32 v[6:7], v[12:13], v[10:11]
	v_pk_add_f32 v[0:1], v[0:1], v[4:5] op_sel_hi:[0,1]
	v_pk_mul_f32 v[0:1], v[6:7], v[0:1]
	v_cvt_pk_bf16_f32 v2, v2, v3
	v_cvt_pk_bf16_f32 v3, v0, v1
	global_store_dwordx2 v[34:35], v[2:3], off offset:224
	s_barrier
	s_barrier
	v_mov_b32_e32 v9, v71
	v_ashrrev_i32_e32 v78, 3, v134
	v_ashrrev_i32_e32 v79, 7, v134
	v_add_u32_e32 v115, 64, v78
	v_add_u32_e32 v86, s87, v79
	v_lshlrev_b32_e32 v2, 7, v78
	v_ashrrev_i32_e32 v116, 4, v115
	v_and_b32_e32 v135, 7, v134
	v_mad_i64_i32 v[0:1], s[4:5], v86, s78, v[76:77]
	v_and_b32_e32 v70, 0x780, v2
	v_add_u32_e32 v114, s87, v116
	v_lshl_add_u64 v[0:1], v[0:1], 0, v[70:71]
	v_lshlrev_b32_e32 v8, 4, v135
	v_mad_i64_i32 v[2:3], s[4:5], v114, s78, v[76:77]
	v_lshl_add_u64 v[0:1], v[0:1], 0, v[8:9]
	v_lshl_add_u64 v[2:3], v[2:3], 0, v[70:71]
	v_lshl_add_u64 v[4:5], v[2:3], 0, v[8:9]
	global_load_dwordx4 v[0:3], v[0:1], off offset:3072
	s_nop 0
	global_load_dwordx4 v[64:67], v[4:5], off offset:3072
	v_add_u32_e32 v113, 0x80, v78
	v_ashrrev_i32_e32 v152, 4, v113
	v_add_u32_e32 v111, 0xc0, v78
	v_add_u32_e32 v112, s87, v152
	v_ashrrev_i32_e32 v151, 4, v111
	v_mad_i64_i32 v[4:5], s[4:5], v112, s78, v[76:77]
	v_add_u32_e32 v110, s87, v151
	v_add_u32_e32 v109, 0x100, v78
	v_lshl_add_u64 v[4:5], v[4:5], 0, v[70:71]
	v_mad_i64_i32 v[6:7], s[4:5], v110, s78, v[76:77]
	v_ashrrev_i32_e32 v150, 4, v109
	v_add_u32_e32 v107, 0x140, v78
	v_lshl_add_u64 v[4:5], v[4:5], 0, v[8:9]
	v_lshl_add_u64 v[6:7], v[6:7], 0, v[70:71]
	v_add_u32_e32 v108, s87, v150
	v_ashrrev_i32_e32 v149, 4, v107
	v_lshl_add_u64 v[6:7], v[6:7], 0, v[8:9]
	global_load_dwordx4 v[60:63], v[4:5], off offset:3072
	global_load_dwordx4 v[56:59], v[6:7], off offset:3072
	v_mad_i64_i32 v[4:5], s[4:5], v108, s78, v[76:77]
	v_add_u32_e32 v106, s87, v149
	v_add_u32_e32 v105, 0x180, v78
	v_lshl_add_u64 v[4:5], v[4:5], 0, v[70:71]
	v_mad_i64_i32 v[6:7], s[4:5], v106, s78, v[76:77]
	v_ashrrev_i32_e32 v148, 4, v105
	v_add_u32_e32 v103, 0x1c0, v78
	v_lshl_add_u64 v[4:5], v[4:5], 0, v[8:9]
	v_lshl_add_u64 v[6:7], v[6:7], 0, v[70:71]
	v_add_u32_e32 v104, s87, v148
	v_ashrrev_i32_e32 v147, 4, v103
	v_lshl_add_u64 v[6:7], v[6:7], 0, v[8:9]
	global_load_dwordx4 v[52:55], v[4:5], off offset:3072
	global_load_dwordx4 v[48:51], v[6:7], off offset:3072
	v_mad_i64_i32 v[4:5], s[4:5], v104, s78, v[76:77]
	v_add_u32_e32 v102, s87, v147
	v_add_u32_e32 v101, 0x200, v78
	v_lshl_add_u64 v[4:5], v[4:5], 0, v[70:71]
	v_mad_i64_i32 v[6:7], s[4:5], v102, s78, v[76:77]
	v_ashrrev_i32_e32 v146, 4, v101
	v_add_u32_e32 v99, 0x240, v78
	v_lshl_add_u64 v[4:5], v[4:5], 0, v[8:9]
	v_lshl_add_u64 v[6:7], v[6:7], 0, v[70:71]
	v_add_u32_e32 v100, s87, v146
	v_ashrrev_i32_e32 v145, 4, v99
	v_lshl_add_u64 v[6:7], v[6:7], 0, v[8:9]
	global_load_dwordx4 v[44:47], v[4:5], off offset:3072
	global_load_dwordx4 v[40:43], v[6:7], off offset:3072
	v_mad_i64_i32 v[4:5], s[4:5], v100, s78, v[76:77]
	v_add_u32_e32 v98, s87, v145
	v_add_u32_e32 v97, 0x280, v78
	v_lshl_add_u64 v[4:5], v[4:5], 0, v[70:71]
	v_mad_i64_i32 v[6:7], s[4:5], v98, s78, v[76:77]
	v_ashrrev_i32_e32 v144, 4, v97
	v_lshl_add_u64 v[4:5], v[4:5], 0, v[8:9]
	v_lshl_add_u64 v[6:7], v[6:7], 0, v[70:71]
	v_add_u32_e32 v96, s87, v144
	v_add_u32_e32 v95, 0x2c0, v78
	v_lshl_add_u64 v[6:7], v[6:7], 0, v[8:9]
	global_load_dwordx4 v[36:39], v[4:5], off offset:3072
	global_load_dwordx4 v[32:35], v[6:7], off offset:3072
	v_mad_i64_i32 v[4:5], s[4:5], v96, s78, v[76:77]
	v_ashrrev_i32_e32 v143, 4, v95
	v_lshl_add_u64 v[4:5], v[4:5], 0, v[70:71]
	v_add_u32_e32 v94, s87, v143
	v_add_u32_e32 v93, 0x300, v78
	v_lshl_add_u64 v[10:11], v[4:5], 0, v[8:9]
	v_mad_i64_i32 v[4:5], s[4:5], v94, s78, v[76:77]
	v_ashrrev_i32_e32 v142, 4, v93
	v_add_u32_e32 v91, 0x340, v78
	v_lshl_add_u64 v[4:5], v[4:5], 0, v[70:71]
	v_add_u32_e32 v92, s87, v142
	v_ashrrev_i32_e32 v141, 4, v91
	v_add_u32_e32 v89, 0x380, v78
	v_lshl_add_u64 v[12:13], v[4:5], 0, v[8:9]
	v_mad_i64_i32 v[4:5], s[4:5], v92, s78, v[76:77]
	v_add_u32_e32 v90, s87, v141
	v_ashrrev_i32_e32 v140, 4, v89
	v_add_u32_e32 v137, 0x3c0, v78
	v_lshl_add_u64 v[14:15], v[4:5], 0, v[70:71]
	v_mad_i64_i32 v[4:5], s[4:5], v90, s78, v[76:77]
	v_add_u32_e32 v88, s87, v140
	v_ashrrev_i32_e32 v139, 4, v137
	v_lshl_add_u64 v[16:17], v[4:5], 0, v[70:71]
	v_mad_i64_i32 v[4:5], s[4:5], v88, s78, v[76:77]
	v_add_u32_e32 v74, s87, v139
	v_lshl_add_u64 v[84:85], v[4:5], 0, v[70:71]
	v_mad_i64_i32 v[4:5], s[4:5], v74, s78, v[76:77]
	v_and_b32_e32 v87, 15, v78
	v_lshl_add_u64 v[118:119], v[4:5], 0, v[70:71]
	v_mov_b32_e32 v4, s43
	v_mov_b32_e32 v5, s41
	v_subrev_co_u32_e64 v76, s[6:7], 8, v87
	v_mov_b32_e32 v6, s40
	s_nop 0
	v_cndmask_b32_e64 v5, v4, v5, s[6:7]
	v_mov_b32_e32 v4, s42
	v_cndmask_b32_e64 v4, v4, v6, s[6:7]
	v_lshlrev_b32_e32 v70, 5, v135
	v_lshl_add_u64 v[18:19], v[4:5], 0, v[70:71]
	global_load_dwordx4 v[4:7], v[18:19], off offset:272
	global_load_dwordx4 v[80:83], v[18:19], off offset:256
	global_load_dwordx4 v[28:31], v[10:11], off offset:3072
	global_load_dwordx4 v[24:27], v[12:13], off offset:3072
	v_lshl_add_u64 v[10:11], v[14:15], 0, v[8:9]
	v_lshl_add_u64 v[12:13], v[16:17], 0, v[8:9]
	global_load_dwordx4 v[20:23], v[10:11], off offset:3072
	global_load_dwordx4 v[16:19], v[12:13], off offset:3072
	v_lshl_add_u64 v[10:11], v[84:85], 0, v[8:9]
	v_lshl_add_u64 v[8:9], v[118:119], 0, v[8:9]
	global_load_dwordx4 v[12:15], v[10:11], off offset:3072
	s_nop 0
	global_load_dwordx4 v[8:11], v[8:9], off offset:3072
	s_waitcnt vmcnt(17)
	v_lshlrev_b32_e32 v118, 16, v0
	v_and_b32_e32 v119, 0xffff0000, v0
	v_pk_mul_f32 v[84:85], v[118:119], v[118:119]
	v_lshlrev_b32_e32 v154, 16, v1
	v_and_b32_e32 v155, 0xffff0000, v1
	v_pk_mul_f32 v[0:1], v[154:155], v[154:155]
	v_add_f32_e32 v70, v84, v85
	v_lshlrev_b32_e32 v156, 16, v2
	v_and_b32_e32 v157, 0xffff0000, v2
	v_add_f32_e32 v0, v0, v70
	v_pk_mul_f32 v[158:159], v[156:157], v[156:157]
	v_add_f32_e32 v0, v1, v0
	v_lshlrev_b32_e32 v160, 16, v3
	v_and_b32_e32 v161, 0xffff0000, v3
	v_add_f32_e32 v0, v158, v0
	v_pk_mul_f32 v[2:3], v[160:161], v[160:161]
	v_add_f32_e32 v0, v159, v0
	v_add_f32_e32 v0, v2, v0
	v_add_f32_e32 v0, v3, v0
	ds_bpermute_b32 v1, v132, v0
	v_lshlrev_b32_e32 v136, 4, v134
	v_cmp_gt_u32_e64 s[12:13], 4, v135
	v_and_b32_e32 v138, 16, v136
	v_add_u32_e32 v84, s80, v79
	s_waitcnt lgkmcnt(0)
	v_add_f32_e32 v0, v0, v1
	ds_bpermute_b32 v1, v75, v0
	s_waitcnt lgkmcnt(0)
	v_add_f32_e32 v0, v0, v1
	ds_bpermute_b32 v1, v133, v0
	s_waitcnt lgkmcnt(0)
	v_add_f32_e32 v0, v0, v1
	v_fmamk_f32 v0, v0, 0x3c800000, v127
	v_mul_f32_e32 v1, 0x4b800000, v0
	v_cmp_gt_f32_e64 s[14:15], s79, v0
	s_nop 1
	v_cndmask_b32_e64 v0, v0, v1, s[14:15]
	v_rsq_f32_e32 v0, v0
	v_and_b32_e32 v1, 2, v134
	v_cmp_eq_u32_e64 s[10:11], 0, v1
	v_mul_f32_e32 v1, 0x45800000, v0
	v_cndmask_b32_e64 v70, v0, v1, s[14:15]
	v_pk_mul_f32 v[0:1], v[70:71], v[118:119] op_sel_hi:[0,1]
	v_pk_mul_f32 v[2:3], v[70:71], v[154:155] op_sel_hi:[0,1]
	s_waitcnt vmcnt(6)
	v_mov_b32_e32 v168, v80
	v_mov_b32_e32 v169, v81
	v_mov_b32_e32 v170, v82
	v_mov_b32_e32 v171, v83
	v_mov_b32_e32 v172, v4
	v_mov_b32_e32 v173, v5
	v_mov_b32_e32 v174, v6
	v_mov_b32_e32 v175, v7
	v_pk_mul_f32 v[0:1], v[80:81], v[0:1]
	v_pk_mul_f32 v[80:81], v[70:71], v[156:157] op_sel_hi:[0,1]
	v_pk_mul_f32 v[4:5], v[4:5], v[80:81]
	v_pk_mul_f32 v[80:81], v[70:71], v[160:161] op_sel_hi:[0,1]
	v_pk_mul_f32 v[2:3], v[82:83], v[2:3]
	v_pk_mul_f32 v[6:7], v[6:7], v[80:81]
	s_cbranch_vccnz .LBB0_1298
	v_ashrrev_i32_e32 v70, 6, v84
	v_bfe_u32 v77, v134, 7, 6
	v_cndmask_b32_e64 v70, v77, v70, s[12:13]
	v_lshl_or_b32 v80, v70, 5, v138
	v_ashrrev_i32_e32 v81, 31, v80
	v_lshl_add_u64 v[118:119], v[80:81], 2, s[56:57]
	v_mov_b32_e32 v194, 0x200
	v_mov_b32_e32 v195, 0
	v_cndmask_b32_e64 v194, v194, 0, s[12:13]
	v_mov_b32_e32 v192, v118
	v_mov_b32_e32 v193, v119
	global_load_dwordx4 v[80:83], v[118:119], off offset:48
	global_load_dwordx4 v[154:157], v[118:119], off offset:32
	global_load_dwordx4 v[158:161], v[118:119], off offset:16
	global_load_dwordx4 v[162:165], v[118:119], off
	ds_bpermute_b32 v166, v75, v0
	ds_bpermute_b32 v167, v75, v1
	s_waitcnt vmcnt(0)
	v_lshl_add_u64 v[192:193], v[192:193], 0, v[194:195]
	global_load_dwordx4 v[188:191], v[192:193], off offset:48
	global_load_dwordx4 v[184:187], v[192:193], off offset:32
	global_load_dwordx4 v[180:183], v[192:193], off offset:16
	global_load_dwordx4 v[176:179], v[192:193], off
	v_mov_b32_e32 v119, v164
	v_mov_b32_e32 v164, v163
	v_mov_b32_e32 v118, v162
	s_waitcnt lgkmcnt(0)
	v_pk_mul_f32 v[162:163], v[164:165], v[166:167]
	s_nop 0
	v_cndmask_b32_e64 v163, v163, -v163, s[10:11]
	v_cndmask_b32_e64 v162, v162, -v162, s[10:11]
	v_pk_fma_f32 v[0:1], v[0:1], v[118:119], v[162:163]
	ds_bpermute_b32 v118, v75, v2
	ds_bpermute_b32 v119, v75, v3
	v_mov_b32_e32 v163, v160
	v_mov_b32_e32 v160, v159
	v_mov_b32_e32 v162, v158
	v_mov_b32_e32 v159, v156
	s_waitcnt lgkmcnt(0)
	v_pk_mul_f32 v[118:119], v[160:161], v[118:119]
	v_mov_b32_e32 v156, v155
	v_cndmask_b32_e64 v119, v119, -v119, s[10:11]
	v_cndmask_b32_e64 v118, v118, -v118, s[10:11]
	v_pk_fma_f32 v[2:3], v[2:3], v[162:163], v[118:119]
	ds_bpermute_b32 v118, v75, v4
	ds_bpermute_b32 v119, v75, v5
	v_mov_b32_e32 v158, v154
	v_mov_b32_e32 v155, v82
	v_mov_b32_e32 v82, v81
	v_mov_b32_e32 v154, v80
	s_waitcnt lgkmcnt(0)
	v_pk_mul_f32 v[118:119], v[156:157], v[118:119]
	s_nop 0
	v_cndmask_b32_e64 v119, v119, -v119, s[10:11]
	v_cndmask_b32_e64 v118, v118, -v118, s[10:11]
	v_pk_fma_f32 v[4:5], v[4:5], v[158:159], v[118:119]
	ds_bpermute_b32 v118, v75, v6
	ds_bpermute_b32 v119, v75, v7
	s_waitcnt lgkmcnt(0)
	v_pk_mul_f32 v[80:81], v[82:83], v[118:119]
	s_nop 0
	v_cndmask_b32_e64 v81, v81, -v81, s[10:11]
	v_cndmask_b32_e64 v80, v80, -v80, s[10:11]
	v_pk_fma_f32 v[6:7], v[6:7], v[154:155], v[80:81]

.LBB0_1304:
	s_or_b64 exec, exec, s[4:5]
	v_lshlrev_b32_e32 v86, 2, v117
	v_mov_b32_e32 v87, v71
	v_lshl_add_u64 v[0:1], v[118:119], 0, v[86:87]
	v_mov_b32_e32 v4, v172
	v_mov_b32_e32 v5, v173
	v_mov_b32_e32 v6, v174
	v_mov_b32_e32 v7, v175
	s_nop 0
	v_mov_b32_e32 v0, v168
	v_mov_b32_e32 v1, v169
	v_mov_b32_e32 v2, v170
	v_mov_b32_e32 v3, v171
	v_lshlrev_b32_e32 v118, 16, v64
	v_and_b32_e32 v119, 0xffff0000, v64
	v_pk_mul_f32 v[154:155], v[118:119], v[118:119]
	v_lshlrev_b32_e32 v64, 16, v65
	v_and_b32_e32 v65, 0xffff0000, v65
	v_pk_mul_f32 v[156:157], v[64:65], v[64:65]
	v_add_f32_e32 v79, v154, v155
	v_lshlrev_b32_e32 v158, 16, v66
	v_and_b32_e32 v159, 0xffff0000, v66
	v_add_f32_e32 v79, v156, v79
	v_pk_mul_f32 v[160:161], v[158:159], v[158:159]
	v_add_f32_e32 v79, v157, v79
	v_lshlrev_b32_e32 v66, 16, v67
	v_and_b32_e32 v67, 0xffff0000, v67
	v_add_f32_e32 v79, v160, v79
	v_pk_mul_f32 v[162:163], v[66:67], v[66:67]
	v_add_f32_e32 v79, v161, v79
	v_add_f32_e32 v79, v162, v79
	v_add_f32_e32 v79, v163, v79
	ds_bpermute_b32 v87, v132, v79
	v_add_u32_e32 v116, s80, v116
	s_waitcnt lgkmcnt(0)
	v_add_f32_e32 v79, v79, v87
	ds_bpermute_b32 v87, v75, v79
	s_waitcnt lgkmcnt(0)
	v_add_f32_e32 v79, v79, v87
	ds_bpermute_b32 v87, v133, v79
	s_waitcnt lgkmcnt(0)
	v_add_f32_e32 v79, v79, v87
	v_fmamk_f32 v79, v79, 0x3c800000, v127
	v_cmp_gt_f32_e32 vcc, s79, v79
	v_mul_f32_e32 v87, 0x4b800000, v79
	s_nop 0
	v_cndmask_b32_e32 v79, v79, v87, vcc
	v_rsq_f32_e32 v79, v79
	s_nop 0
	v_mul_f32_e32 v87, 0x45800000, v79
	v_cndmask_b32_e32 v154, v79, v87, vcc
	v_pk_mul_f32 v[64:65], v[154:155], v[64:65] op_sel_hi:[0,1]
	v_pk_mul_f32 v[118:119], v[154:155], v[118:119] op_sel_hi:[0,1]
	s_andn2_b64 vcc, exec, s[92:93]
	s_waitcnt vmcnt(0)
	v_pk_mul_f32 v[2:3], v[2:3], v[64:65]
	v_pk_mul_f32 v[64:65], v[154:155], v[158:159] op_sel_hi:[0,1]
	v_pk_mul_f32 v[4:5], v[4:5], v[64:65]
	v_pk_mul_f32 v[64:65], v[154:155], v[66:67] op_sel_hi:[0,1]
	v_pk_mul_f32 v[6:7], v[6:7], v[64:65]
	v_cndmask_b32_e64 v64, 0, 1, s[92:93]
	v_pk_mul_f32 v[0:1], v[0:1], v[118:119]
	v_cmp_ne_u32_e64 s[6:7], 1, v64
	s_cbranch_vccnz .LBB0_1393
	v_ashrrev_i32_e32 v64, 6, v116
	v_bfe_u32 v65, v115, 4, 6
	v_cndmask_b32_e64 v64, v65, v64, s[12:13]
	v_lshl_or_b32 v64, v64, 5, v138
	v_ashrrev_i32_e32 v65, 31, v64
	v_lshl_add_u64 v[118:119], v[64:65], 2, s[56:57]
	s_waitcnt vmcnt(1)
	v_mov_b32_e32 v64, v188
	v_mov_b32_e32 v65, v189
	v_mov_b32_e32 v66, v190
	v_mov_b32_e32 v67, v191
	v_mov_b32_e32 v154, v184
	v_mov_b32_e32 v155, v185
	v_mov_b32_e32 v156, v186
	v_mov_b32_e32 v157, v187
	v_mov_b32_e32 v158, v180
	v_mov_b32_e32 v159, v181
	v_mov_b32_e32 v160, v182
	v_mov_b32_e32 v161, v183
	v_mov_b32_e32 v162, v176
	v_mov_b32_e32 v163, v177
	v_mov_b32_e32 v164, v178
	v_mov_b32_e32 v165, v179
	v_lshl_add_u64 v[192:193], v[192:193], 0, v[194:195]
	global_load_dwordx4 v[188:191], v[192:193], off offset:48
	global_load_dwordx4 v[184:187], v[192:193], off offset:32
	global_load_dwordx4 v[180:183], v[192:193], off offset:16
	global_load_dwordx4 v[176:179], v[192:193], off
	ds_bpermute_b32 v166, v75, v0
	ds_bpermute_b32 v167, v75, v1
	v_mov_b32_e32 v119, v164
	v_mov_b32_e32 v164, v163
	v_mov_b32_e32 v118, v162
	s_waitcnt lgkmcnt(0)
	v_pk_mul_f32 v[162:163], v[164:165], v[166:167]
	s_nop 0
	v_cndmask_b32_e64 v163, v163, -v163, s[10:11]
	v_cndmask_b32_e64 v162, v162, -v162, s[10:11]
	v_pk_fma_f32 v[0:1], v[0:1], v[118:119], v[162:163]
	ds_bpermute_b32 v118, v75, v2
	ds_bpermute_b32 v119, v75, v3
	v_mov_b32_e32 v163, v160
	v_mov_b32_e32 v160, v159
	v_mov_b32_e32 v162, v158
	v_mov_b32_e32 v159, v156
	s_waitcnt lgkmcnt(0)
	v_pk_mul_f32 v[118:119], v[160:161], v[118:119]
	v_mov_b32_e32 v156, v155
	v_cndmask_b32_e64 v119, v119, -v119, s[10:11]
	v_cndmask_b32_e64 v118, v118, -v118, s[10:11]
	v_pk_fma_f32 v[2:3], v[2:3], v[162:163], v[118:119]
	ds_bpermute_b32 v118, v75, v4
	ds_bpermute_b32 v119, v75, v5
	v_mov_b32_e32 v158, v154
	v_mov_b32_e32 v155, v66
	v_mov_b32_e32 v66, v65
	v_mov_b32_e32 v154, v64
	s_waitcnt lgkmcnt(0)
	v_pk_mul_f32 v[118:119], v[156:157], v[118:119]
	s_nop 0
	v_cndmask_b32_e64 v119, v119, -v119, s[10:11]
	v_cndmask_b32_e64 v118, v118, -v118, s[10:11]
	v_pk_fma_f32 v[4:5], v[4:5], v[158:159], v[118:119]
	ds_bpermute_b32 v118, v75, v6
	ds_bpermute_b32 v119, v75, v7
	s_waitcnt lgkmcnt(0)
	v_pk_mul_f32 v[64:65], v[66:67], v[118:119]
	s_nop 0
	v_cndmask_b32_e64 v65, v65, -v65, s[10:11]
	v_cndmask_b32_e64 v64, v64, -v64, s[10:11]
	v_pk_fma_f32 v[6:7], v[6:7], v[154:155], v[64:65]
	v_mov_b64_e32 v[64:65], s[40:41]
	s_and_saveexec_b64 s[4:5], s[96:97]
	s_xor_b64 s[4:5], exec, s[4:5]
	s_cbranch_execnz .LBB0_1394

.LBB0_1308:
	s_or_b64 exec, exec, s[4:5]
	v_mov_b32_e32 v87, v71
	v_lshl_add_u64 v[4:5], v[64:65], 0, v[86:87]
	v_mov_b32_e32 v0, v168
	v_mov_b32_e32 v1, v169
	v_mov_b32_e32 v2, v170
	v_mov_b32_e32 v3, v171
	s_nop 0
	v_mov_b32_e32 v4, v172
	v_mov_b32_e32 v5, v173
	v_mov_b32_e32 v6, v174
	v_mov_b32_e32 v7, v175
	v_lshlrev_b32_e32 v64, 16, v60
	v_and_b32_e32 v65, 0xffff0000, v60
	v_lshlrev_b32_e32 v66, 16, v61
	v_and_b32_e32 v67, 0xffff0000, v61
	v_pk_mul_f32 v[60:61], v[64:65], v[64:65]
	v_pk_mul_f32 v[116:117], v[66:67], v[66:67]
	v_add_f32_e32 v60, v60, v61
	v_lshlrev_b32_e32 v114, 16, v62
	v_and_b32_e32 v115, 0xffff0000, v62
	v_add_f32_e32 v60, v116, v60
	v_pk_mul_f32 v[118:119], v[114:115], v[114:115]
	v_add_f32_e32 v60, v117, v60
	v_lshlrev_b32_e32 v62, 16, v63
	v_and_b32_e32 v63, 0xffff0000, v63
	v_add_f32_e32 v60, v118, v60
	v_pk_mul_f32 v[154:155], v[62:63], v[62:63]
	v_add_f32_e32 v60, v119, v60
	v_add_f32_e32 v60, v154, v60
	v_add_f32_e32 v60, v155, v60
	ds_bpermute_b32 v61, v132, v60
	s_and_b64 vcc, exec, s[6:7]
	s_waitcnt lgkmcnt(0)
	v_add_f32_e32 v60, v60, v61
	ds_bpermute_b32 v61, v75, v60
	s_waitcnt lgkmcnt(0)
	v_add_f32_e32 v60, v60, v61
	ds_bpermute_b32 v61, v133, v60
	s_waitcnt lgkmcnt(0)
	v_add_f32_e32 v60, v60, v61
	v_fmamk_f32 v60, v60, 0x3c800000, v127
	v_mul_f32_e32 v61, 0x4b800000, v60
	v_cmp_gt_f32_e64 s[16:17], s79, v60
	s_nop 1
	v_cndmask_b32_e64 v60, v60, v61, s[16:17]
	v_rsq_f32_e32 v61, v60
	v_add_u32_e32 v60, s80, v152
	v_mul_f32_e32 v79, 0x45800000, v61
	v_cndmask_b32_e64 v116, v61, v79, s[16:17]
	v_pk_mul_f32 v[64:65], v[116:117], v[64:65] op_sel_hi:[0,1]
	v_pk_mul_f32 v[66:67], v[116:117], v[66:67] op_sel_hi:[0,1]
	v_pk_mul_f32 v[114:115], v[116:117], v[114:115] op_sel_hi:[0,1]
	v_pk_mul_f32 v[62:63], v[116:117], v[62:63] op_sel_hi:[0,1]
	v_pk_mul_f32 v[0:1], v[0:1], v[64:65]
	v_pk_mul_f32 v[2:3], v[2:3], v[66:67]
	v_pk_mul_f32 v[4:5], v[4:5], v[114:115]
	v_pk_mul_f32 v[6:7], v[6:7], v[62:63]
	s_cbranch_vccnz .LBB0_1397
	v_ashrrev_i32_e32 v61, 6, v60
	v_bfe_u32 v62, v113, 4, 6
	v_cndmask_b32_e64 v61, v62, v61, s[12:13]
	v_lshl_or_b32 v62, v61, 5, v138
	v_ashrrev_i32_e32 v63, 31, v62
	v_lshl_add_u64 v[66:67], v[62:63], 2, s[56:57]
	s_waitcnt vmcnt(1)
	v_mov_b32_e32 v62, v188
	v_mov_b32_e32 v63, v189
	v_mov_b32_e32 v64, v190
	v_mov_b32_e32 v65, v191
	v_mov_b32_e32 v114, v184
	v_mov_b32_e32 v115, v185
	v_mov_b32_e32 v116, v186
	v_mov_b32_e32 v117, v187
	v_mov_b32_e32 v152, v180
	v_mov_b32_e32 v153, v181
	v_mov_b32_e32 v154, v182
	v_mov_b32_e32 v155, v183
	v_mov_b32_e32 v156, v176
	v_mov_b32_e32 v157, v177
	v_mov_b32_e32 v158, v178
	v_mov_b32_e32 v159, v179
	v_lshl_add_u64 v[192:193], v[192:193], 0, v[194:195]
	global_load_dwordx4 v[188:191], v[192:193], off offset:48
	global_load_dwordx4 v[184:187], v[192:193], off offset:32
	global_load_dwordx4 v[180:183], v[192:193], off offset:16
	global_load_dwordx4 v[176:179], v[192:193], off
	ds_bpermute_b32 v118, v75, v0
	ds_bpermute_b32 v119, v75, v1
	v_mov_b32_e32 v67, v158
	v_mov_b32_e32 v158, v157
	s_waitcnt lgkmcnt(0)
	v_pk_mul_f32 v[118:119], v[158:159], v[118:119]
	v_mov_b32_e32 v66, v156
	v_cndmask_b32_e64 v119, v119, -v119, s[10:11]
	v_cndmask_b32_e64 v118, v118, -v118, s[10:11]
	v_pk_fma_f32 v[0:1], v[0:1], v[66:67], v[118:119]
	ds_bpermute_b32 v66, v75, v2
	ds_bpermute_b32 v67, v75, v3
	v_mov_b32_e32 v119, v154
	v_mov_b32_e32 v154, v153
	v_mov_b32_e32 v118, v152
	s_waitcnt lgkmcnt(0)
	v_pk_mul_f32 v[66:67], v[154:155], v[66:67]
	s_nop 0
	v_cndmask_b32_e64 v67, v67, -v67, s[10:11]
	v_cndmask_b32_e64 v66, v66, -v66, s[10:11]
	v_pk_fma_f32 v[2:3], v[2:3], v[118:119], v[66:67]
	ds_bpermute_b32 v66, v75, v4
	ds_bpermute_b32 v67, v75, v5
	v_mov_b32_e32 v119, v116
	v_mov_b32_e32 v116, v115
	v_mov_b32_e32 v118, v114
	v_mov_b32_e32 v115, v64
	s_waitcnt lgkmcnt(0)
	v_pk_mul_f32 v[66:67], v[116:117], v[66:67]
	v_mov_b32_e32 v64, v63
	v_cndmask_b32_e64 v67, v67, -v67, s[10:11]
	v_cndmask_b32_e64 v66, v66, -v66, s[10:11]
	v_pk_fma_f32 v[4:5], v[4:5], v[118:119], v[66:67]
	ds_bpermute_b32 v66, v75, v6
	ds_bpermute_b32 v67, v75, v7
	v_mov_b32_e32 v114, v62
	s_waitcnt lgkmcnt(0)
	v_pk_mul_f32 v[62:63], v[64:65], v[66:67]
	s_nop 0
	v_cndmask_b32_e64 v63, v63, -v63, s[10:11]
	v_cndmask_b32_e64 v62, v62, -v62, s[10:11]
	v_pk_fma_f32 v[6:7], v[6:7], v[114:115], v[62:63]
	v_mov_b64_e32 v[62:63], s[40:41]
	s_and_saveexec_b64 s[4:5], s[96:97]
	s_xor_b64 s[4:5], exec, s[4:5]
	s_cbranch_execnz .LBB0_1398

.LBB0_1312:
	s_or_b64 exec, exec, s[4:5]
	v_mov_b32_e32 v87, v71
	v_lshl_add_u64 v[4:5], v[62:63], 0, v[86:87]
	v_mov_b32_e32 v0, v168
	v_mov_b32_e32 v1, v169
	v_mov_b32_e32 v2, v170
	v_mov_b32_e32 v3, v171
	s_nop 0
	v_mov_b32_e32 v4, v172
	v_mov_b32_e32 v5, v173
	v_mov_b32_e32 v6, v174
	v_mov_b32_e32 v7, v175
	v_lshlrev_b32_e32 v60, 16, v56
	v_and_b32_e32 v61, 0xffff0000, v56
	v_lshlrev_b32_e32 v62, 16, v57
	v_and_b32_e32 v63, 0xffff0000, v57
	v_pk_mul_f32 v[56:57], v[60:61], v[60:61]
	v_pk_mul_f32 v[66:67], v[62:63], v[62:63]
	v_add_f32_e32 v56, v56, v57
	v_lshlrev_b32_e32 v64, 16, v58
	v_and_b32_e32 v65, 0xffff0000, v58
	v_add_f32_e32 v56, v66, v56
	v_pk_mul_f32 v[112:113], v[64:65], v[64:65]
	v_add_f32_e32 v56, v67, v56
	v_lshlrev_b32_e32 v58, 16, v59
	v_and_b32_e32 v59, 0xffff0000, v59
	v_add_f32_e32 v56, v112, v56
	v_pk_mul_f32 v[114:115], v[58:59], v[58:59]
	v_add_f32_e32 v56, v113, v56
	v_add_f32_e32 v56, v114, v56
	v_add_f32_e32 v56, v115, v56
	ds_bpermute_b32 v57, v132, v56
	s_and_b64 vcc, exec, s[6:7]
	s_waitcnt lgkmcnt(0)
	v_add_f32_e32 v56, v56, v57
	ds_bpermute_b32 v57, v75, v56
	s_waitcnt lgkmcnt(0)
	v_add_f32_e32 v56, v56, v57
	ds_bpermute_b32 v57, v133, v56
	s_waitcnt lgkmcnt(0)
	v_add_f32_e32 v56, v56, v57
	v_fmamk_f32 v56, v56, 0x3c800000, v127
	v_mul_f32_e32 v57, 0x4b800000, v56
	v_cmp_gt_f32_e64 s[16:17], s79, v56
	s_nop 1
	v_cndmask_b32_e64 v56, v56, v57, s[16:17]
	v_rsq_f32_e32 v57, v56
	v_add_u32_e32 v56, s80, v151
	v_mul_f32_e32 v66, 0x45800000, v57
	v_cndmask_b32_e64 v66, v57, v66, s[16:17]
	v_pk_mul_f32 v[60:61], v[66:67], v[60:61] op_sel_hi:[0,1]
	v_pk_mul_f32 v[62:63], v[66:67], v[62:63] op_sel_hi:[0,1]
	v_pk_mul_f32 v[64:65], v[66:67], v[64:65] op_sel_hi:[0,1]
	v_pk_mul_f32 v[58:59], v[66:67], v[58:59] op_sel_hi:[0,1]
	v_pk_mul_f32 v[0:1], v[0:1], v[60:61]
	v_pk_mul_f32 v[2:3], v[2:3], v[62:63]
	v_pk_mul_f32 v[4:5], v[4:5], v[64:65]
	v_pk_mul_f32 v[6:7], v[6:7], v[58:59]
	s_cbranch_vccnz .LBB0_1401
	v_ashrrev_i32_e32 v57, 6, v56
	v_bfe_u32 v58, v111, 4, 6
	v_cndmask_b32_e64 v57, v58, v57, s[12:13]
	v_lshl_or_b32 v58, v57, 5, v138
	v_ashrrev_i32_e32 v59, 31, v58
	v_lshl_add_u64 v[66:67], v[58:59], 2, s[56:57]
	s_waitcnt vmcnt(1)
	v_mov_b32_e32 v58, v188
	v_mov_b32_e32 v59, v189
	v_mov_b32_e32 v60, v190
	v_mov_b32_e32 v61, v191
	v_mov_b32_e32 v62, v184
	v_mov_b32_e32 v63, v185
	v_mov_b32_e32 v64, v186
	v_mov_b32_e32 v65, v187
	v_mov_b32_e32 v112, v180
	v_mov_b32_e32 v113, v181
	v_mov_b32_e32 v114, v182
	v_mov_b32_e32 v115, v183
	v_mov_b32_e32 v116, v176
	v_mov_b32_e32 v117, v177
	v_mov_b32_e32 v118, v178
	v_mov_b32_e32 v119, v179
	v_lshl_add_u64 v[192:193], v[192:193], 0, v[194:195]
	global_load_dwordx4 v[188:191], v[192:193], off offset:48
	global_load_dwordx4 v[184:187], v[192:193], off offset:32
	global_load_dwordx4 v[180:183], v[192:193], off offset:16
	global_load_dwordx4 v[176:179], v[192:193], off
	ds_bpermute_b32 v152, v75, v0
	ds_bpermute_b32 v153, v75, v1
	v_mov_b32_e32 v67, v118
	v_mov_b32_e32 v118, v117
	v_mov_b32_e32 v66, v116
	s_waitcnt lgkmcnt(0)
	v_pk_mul_f32 v[116:117], v[118:119], v[152:153]
	s_nop 0
	v_cndmask_b32_e64 v117, v117, -v117, s[10:11]
	v_cndmask_b32_e64 v116, v116, -v116, s[10:11]
	v_pk_fma_f32 v[0:1], v[0:1], v[66:67], v[116:117]
	ds_bpermute_b32 v66, v75, v2
	ds_bpermute_b32 v67, v75, v3
	v_mov_b32_e32 v117, v114
	v_mov_b32_e32 v114, v113
	v_mov_b32_e32 v116, v112
	v_mov_b32_e32 v113, v64
	s_waitcnt lgkmcnt(0)
	v_pk_mul_f32 v[66:67], v[114:115], v[66:67]
	v_mov_b32_e32 v64, v63
	v_cndmask_b32_e64 v67, v67, -v67, s[10:11]
	v_cndmask_b32_e64 v66, v66, -v66, s[10:11]
	v_pk_fma_f32 v[2:3], v[2:3], v[116:117], v[66:67]
	ds_bpermute_b32 v66, v75, v4
	ds_bpermute_b32 v67, v75, v5
	v_mov_b32_e32 v112, v62
	s_waitcnt lgkmcnt(0)
	v_pk_mul_f32 v[62:63], v[64:65], v[66:67]
	s_nop 0
	v_cndmask_b32_e64 v63, v63, -v63, s[10:11]
	v_cndmask_b32_e64 v62, v62, -v62, s[10:11]
	v_pk_fma_f32 v[4:5], v[4:5], v[112:113], v[62:63]
	ds_bpermute_b32 v62, v75, v6
	ds_bpermute_b32 v63, v75, v7
	v_mov_b32_e32 v65, v60
	v_mov_b32_e32 v60, v59
	v_mov_b32_e32 v64, v58
	s_waitcnt lgkmcnt(0)
	v_pk_mul_f32 v[58:59], v[60:61], v[62:63]
	s_nop 0
	v_cndmask_b32_e64 v59, v59, -v59, s[10:11]
	v_cndmask_b32_e64 v58, v58, -v58, s[10:11]
	v_pk_fma_f32 v[6:7], v[6:7], v[64:65], v[58:59]
	v_mov_b64_e32 v[58:59], s[40:41]
	s_and_saveexec_b64 s[4:5], s[96:97]
	s_xor_b64 s[4:5], exec, s[4:5]
	s_cbranch_execnz .LBB0_1402

.LBB0_1316:
	s_or_b64 exec, exec, s[4:5]
	v_mov_b32_e32 v87, v71
	v_lshl_add_u64 v[4:5], v[58:59], 0, v[86:87]
	v_mov_b32_e32 v0, v168
	v_mov_b32_e32 v1, v169
	v_mov_b32_e32 v2, v170
	v_mov_b32_e32 v3, v171
	s_nop 0
	v_mov_b32_e32 v4, v172
	v_mov_b32_e32 v5, v173
	v_mov_b32_e32 v6, v174
	v_mov_b32_e32 v7, v175
	v_lshlrev_b32_e32 v56, 16, v52
	v_and_b32_e32 v57, 0xffff0000, v52
	v_lshlrev_b32_e32 v58, 16, v53
	v_and_b32_e32 v59, 0xffff0000, v53
	v_pk_mul_f32 v[52:53], v[56:57], v[56:57]
	v_pk_mul_f32 v[62:63], v[58:59], v[58:59]
	v_add_f32_e32 v52, v52, v53
	v_lshlrev_b32_e32 v60, 16, v54
	v_and_b32_e32 v61, 0xffff0000, v54
	v_add_f32_e32 v52, v62, v52
	v_pk_mul_f32 v[64:65], v[60:61], v[60:61]
	v_add_f32_e32 v52, v63, v52
	v_lshlrev_b32_e32 v54, 16, v55
	v_and_b32_e32 v55, 0xffff0000, v55
	v_add_f32_e32 v52, v64, v52
	v_pk_mul_f32 v[66:67], v[54:55], v[54:55]
	v_add_f32_e32 v52, v65, v52
	v_add_f32_e32 v52, v66, v52
	v_add_f32_e32 v52, v67, v52
	ds_bpermute_b32 v53, v132, v52
	s_and_b64 vcc, exec, s[6:7]
	s_waitcnt lgkmcnt(0)
	v_add_f32_e32 v52, v52, v53
	ds_bpermute_b32 v53, v75, v52
	s_waitcnt lgkmcnt(0)
	v_add_f32_e32 v52, v52, v53
	ds_bpermute_b32 v53, v133, v52
	s_waitcnt lgkmcnt(0)
	v_add_f32_e32 v52, v52, v53
	v_fmamk_f32 v52, v52, 0x3c800000, v127
	v_mul_f32_e32 v53, 0x4b800000, v52
	v_cmp_gt_f32_e64 s[16:17], s79, v52
	s_nop 1
	v_cndmask_b32_e64 v52, v52, v53, s[16:17]
	v_rsq_f32_e32 v53, v52
	v_add_u32_e32 v52, s80, v150
	v_mul_f32_e32 v62, 0x45800000, v53
	v_cndmask_b32_e64 v62, v53, v62, s[16:17]
	v_pk_mul_f32 v[56:57], v[62:63], v[56:57] op_sel_hi:[0,1]
	v_pk_mul_f32 v[58:59], v[62:63], v[58:59] op_sel_hi:[0,1]
	v_pk_mul_f32 v[60:61], v[62:63], v[60:61] op_sel_hi:[0,1]
	v_pk_mul_f32 v[54:55], v[62:63], v[54:55] op_sel_hi:[0,1]
	v_pk_mul_f32 v[0:1], v[0:1], v[56:57]
	v_pk_mul_f32 v[2:3], v[2:3], v[58:59]
	v_pk_mul_f32 v[4:5], v[4:5], v[60:61]
	v_pk_mul_f32 v[6:7], v[6:7], v[54:55]
	s_cbranch_vccnz .LBB0_1405
	v_ashrrev_i32_e32 v53, 6, v52
	v_bfe_u32 v54, v109, 4, 6
	v_cndmask_b32_e64 v53, v54, v53, s[12:13]
	v_lshl_or_b32 v54, v53, 5, v138
	v_ashrrev_i32_e32 v55, 31, v54
	v_lshl_add_u64 v[66:67], v[54:55], 2, s[56:57]
	s_waitcnt vmcnt(1)
	v_mov_b32_e32 v54, v188
	v_mov_b32_e32 v55, v189
	v_mov_b32_e32 v56, v190
	v_mov_b32_e32 v57, v191
	v_mov_b32_e32 v58, v184
	v_mov_b32_e32 v59, v185
	v_mov_b32_e32 v60, v186
	v_mov_b32_e32 v61, v187
	v_mov_b32_e32 v62, v180
	v_mov_b32_e32 v63, v181
	v_mov_b32_e32 v64, v182
	v_mov_b32_e32 v65, v183
	v_mov_b32_e32 v110, v176
	v_mov_b32_e32 v111, v177
	v_mov_b32_e32 v112, v178
	v_mov_b32_e32 v113, v179
	v_lshl_add_u64 v[192:193], v[192:193], 0, v[194:195]
	global_load_dwordx4 v[188:191], v[192:193], off offset:48
	global_load_dwordx4 v[184:187], v[192:193], off offset:32
	global_load_dwordx4 v[180:183], v[192:193], off offset:16
	global_load_dwordx4 v[176:179], v[192:193], off
	ds_bpermute_b32 v114, v75, v0
	ds_bpermute_b32 v115, v75, v1
	v_mov_b32_e32 v67, v112
	v_mov_b32_e32 v112, v111
	v_mov_b32_e32 v66, v110
	s_waitcnt lgkmcnt(0)
	v_pk_mul_f32 v[110:111], v[112:113], v[114:115]
	s_nop 0
	v_cndmask_b32_e64 v111, v111, -v111, s[10:11]
	v_cndmask_b32_e64 v110, v110, -v110, s[10:11]
	v_pk_fma_f32 v[0:1], v[0:1], v[66:67], v[110:111]
	ds_bpermute_b32 v66, v75, v2
	ds_bpermute_b32 v67, v75, v3
	v_mov_b32_e32 v111, v64
	v_mov_b32_e32 v64, v63
	v_mov_b32_e32 v110, v62
	s_waitcnt lgkmcnt(0)
	v_pk_mul_f32 v[62:63], v[64:65], v[66:67]
	s_nop 0
	v_cndmask_b32_e64 v63, v63, -v63, s[10:11]
	v_cndmask_b32_e64 v62, v62, -v62, s[10:11]
	v_pk_fma_f32 v[2:3], v[2:3], v[110:111], v[62:63]
	ds_bpermute_b32 v62, v75, v4
	ds_bpermute_b32 v63, v75, v5
	v_mov_b32_e32 v65, v60
	v_mov_b32_e32 v60, v59
	v_mov_b32_e32 v64, v58
	s_waitcnt lgkmcnt(0)
	v_pk_mul_f32 v[58:59], v[60:61], v[62:63]
	s_nop 0
	v_cndmask_b32_e64 v59, v59, -v59, s[10:11]
	v_cndmask_b32_e64 v58, v58, -v58, s[10:11]
	v_pk_fma_f32 v[4:5], v[4:5], v[64:65], v[58:59]
	ds_bpermute_b32 v58, v75, v6
	ds_bpermute_b32 v59, v75, v7
	v_mov_b32_e32 v61, v56
	v_mov_b32_e32 v56, v55
	v_mov_b32_e32 v60, v54
	s_waitcnt lgkmcnt(0)
	v_pk_mul_f32 v[54:55], v[56:57], v[58:59]
	s_nop 0
	v_cndmask_b32_e64 v55, v55, -v55, s[10:11]
	v_cndmask_b32_e64 v54, v54, -v54, s[10:11]
	v_pk_fma_f32 v[6:7], v[6:7], v[60:61], v[54:55]
	v_mov_b64_e32 v[54:55], s[40:41]
	s_and_saveexec_b64 s[4:5], s[96:97]
	s_xor_b64 s[4:5], exec, s[4:5]
	s_cbranch_execnz .LBB0_1406

.LBB0_1320:
	s_or_b64 exec, exec, s[4:5]
	v_mov_b32_e32 v87, v71
	v_lshl_add_u64 v[4:5], v[54:55], 0, v[86:87]
	v_mov_b32_e32 v0, v168
	v_mov_b32_e32 v1, v169
	v_mov_b32_e32 v2, v170
	v_mov_b32_e32 v3, v171
	s_nop 0
	v_mov_b32_e32 v4, v172
	v_mov_b32_e32 v5, v173
	v_mov_b32_e32 v6, v174
	v_mov_b32_e32 v7, v175
	v_lshlrev_b32_e32 v52, 16, v48
	v_and_b32_e32 v53, 0xffff0000, v48
	v_lshlrev_b32_e32 v54, 16, v49
	v_and_b32_e32 v55, 0xffff0000, v49
	v_pk_mul_f32 v[48:49], v[52:53], v[52:53]
	v_pk_mul_f32 v[58:59], v[54:55], v[54:55]
	v_add_f32_e32 v48, v48, v49
	v_lshlrev_b32_e32 v56, 16, v50
	v_and_b32_e32 v57, 0xffff0000, v50
	v_add_f32_e32 v48, v58, v48
	v_pk_mul_f32 v[60:61], v[56:57], v[56:57]
	v_add_f32_e32 v48, v59, v48
	v_lshlrev_b32_e32 v50, 16, v51
	v_and_b32_e32 v51, 0xffff0000, v51
	v_add_f32_e32 v48, v60, v48
	v_pk_mul_f32 v[62:63], v[50:51], v[50:51]
	v_add_f32_e32 v48, v61, v48
	v_add_f32_e32 v48, v62, v48
	v_add_f32_e32 v48, v63, v48
	ds_bpermute_b32 v49, v132, v48
	s_and_b64 vcc, exec, s[6:7]
	s_waitcnt lgkmcnt(0)
	v_add_f32_e32 v48, v48, v49
	ds_bpermute_b32 v49, v75, v48
	s_waitcnt lgkmcnt(0)
	v_add_f32_e32 v48, v48, v49
	ds_bpermute_b32 v49, v133, v48
	s_waitcnt lgkmcnt(0)
	v_add_f32_e32 v48, v48, v49
	v_fmamk_f32 v48, v48, 0x3c800000, v127
	v_mul_f32_e32 v49, 0x4b800000, v48
	v_cmp_gt_f32_e64 s[16:17], s79, v48
	s_nop 1
	v_cndmask_b32_e64 v48, v48, v49, s[16:17]
	v_rsq_f32_e32 v49, v48
	v_add_u32_e32 v48, s80, v149
	v_mul_f32_e32 v58, 0x45800000, v49
	v_cndmask_b32_e64 v58, v49, v58, s[16:17]
	v_pk_mul_f32 v[52:53], v[58:59], v[52:53] op_sel_hi:[0,1]
	v_pk_mul_f32 v[54:55], v[58:59], v[54:55] op_sel_hi:[0,1]
	v_pk_mul_f32 v[56:57], v[58:59], v[56:57] op_sel_hi:[0,1]
	v_pk_mul_f32 v[50:51], v[58:59], v[50:51] op_sel_hi:[0,1]
	v_pk_mul_f32 v[0:1], v[0:1], v[52:53]
	v_pk_mul_f32 v[2:3], v[2:3], v[54:55]
	v_pk_mul_f32 v[4:5], v[4:5], v[56:57]
	v_pk_mul_f32 v[6:7], v[6:7], v[50:51]
	s_cbranch_vccnz .LBB0_1409
	v_ashrrev_i32_e32 v49, 6, v48
	v_bfe_u32 v50, v107, 4, 6
	v_cndmask_b32_e64 v49, v50, v49, s[12:13]
	v_lshl_or_b32 v50, v49, 5, v138
	v_ashrrev_i32_e32 v51, 31, v50
	v_lshl_add_u64 v[62:63], v[50:51], 2, s[56:57]
	s_waitcnt vmcnt(1)
	v_mov_b32_e32 v50, v188
	v_mov_b32_e32 v51, v189
	v_mov_b32_e32 v52, v190
	v_mov_b32_e32 v53, v191
	v_mov_b32_e32 v54, v184
	v_mov_b32_e32 v55, v185
	v_mov_b32_e32 v56, v186
	v_mov_b32_e32 v57, v187
	v_mov_b32_e32 v58, v180
	v_mov_b32_e32 v59, v181
	v_mov_b32_e32 v60, v182
	v_mov_b32_e32 v61, v183
	v_mov_b32_e32 v62, v176
	v_mov_b32_e32 v63, v177
	v_mov_b32_e32 v64, v178
	v_mov_b32_e32 v65, v179
	v_lshl_add_u64 v[192:193], v[192:193], 0, v[194:195]
	global_load_dwordx4 v[188:191], v[192:193], off offset:48
	global_load_dwordx4 v[184:187], v[192:193], off offset:32
	global_load_dwordx4 v[180:183], v[192:193], off offset:16
	global_load_dwordx4 v[176:179], v[192:193], off
	ds_bpermute_b32 v66, v75, v0
	ds_bpermute_b32 v67, v75, v1
	v_mov_b32_e32 v109, v64
	v_mov_b32_e32 v64, v63
	v_mov_b32_e32 v108, v62
	s_waitcnt lgkmcnt(0)
	v_pk_mul_f32 v[62:63], v[64:65], v[66:67]
	v_mov_b32_e32 v65, v60
	v_cndmask_b32_e64 v63, v63, -v63, s[10:11]
	v_cndmask_b32_e64 v62, v62, -v62, s[10:11]
	v_pk_fma_f32 v[0:1], v[0:1], v[108:109], v[62:63]
	ds_bpermute_b32 v62, v75, v2
	ds_bpermute_b32 v63, v75, v3
	v_mov_b32_e32 v60, v59
	v_mov_b32_e32 v64, v58
	s_waitcnt lgkmcnt(0)
	v_pk_mul_f32 v[58:59], v[60:61], v[62:63]
	s_nop 0
	v_cndmask_b32_e64 v59, v59, -v59, s[10:11]
	v_cndmask_b32_e64 v58, v58, -v58, s[10:11]
	v_pk_fma_f32 v[2:3], v[2:3], v[64:65], v[58:59]
	ds_bpermute_b32 v58, v75, v4
	ds_bpermute_b32 v59, v75, v5
	v_mov_b32_e32 v61, v56
	v_mov_b32_e32 v56, v55
	v_mov_b32_e32 v60, v54
	s_waitcnt lgkmcnt(0)
	v_pk_mul_f32 v[54:55], v[56:57], v[58:59]
	s_nop 0
	v_cndmask_b32_e64 v55, v55, -v55, s[10:11]
	v_cndmask_b32_e64 v54, v54, -v54, s[10:11]
	v_pk_fma_f32 v[4:5], v[4:5], v[60:61], v[54:55]
	ds_bpermute_b32 v54, v75, v6
	ds_bpermute_b32 v55, v75, v7
	v_mov_b32_e32 v57, v52
	v_mov_b32_e32 v52, v51
	v_mov_b32_e32 v56, v50
	s_waitcnt lgkmcnt(0)
	v_pk_mul_f32 v[50:51], v[52:53], v[54:55]
	s_nop 0
	v_cndmask_b32_e64 v51, v51, -v51, s[10:11]
	v_cndmask_b32_e64 v50, v50, -v50, s[10:11]
	v_pk_fma_f32 v[6:7], v[6:7], v[56:57], v[50:51]
	v_mov_b64_e32 v[50:51], s[40:41]
	s_and_saveexec_b64 s[4:5], s[96:97]
	s_xor_b64 s[4:5], exec, s[4:5]
	s_cbranch_execnz .LBB0_1410

.LBB0_1324:
	s_or_b64 exec, exec, s[4:5]
	v_mov_b32_e32 v87, v71
	v_lshl_add_u64 v[4:5], v[50:51], 0, v[86:87]
	v_mov_b32_e32 v0, v168
	v_mov_b32_e32 v1, v169
	v_mov_b32_e32 v2, v170
	v_mov_b32_e32 v3, v171
	s_nop 0
	v_mov_b32_e32 v4, v172
	v_mov_b32_e32 v5, v173
	v_mov_b32_e32 v6, v174
	v_mov_b32_e32 v7, v175
	v_lshlrev_b32_e32 v48, 16, v44
	v_and_b32_e32 v49, 0xffff0000, v44
	v_lshlrev_b32_e32 v50, 16, v45
	v_and_b32_e32 v51, 0xffff0000, v45
	v_pk_mul_f32 v[44:45], v[48:49], v[48:49]
	v_pk_mul_f32 v[54:55], v[50:51], v[50:51]
	v_add_f32_e32 v44, v44, v45
	v_lshlrev_b32_e32 v52, 16, v46
	v_and_b32_e32 v53, 0xffff0000, v46
	v_add_f32_e32 v44, v54, v44
	v_pk_mul_f32 v[56:57], v[52:53], v[52:53]
	v_add_f32_e32 v44, v55, v44
	v_lshlrev_b32_e32 v46, 16, v47
	v_and_b32_e32 v47, 0xffff0000, v47
	v_add_f32_e32 v44, v56, v44
	v_pk_mul_f32 v[58:59], v[46:47], v[46:47]
	v_add_f32_e32 v44, v57, v44
	v_add_f32_e32 v44, v58, v44
	v_add_f32_e32 v44, v59, v44
	ds_bpermute_b32 v45, v132, v44
	s_and_b64 vcc, exec, s[6:7]
	s_waitcnt lgkmcnt(0)
	v_add_f32_e32 v44, v44, v45
	ds_bpermute_b32 v45, v75, v44
	s_waitcnt lgkmcnt(0)
	v_add_f32_e32 v44, v44, v45
	ds_bpermute_b32 v45, v133, v44
	s_waitcnt lgkmcnt(0)
	v_add_f32_e32 v44, v44, v45
	v_fmamk_f32 v44, v44, 0x3c800000, v127
	v_mul_f32_e32 v45, 0x4b800000, v44
	v_cmp_gt_f32_e64 s[16:17], s79, v44
	s_nop 1
	v_cndmask_b32_e64 v44, v44, v45, s[16:17]
	v_rsq_f32_e32 v45, v44
	v_add_u32_e32 v44, s80, v148
	v_mul_f32_e32 v54, 0x45800000, v45
	v_cndmask_b32_e64 v54, v45, v54, s[16:17]
	v_pk_mul_f32 v[48:49], v[54:55], v[48:49] op_sel_hi:[0,1]
	v_pk_mul_f32 v[50:51], v[54:55], v[50:51] op_sel_hi:[0,1]
	v_pk_mul_f32 v[52:53], v[54:55], v[52:53] op_sel_hi:[0,1]
	v_pk_mul_f32 v[46:47], v[54:55], v[46:47] op_sel_hi:[0,1]
	v_pk_mul_f32 v[0:1], v[0:1], v[48:49]
	v_pk_mul_f32 v[2:3], v[2:3], v[50:51]
	v_pk_mul_f32 v[4:5], v[4:5], v[52:53]
	v_pk_mul_f32 v[6:7], v[6:7], v[46:47]
	s_cbranch_vccnz .LBB0_1413
	v_ashrrev_i32_e32 v45, 6, v44
	v_bfe_u32 v46, v105, 4, 6
	v_cndmask_b32_e64 v45, v46, v45, s[12:13]
	v_lshl_or_b32 v46, v45, 5, v138
	v_ashrrev_i32_e32 v47, 31, v46
	v_lshl_add_u64 v[58:59], v[46:47], 2, s[56:57]
	s_waitcnt vmcnt(1)
	v_mov_b32_e32 v46, v188
	v_mov_b32_e32 v47, v189
	v_mov_b32_e32 v48, v190
	v_mov_b32_e32 v49, v191
	v_mov_b32_e32 v50, v184
	v_mov_b32_e32 v51, v185
	v_mov_b32_e32 v52, v186
	v_mov_b32_e32 v53, v187
	v_mov_b32_e32 v54, v180
	v_mov_b32_e32 v55, v181
	v_mov_b32_e32 v56, v182
	v_mov_b32_e32 v57, v183
	v_mov_b32_e32 v58, v176
	v_mov_b32_e32 v59, v177
	v_mov_b32_e32 v60, v178
	v_mov_b32_e32 v61, v179
	v_lshl_add_u64 v[192:193], v[192:193], 0, v[194:195]
	global_load_dwordx4 v[188:191], v[192:193], off offset:48
	global_load_dwordx4 v[184:187], v[192:193], off offset:32
	global_load_dwordx4 v[180:183], v[192:193], off offset:16
	global_load_dwordx4 v[176:179], v[192:193], off
	ds_bpermute_b32 v62, v75, v0
	ds_bpermute_b32 v63, v75, v1
	v_mov_b32_e32 v65, v60
	v_mov_b32_e32 v60, v59
	v_mov_b32_e32 v64, v58
	s_waitcnt lgkmcnt(0)
	v_pk_mul_f32 v[58:59], v[60:61], v[62:63]
	v_mov_b32_e32 v61, v56
	v_cndmask_b32_e64 v59, v59, -v59, s[10:11]
	v_cndmask_b32_e64 v58, v58, -v58, s[10:11]
	v_pk_fma_f32 v[0:1], v[0:1], v[64:65], v[58:59]
	ds_bpermute_b32 v58, v75, v2
	ds_bpermute_b32 v59, v75, v3
	v_mov_b32_e32 v56, v55
	v_mov_b32_e32 v60, v54
	s_waitcnt lgkmcnt(0)
	v_pk_mul_f32 v[54:55], v[56:57], v[58:59]
	s_nop 0
	v_cndmask_b32_e64 v55, v55, -v55, s[10:11]
	v_cndmask_b32_e64 v54, v54, -v54, s[10:11]
	v_pk_fma_f32 v[2:3], v[2:3], v[60:61], v[54:55]
	ds_bpermute_b32 v54, v75, v4
	ds_bpermute_b32 v55, v75, v5
	v_mov_b32_e32 v57, v52
	v_mov_b32_e32 v52, v51
	v_mov_b32_e32 v56, v50
	s_waitcnt lgkmcnt(0)
	v_pk_mul_f32 v[50:51], v[52:53], v[54:55]
	s_nop 0
	v_cndmask_b32_e64 v51, v51, -v51, s[10:11]
	v_cndmask_b32_e64 v50, v50, -v50, s[10:11]
	v_pk_fma_f32 v[4:5], v[4:5], v[56:57], v[50:51]
	ds_bpermute_b32 v50, v75, v6
	ds_bpermute_b32 v51, v75, v7
	v_mov_b32_e32 v53, v48
	v_mov_b32_e32 v48, v47
	v_mov_b32_e32 v52, v46
	s_waitcnt lgkmcnt(0)
	v_pk_mul_f32 v[46:47], v[48:49], v[50:51]
	s_nop 0
	v_cndmask_b32_e64 v47, v47, -v47, s[10:11]
	v_cndmask_b32_e64 v46, v46, -v46, s[10:11]
	v_pk_fma_f32 v[6:7], v[6:7], v[52:53], v[46:47]
	v_mov_b64_e32 v[46:47], s[40:41]
	s_and_saveexec_b64 s[4:5], s[96:97]
	s_xor_b64 s[4:5], exec, s[4:5]
	s_cbranch_execnz .LBB0_1414

.LBB0_1328:
	s_or_b64 exec, exec, s[4:5]
	v_mov_b32_e32 v87, v71
	v_lshl_add_u64 v[4:5], v[46:47], 0, v[86:87]
	v_mov_b32_e32 v0, v168
	v_mov_b32_e32 v1, v169
	v_mov_b32_e32 v2, v170
	v_mov_b32_e32 v3, v171
	s_nop 0
	v_mov_b32_e32 v4, v172
	v_mov_b32_e32 v5, v173
	v_mov_b32_e32 v6, v174
	v_mov_b32_e32 v7, v175
	v_lshlrev_b32_e32 v44, 16, v40
	v_and_b32_e32 v45, 0xffff0000, v40
	v_lshlrev_b32_e32 v46, 16, v41
	v_and_b32_e32 v47, 0xffff0000, v41
	v_pk_mul_f32 v[40:41], v[44:45], v[44:45]
	v_pk_mul_f32 v[50:51], v[46:47], v[46:47]
	v_add_f32_e32 v40, v40, v41
	v_lshlrev_b32_e32 v48, 16, v42
	v_and_b32_e32 v49, 0xffff0000, v42
	v_add_f32_e32 v40, v50, v40
	v_pk_mul_f32 v[52:53], v[48:49], v[48:49]
	v_add_f32_e32 v40, v51, v40
	v_lshlrev_b32_e32 v42, 16, v43
	v_and_b32_e32 v43, 0xffff0000, v43
	v_add_f32_e32 v40, v52, v40
	v_pk_mul_f32 v[54:55], v[42:43], v[42:43]
	v_add_f32_e32 v40, v53, v40
	v_add_f32_e32 v40, v54, v40
	v_add_f32_e32 v40, v55, v40
	ds_bpermute_b32 v41, v132, v40
	s_and_b64 vcc, exec, s[6:7]
	s_waitcnt lgkmcnt(0)
	v_add_f32_e32 v40, v40, v41
	ds_bpermute_b32 v41, v75, v40
	s_waitcnt lgkmcnt(0)
	v_add_f32_e32 v40, v40, v41
	ds_bpermute_b32 v41, v133, v40
	s_waitcnt lgkmcnt(0)
	v_add_f32_e32 v40, v40, v41
	v_fmamk_f32 v40, v40, 0x3c800000, v127
	v_mul_f32_e32 v41, 0x4b800000, v40
	v_cmp_gt_f32_e64 s[16:17], s79, v40
	s_nop 1
	v_cndmask_b32_e64 v40, v40, v41, s[16:17]
	v_rsq_f32_e32 v41, v40
	v_add_u32_e32 v40, s80, v147
	v_mul_f32_e32 v50, 0x45800000, v41
	v_cndmask_b32_e64 v50, v41, v50, s[16:17]
	v_pk_mul_f32 v[44:45], v[50:51], v[44:45] op_sel_hi:[0,1]
	v_pk_mul_f32 v[46:47], v[50:51], v[46:47] op_sel_hi:[0,1]
	v_pk_mul_f32 v[48:49], v[50:51], v[48:49] op_sel_hi:[0,1]
	v_pk_mul_f32 v[42:43], v[50:51], v[42:43] op_sel_hi:[0,1]
	v_pk_mul_f32 v[0:1], v[0:1], v[44:45]
	v_pk_mul_f32 v[2:3], v[2:3], v[46:47]
	v_pk_mul_f32 v[4:5], v[4:5], v[48:49]
	v_pk_mul_f32 v[6:7], v[6:7], v[42:43]
	s_cbranch_vccnz .LBB0_1417
	v_ashrrev_i32_e32 v41, 6, v40
	v_bfe_u32 v42, v103, 4, 6
	v_cndmask_b32_e64 v41, v42, v41, s[12:13]
	v_lshl_or_b32 v42, v41, 5, v138
	v_ashrrev_i32_e32 v43, 31, v42
	v_lshl_add_u64 v[54:55], v[42:43], 2, s[56:57]
	s_waitcnt vmcnt(1)
	v_mov_b32_e32 v42, v188
	v_mov_b32_e32 v43, v189
	v_mov_b32_e32 v44, v190
	v_mov_b32_e32 v45, v191
	v_mov_b32_e32 v46, v184
	v_mov_b32_e32 v47, v185
	v_mov_b32_e32 v48, v186
	v_mov_b32_e32 v49, v187
	v_mov_b32_e32 v50, v180
	v_mov_b32_e32 v51, v181
	v_mov_b32_e32 v52, v182
	v_mov_b32_e32 v53, v183
	v_mov_b32_e32 v54, v176
	v_mov_b32_e32 v55, v177
	v_mov_b32_e32 v56, v178
	v_mov_b32_e32 v57, v179
	v_lshl_add_u64 v[192:193], v[192:193], 0, v[194:195]
	global_load_dwordx4 v[188:191], v[192:193], off offset:48
	global_load_dwordx4 v[184:187], v[192:193], off offset:32
	global_load_dwordx4 v[180:183], v[192:193], off offset:16
	global_load_dwordx4 v[176:179], v[192:193], off
	ds_bpermute_b32 v58, v75, v0
	ds_bpermute_b32 v59, v75, v1
	v_mov_b32_e32 v61, v56
	v_mov_b32_e32 v56, v55
	v_mov_b32_e32 v60, v54
	s_waitcnt lgkmcnt(0)
	v_pk_mul_f32 v[54:55], v[56:57], v[58:59]
	v_mov_b32_e32 v57, v52
	v_cndmask_b32_e64 v55, v55, -v55, s[10:11]
	v_cndmask_b32_e64 v54, v54, -v54, s[10:11]
	v_pk_fma_f32 v[0:1], v[0:1], v[60:61], v[54:55]
	ds_bpermute_b32 v54, v75, v2
	ds_bpermute_b32 v55, v75, v3
	v_mov_b32_e32 v52, v51
	v_mov_b32_e32 v56, v50
	s_waitcnt lgkmcnt(0)
	v_pk_mul_f32 v[50:51], v[52:53], v[54:55]
	s_nop 0
	v_cndmask_b32_e64 v51, v51, -v51, s[10:11]
	v_cndmask_b32_e64 v50, v50, -v50, s[10:11]
	v_pk_fma_f32 v[2:3], v[2:3], v[56:57], v[50:51]
	ds_bpermute_b32 v50, v75, v4
	ds_bpermute_b32 v51, v75, v5
	v_mov_b32_e32 v53, v48
	v_mov_b32_e32 v48, v47
	v_mov_b32_e32 v52, v46
	s_waitcnt lgkmcnt(0)
	v_pk_mul_f32 v[46:47], v[48:49], v[50:51]
	s_nop 0
	v_cndmask_b32_e64 v47, v47, -v47, s[10:11]
	v_cndmask_b32_e64 v46, v46, -v46, s[10:11]
	v_pk_fma_f32 v[4:5], v[4:5], v[52:53], v[46:47]
	ds_bpermute_b32 v46, v75, v6
	ds_bpermute_b32 v47, v75, v7
	v_mov_b32_e32 v49, v44
	v_mov_b32_e32 v44, v43
	v_mov_b32_e32 v48, v42
	s_waitcnt lgkmcnt(0)
	v_pk_mul_f32 v[42:43], v[44:45], v[46:47]
	s_nop 0
	v_cndmask_b32_e64 v43, v43, -v43, s[10:11]
	v_cndmask_b32_e64 v42, v42, -v42, s[10:11]
	v_pk_fma_f32 v[6:7], v[6:7], v[48:49], v[42:43]
	v_mov_b64_e32 v[42:43], s[40:41]
	s_and_saveexec_b64 s[4:5], s[96:97]
	s_xor_b64 s[4:5], exec, s[4:5]
	s_cbranch_execnz .LBB0_1418

.LBB0_1332:
	s_or_b64 exec, exec, s[4:5]
	v_mov_b32_e32 v87, v71
	v_lshl_add_u64 v[4:5], v[42:43], 0, v[86:87]
	v_mov_b32_e32 v0, v168
	v_mov_b32_e32 v1, v169
	v_mov_b32_e32 v2, v170
	v_mov_b32_e32 v3, v171
	s_nop 0
	v_mov_b32_e32 v4, v172
	v_mov_b32_e32 v5, v173
	v_mov_b32_e32 v6, v174
	v_mov_b32_e32 v7, v175
	v_lshlrev_b32_e32 v40, 16, v36
	v_and_b32_e32 v41, 0xffff0000, v36
	v_lshlrev_b32_e32 v42, 16, v37
	v_and_b32_e32 v43, 0xffff0000, v37
	v_pk_mul_f32 v[36:37], v[40:41], v[40:41]
	v_pk_mul_f32 v[46:47], v[42:43], v[42:43]
	v_add_f32_e32 v36, v36, v37
	v_lshlrev_b32_e32 v44, 16, v38
	v_and_b32_e32 v45, 0xffff0000, v38
	v_add_f32_e32 v36, v46, v36
	v_pk_mul_f32 v[48:49], v[44:45], v[44:45]
	v_add_f32_e32 v36, v47, v36
	v_lshlrev_b32_e32 v38, 16, v39
	v_and_b32_e32 v39, 0xffff0000, v39
	v_add_f32_e32 v36, v48, v36
	v_pk_mul_f32 v[50:51], v[38:39], v[38:39]
	v_add_f32_e32 v36, v49, v36
	v_add_f32_e32 v36, v50, v36
	v_add_f32_e32 v36, v51, v36
	ds_bpermute_b32 v37, v132, v36
	s_and_b64 vcc, exec, s[6:7]
	s_waitcnt lgkmcnt(0)
	v_add_f32_e32 v36, v36, v37
	ds_bpermute_b32 v37, v75, v36
	s_waitcnt lgkmcnt(0)
	v_add_f32_e32 v36, v36, v37
	ds_bpermute_b32 v37, v133, v36
	s_waitcnt lgkmcnt(0)
	v_add_f32_e32 v36, v36, v37
	v_fmamk_f32 v36, v36, 0x3c800000, v127
	v_mul_f32_e32 v37, 0x4b800000, v36
	v_cmp_gt_f32_e64 s[16:17], s79, v36
	s_nop 1
	v_cndmask_b32_e64 v36, v36, v37, s[16:17]
	v_rsq_f32_e32 v37, v36
	v_add_u32_e32 v36, s80, v146
	v_mul_f32_e32 v46, 0x45800000, v37
	v_cndmask_b32_e64 v46, v37, v46, s[16:17]
	v_pk_mul_f32 v[40:41], v[46:47], v[40:41] op_sel_hi:[0,1]
	v_pk_mul_f32 v[42:43], v[46:47], v[42:43] op_sel_hi:[0,1]
	v_pk_mul_f32 v[44:45], v[46:47], v[44:45] op_sel_hi:[0,1]
	v_pk_mul_f32 v[38:39], v[46:47], v[38:39] op_sel_hi:[0,1]
	v_pk_mul_f32 v[0:1], v[0:1], v[40:41]
	v_pk_mul_f32 v[2:3], v[2:3], v[42:43]
	v_pk_mul_f32 v[4:5], v[4:5], v[44:45]
	v_pk_mul_f32 v[6:7], v[6:7], v[38:39]
	s_cbranch_vccnz .LBB0_1421
	v_ashrrev_i32_e32 v37, 6, v36
	v_bfe_u32 v38, v101, 4, 6
	v_cndmask_b32_e64 v37, v38, v37, s[12:13]
	v_lshl_or_b32 v38, v37, 5, v138
	v_ashrrev_i32_e32 v39, 31, v38
	v_lshl_add_u64 v[50:51], v[38:39], 2, s[56:57]
	s_waitcnt vmcnt(1)
	v_mov_b32_e32 v38, v188
	v_mov_b32_e32 v39, v189
	v_mov_b32_e32 v40, v190
	v_mov_b32_e32 v41, v191
	v_mov_b32_e32 v42, v184
	v_mov_b32_e32 v43, v185
	v_mov_b32_e32 v44, v186
	v_mov_b32_e32 v45, v187
	v_mov_b32_e32 v46, v180
	v_mov_b32_e32 v47, v181
	v_mov_b32_e32 v48, v182
	v_mov_b32_e32 v49, v183
	v_mov_b32_e32 v50, v176
	v_mov_b32_e32 v51, v177
	v_mov_b32_e32 v52, v178
	v_mov_b32_e32 v53, v179
	v_lshl_add_u64 v[192:193], v[192:193], 0, v[194:195]
	global_load_dwordx4 v[188:191], v[192:193], off offset:48
	global_load_dwordx4 v[184:187], v[192:193], off offset:32
	global_load_dwordx4 v[180:183], v[192:193], off offset:16
	global_load_dwordx4 v[176:179], v[192:193], off
	ds_bpermute_b32 v54, v75, v0
	ds_bpermute_b32 v55, v75, v1
	v_mov_b32_e32 v57, v52
	v_mov_b32_e32 v52, v51
	v_mov_b32_e32 v56, v50
	s_waitcnt lgkmcnt(0)
	v_pk_mul_f32 v[50:51], v[52:53], v[54:55]
	v_mov_b32_e32 v53, v48
	v_cndmask_b32_e64 v51, v51, -v51, s[10:11]
	v_cndmask_b32_e64 v50, v50, -v50, s[10:11]
	v_pk_fma_f32 v[0:1], v[0:1], v[56:57], v[50:51]
	ds_bpermute_b32 v50, v75, v2
	ds_bpermute_b32 v51, v75, v3
	v_mov_b32_e32 v48, v47
	v_mov_b32_e32 v52, v46
	s_waitcnt lgkmcnt(0)
	v_pk_mul_f32 v[46:47], v[48:49], v[50:51]
	s_nop 0
	v_cndmask_b32_e64 v47, v47, -v47, s[10:11]
	v_cndmask_b32_e64 v46, v46, -v46, s[10:11]
	v_pk_fma_f32 v[2:3], v[2:3], v[52:53], v[46:47]
	ds_bpermute_b32 v46, v75, v4
	ds_bpermute_b32 v47, v75, v5
	v_mov_b32_e32 v49, v44
	v_mov_b32_e32 v44, v43
	v_mov_b32_e32 v48, v42
	s_waitcnt lgkmcnt(0)
	v_pk_mul_f32 v[42:43], v[44:45], v[46:47]
	s_nop 0
	v_cndmask_b32_e64 v43, v43, -v43, s[10:11]
	v_cndmask_b32_e64 v42, v42, -v42, s[10:11]
	v_pk_fma_f32 v[4:5], v[4:5], v[48:49], v[42:43]
	ds_bpermute_b32 v42, v75, v6
	ds_bpermute_b32 v43, v75, v7
	v_mov_b32_e32 v45, v40
	v_mov_b32_e32 v40, v39
	v_mov_b32_e32 v44, v38
	s_waitcnt lgkmcnt(0)
	v_pk_mul_f32 v[38:39], v[40:41], v[42:43]
	s_nop 0
	v_cndmask_b32_e64 v39, v39, -v39, s[10:11]
	v_cndmask_b32_e64 v38, v38, -v38, s[10:11]
	v_pk_fma_f32 v[6:7], v[6:7], v[44:45], v[38:39]
	v_mov_b64_e32 v[38:39], s[40:41]
	s_and_saveexec_b64 s[4:5], s[96:97]
	s_xor_b64 s[4:5], exec, s[4:5]
	s_cbranch_execnz .LBB0_1422

.LBB0_1336:
	s_or_b64 exec, exec, s[4:5]
	v_mov_b32_e32 v87, v71
	v_lshl_add_u64 v[4:5], v[38:39], 0, v[86:87]
	v_mov_b32_e32 v0, v168
	v_mov_b32_e32 v1, v169
	v_mov_b32_e32 v2, v170
	v_mov_b32_e32 v3, v171
	s_nop 0
	v_mov_b32_e32 v4, v172
	v_mov_b32_e32 v5, v173
	v_mov_b32_e32 v6, v174
	v_mov_b32_e32 v7, v175
	v_lshlrev_b32_e32 v36, 16, v32
	v_and_b32_e32 v37, 0xffff0000, v32
	v_lshlrev_b32_e32 v38, 16, v33
	v_and_b32_e32 v39, 0xffff0000, v33
	v_pk_mul_f32 v[32:33], v[36:37], v[36:37]
	v_pk_mul_f32 v[42:43], v[38:39], v[38:39]
	v_add_f32_e32 v32, v32, v33
	v_lshlrev_b32_e32 v40, 16, v34
	v_and_b32_e32 v41, 0xffff0000, v34
	v_add_f32_e32 v32, v42, v32
	v_pk_mul_f32 v[44:45], v[40:41], v[40:41]
	v_add_f32_e32 v32, v43, v32
	v_lshlrev_b32_e32 v34, 16, v35
	v_and_b32_e32 v35, 0xffff0000, v35
	v_add_f32_e32 v32, v44, v32
	v_pk_mul_f32 v[46:47], v[34:35], v[34:35]
	v_add_f32_e32 v32, v45, v32
	v_add_f32_e32 v32, v46, v32
	v_add_f32_e32 v32, v47, v32
	ds_bpermute_b32 v33, v132, v32
	s_and_b64 vcc, exec, s[6:7]
	s_waitcnt lgkmcnt(0)
	v_add_f32_e32 v32, v32, v33
	ds_bpermute_b32 v33, v75, v32
	s_waitcnt lgkmcnt(0)
	v_add_f32_e32 v32, v32, v33
	ds_bpermute_b32 v33, v133, v32
	s_waitcnt lgkmcnt(0)
	v_add_f32_e32 v32, v32, v33
	v_fmamk_f32 v32, v32, 0x3c800000, v127
	v_mul_f32_e32 v33, 0x4b800000, v32
	v_cmp_gt_f32_e64 s[16:17], s79, v32
	s_nop 1
	v_cndmask_b32_e64 v32, v32, v33, s[16:17]
	v_rsq_f32_e32 v33, v32
	v_add_u32_e32 v32, s80, v145
	v_mul_f32_e32 v42, 0x45800000, v33
	v_cndmask_b32_e64 v42, v33, v42, s[16:17]
	v_pk_mul_f32 v[36:37], v[42:43], v[36:37] op_sel_hi:[0,1]
	v_pk_mul_f32 v[38:39], v[42:43], v[38:39] op_sel_hi:[0,1]
	v_pk_mul_f32 v[40:41], v[42:43], v[40:41] op_sel_hi:[0,1]
	v_pk_mul_f32 v[34:35], v[42:43], v[34:35] op_sel_hi:[0,1]
	v_pk_mul_f32 v[0:1], v[0:1], v[36:37]
	v_pk_mul_f32 v[2:3], v[2:3], v[38:39]
	v_pk_mul_f32 v[4:5], v[4:5], v[40:41]
	v_pk_mul_f32 v[6:7], v[6:7], v[34:35]
	s_cbranch_vccnz .LBB0_1425
	v_ashrrev_i32_e32 v33, 6, v32
	v_bfe_u32 v34, v99, 4, 6
	v_cndmask_b32_e64 v33, v34, v33, s[12:13]
	v_lshl_or_b32 v34, v33, 5, v138
	v_ashrrev_i32_e32 v35, 31, v34
	v_lshl_add_u64 v[46:47], v[34:35], 2, s[56:57]
	s_waitcnt vmcnt(1)
	v_mov_b32_e32 v34, v188
	v_mov_b32_e32 v35, v189
	v_mov_b32_e32 v36, v190
	v_mov_b32_e32 v37, v191
	v_mov_b32_e32 v38, v184
	v_mov_b32_e32 v39, v185
	v_mov_b32_e32 v40, v186
	v_mov_b32_e32 v41, v187
	v_mov_b32_e32 v42, v180
	v_mov_b32_e32 v43, v181
	v_mov_b32_e32 v44, v182
	v_mov_b32_e32 v45, v183
	v_mov_b32_e32 v46, v176
	v_mov_b32_e32 v47, v177
	v_mov_b32_e32 v48, v178
	v_mov_b32_e32 v49, v179
	v_lshl_add_u64 v[192:193], v[192:193], 0, v[194:195]
	global_load_dwordx4 v[188:191], v[192:193], off offset:48
	global_load_dwordx4 v[184:187], v[192:193], off offset:32
	global_load_dwordx4 v[180:183], v[192:193], off offset:16
	global_load_dwordx4 v[176:179], v[192:193], off
	ds_bpermute_b32 v50, v75, v0
	ds_bpermute_b32 v51, v75, v1
	v_mov_b32_e32 v53, v48
	v_mov_b32_e32 v48, v47
	v_mov_b32_e32 v52, v46
	s_waitcnt lgkmcnt(0)
	v_pk_mul_f32 v[46:47], v[48:49], v[50:51]
	v_mov_b32_e32 v49, v44
	v_cndmask_b32_e64 v47, v47, -v47, s[10:11]
	v_cndmask_b32_e64 v46, v46, -v46, s[10:11]
	v_pk_fma_f32 v[0:1], v[0:1], v[52:53], v[46:47]
	ds_bpermute_b32 v46, v75, v2
	ds_bpermute_b32 v47, v75, v3
	v_mov_b32_e32 v44, v43
	v_mov_b32_e32 v48, v42
	s_waitcnt lgkmcnt(0)
	v_pk_mul_f32 v[42:43], v[44:45], v[46:47]
	s_nop 0
	v_cndmask_b32_e64 v43, v43, -v43, s[10:11]
	v_cndmask_b32_e64 v42, v42, -v42, s[10:11]
	v_pk_fma_f32 v[2:3], v[2:3], v[48:49], v[42:43]
	ds_bpermute_b32 v42, v75, v4
	ds_bpermute_b32 v43, v75, v5
	v_mov_b32_e32 v45, v40
	v_mov_b32_e32 v40, v39
	v_mov_b32_e32 v44, v38
	s_waitcnt lgkmcnt(0)
	v_pk_mul_f32 v[38:39], v[40:41], v[42:43]
	s_nop 0
	v_cndmask_b32_e64 v39, v39, -v39, s[10:11]
	v_cndmask_b32_e64 v38, v38, -v38, s[10:11]
	v_pk_fma_f32 v[4:5], v[4:5], v[44:45], v[38:39]
	ds_bpermute_b32 v38, v75, v6
	ds_bpermute_b32 v39, v75, v7
	v_mov_b32_e32 v41, v36
	v_mov_b32_e32 v36, v35
	v_mov_b32_e32 v40, v34
	s_waitcnt lgkmcnt(0)
	v_pk_mul_f32 v[34:35], v[36:37], v[38:39]
	s_nop 0
	v_cndmask_b32_e64 v35, v35, -v35, s[10:11]
	v_cndmask_b32_e64 v34, v34, -v34, s[10:11]
	v_pk_fma_f32 v[6:7], v[6:7], v[40:41], v[34:35]
	v_mov_b64_e32 v[34:35], s[40:41]
	s_and_saveexec_b64 s[4:5], s[96:97]
	s_xor_b64 s[4:5], exec, s[4:5]
	s_cbranch_execnz .LBB0_1426

.LBB0_1340:
	s_or_b64 exec, exec, s[4:5]
	v_mov_b32_e32 v87, v71
	v_lshl_add_u64 v[4:5], v[34:35], 0, v[86:87]
	v_mov_b32_e32 v0, v168
	v_mov_b32_e32 v1, v169
	v_mov_b32_e32 v2, v170
	v_mov_b32_e32 v3, v171
	s_nop 0
	v_mov_b32_e32 v4, v172
	v_mov_b32_e32 v5, v173
	v_mov_b32_e32 v6, v174
	v_mov_b32_e32 v7, v175
	v_lshlrev_b32_e32 v32, 16, v28
	v_and_b32_e32 v33, 0xffff0000, v28
	v_lshlrev_b32_e32 v34, 16, v29
	v_and_b32_e32 v35, 0xffff0000, v29
	v_pk_mul_f32 v[28:29], v[32:33], v[32:33]
	v_pk_mul_f32 v[38:39], v[34:35], v[34:35]
	v_add_f32_e32 v28, v28, v29
	v_lshlrev_b32_e32 v36, 16, v30
	v_and_b32_e32 v37, 0xffff0000, v30
	v_add_f32_e32 v28, v38, v28
	v_pk_mul_f32 v[40:41], v[36:37], v[36:37]
	v_add_f32_e32 v28, v39, v28
	v_lshlrev_b32_e32 v30, 16, v31
	v_and_b32_e32 v31, 0xffff0000, v31
	v_add_f32_e32 v28, v40, v28
	v_pk_mul_f32 v[42:43], v[30:31], v[30:31]
	v_add_f32_e32 v28, v41, v28
	v_add_f32_e32 v28, v42, v28
	v_add_f32_e32 v28, v43, v28
	ds_bpermute_b32 v29, v132, v28
	s_and_b64 vcc, exec, s[6:7]
	s_waitcnt lgkmcnt(0)
	v_add_f32_e32 v28, v28, v29
	ds_bpermute_b32 v29, v75, v28
	s_waitcnt lgkmcnt(0)
	v_add_f32_e32 v28, v28, v29
	ds_bpermute_b32 v29, v133, v28
	s_waitcnt lgkmcnt(0)
	v_add_f32_e32 v28, v28, v29
	v_fmamk_f32 v28, v28, 0x3c800000, v127
	v_mul_f32_e32 v29, 0x4b800000, v28
	v_cmp_gt_f32_e64 s[16:17], s79, v28
	s_nop 1
	v_cndmask_b32_e64 v28, v28, v29, s[16:17]
	v_rsq_f32_e32 v29, v28
	v_add_u32_e32 v28, s80, v144
	v_mul_f32_e32 v38, 0x45800000, v29
	v_cndmask_b32_e64 v38, v29, v38, s[16:17]
	v_pk_mul_f32 v[32:33], v[38:39], v[32:33] op_sel_hi:[0,1]
	v_pk_mul_f32 v[34:35], v[38:39], v[34:35] op_sel_hi:[0,1]
	v_pk_mul_f32 v[36:37], v[38:39], v[36:37] op_sel_hi:[0,1]
	v_pk_mul_f32 v[30:31], v[38:39], v[30:31] op_sel_hi:[0,1]
	v_pk_mul_f32 v[0:1], v[0:1], v[32:33]
	v_pk_mul_f32 v[2:3], v[2:3], v[34:35]
	v_pk_mul_f32 v[4:5], v[4:5], v[36:37]
	v_pk_mul_f32 v[6:7], v[6:7], v[30:31]
	s_cbranch_vccnz .LBB0_1429
	v_ashrrev_i32_e32 v29, 6, v28
	v_bfe_u32 v30, v97, 4, 6
	v_cndmask_b32_e64 v29, v30, v29, s[12:13]
	v_lshl_or_b32 v30, v29, 5, v138
	v_ashrrev_i32_e32 v31, 31, v30
	v_lshl_add_u64 v[42:43], v[30:31], 2, s[56:57]
	s_waitcnt vmcnt(1)
	v_mov_b32_e32 v30, v188
	v_mov_b32_e32 v31, v189
	v_mov_b32_e32 v32, v190
	v_mov_b32_e32 v33, v191
	v_mov_b32_e32 v34, v184
	v_mov_b32_e32 v35, v185
	v_mov_b32_e32 v36, v186
	v_mov_b32_e32 v37, v187
	v_mov_b32_e32 v38, v180
	v_mov_b32_e32 v39, v181
	v_mov_b32_e32 v40, v182
	v_mov_b32_e32 v41, v183
	v_mov_b32_e32 v42, v176
	v_mov_b32_e32 v43, v177
	v_mov_b32_e32 v44, v178
	v_mov_b32_e32 v45, v179
	v_lshl_add_u64 v[192:193], v[192:193], 0, v[194:195]
	global_load_dwordx4 v[188:191], v[192:193], off offset:48
	global_load_dwordx4 v[184:187], v[192:193], off offset:32
	global_load_dwordx4 v[180:183], v[192:193], off offset:16
	global_load_dwordx4 v[176:179], v[192:193], off
	ds_bpermute_b32 v46, v75, v0
	ds_bpermute_b32 v47, v75, v1
	v_mov_b32_e32 v49, v44
	v_mov_b32_e32 v44, v43
	v_mov_b32_e32 v48, v42
	s_waitcnt lgkmcnt(0)
	v_pk_mul_f32 v[42:43], v[44:45], v[46:47]
	v_mov_b32_e32 v45, v40
	v_cndmask_b32_e64 v43, v43, -v43, s[10:11]
	v_cndmask_b32_e64 v42, v42, -v42, s[10:11]
	v_pk_fma_f32 v[0:1], v[0:1], v[48:49], v[42:43]
	ds_bpermute_b32 v42, v75, v2
	ds_bpermute_b32 v43, v75, v3
	v_mov_b32_e32 v40, v39
	v_mov_b32_e32 v44, v38
	s_waitcnt lgkmcnt(0)
	v_pk_mul_f32 v[38:39], v[40:41], v[42:43]
	s_nop 0
	v_cndmask_b32_e64 v39, v39, -v39, s[10:11]
	v_cndmask_b32_e64 v38, v38, -v38, s[10:11]
	v_pk_fma_f32 v[2:3], v[2:3], v[44:45], v[38:39]
	ds_bpermute_b32 v38, v75, v4
	ds_bpermute_b32 v39, v75, v5
	v_mov_b32_e32 v41, v36
	v_mov_b32_e32 v36, v35
	v_mov_b32_e32 v40, v34
	s_waitcnt lgkmcnt(0)
	v_pk_mul_f32 v[34:35], v[36:37], v[38:39]
	s_nop 0
	v_cndmask_b32_e64 v35, v35, -v35, s[10:11]
	v_cndmask_b32_e64 v34, v34, -v34, s[10:11]
	v_pk_fma_f32 v[4:5], v[4:5], v[40:41], v[34:35]
	ds_bpermute_b32 v34, v75, v6
	ds_bpermute_b32 v35, v75, v7
	v_mov_b32_e32 v37, v32
	v_mov_b32_e32 v32, v31
	v_mov_b32_e32 v36, v30
	s_waitcnt lgkmcnt(0)
	v_pk_mul_f32 v[30:31], v[32:33], v[34:35]
	s_nop 0
	v_cndmask_b32_e64 v31, v31, -v31, s[10:11]
	v_cndmask_b32_e64 v30, v30, -v30, s[10:11]
	v_pk_fma_f32 v[6:7], v[6:7], v[36:37], v[30:31]
	v_mov_b64_e32 v[30:31], s[40:41]
	s_and_saveexec_b64 s[4:5], s[96:97]
	s_xor_b64 s[4:5], exec, s[4:5]
	s_cbranch_execnz .LBB0_1430

.LBB0_1344:
	s_or_b64 exec, exec, s[4:5]
	v_mov_b32_e32 v87, v71
	v_lshl_add_u64 v[4:5], v[30:31], 0, v[86:87]
	v_mov_b32_e32 v0, v168
	v_mov_b32_e32 v1, v169
	v_mov_b32_e32 v2, v170
	v_mov_b32_e32 v3, v171
	s_nop 0
	v_mov_b32_e32 v4, v172
	v_mov_b32_e32 v5, v173
	v_mov_b32_e32 v6, v174
	v_mov_b32_e32 v7, v175
	v_lshlrev_b32_e32 v28, 16, v24
	v_and_b32_e32 v29, 0xffff0000, v24
	v_lshlrev_b32_e32 v30, 16, v25
	v_and_b32_e32 v31, 0xffff0000, v25
	v_pk_mul_f32 v[24:25], v[28:29], v[28:29]
	v_pk_mul_f32 v[34:35], v[30:31], v[30:31]
	v_add_f32_e32 v24, v24, v25
	v_lshlrev_b32_e32 v32, 16, v26
	v_and_b32_e32 v33, 0xffff0000, v26
	v_add_f32_e32 v24, v34, v24
	v_pk_mul_f32 v[36:37], v[32:33], v[32:33]
	v_add_f32_e32 v24, v35, v24
	v_lshlrev_b32_e32 v26, 16, v27
	v_and_b32_e32 v27, 0xffff0000, v27
	v_add_f32_e32 v24, v36, v24
	v_pk_mul_f32 v[38:39], v[26:27], v[26:27]
	v_add_f32_e32 v24, v37, v24
	v_add_f32_e32 v24, v38, v24
	v_add_f32_e32 v24, v39, v24
	ds_bpermute_b32 v25, v132, v24
	s_and_b64 vcc, exec, s[6:7]
	s_waitcnt lgkmcnt(0)
	v_add_f32_e32 v24, v24, v25
	ds_bpermute_b32 v25, v75, v24
	s_waitcnt lgkmcnt(0)
	v_add_f32_e32 v24, v24, v25
	ds_bpermute_b32 v25, v133, v24
	s_waitcnt lgkmcnt(0)
	v_add_f32_e32 v24, v24, v25
	v_fmamk_f32 v24, v24, 0x3c800000, v127
	v_mul_f32_e32 v25, 0x4b800000, v24
	v_cmp_gt_f32_e64 s[16:17], s79, v24
	s_nop 1
	v_cndmask_b32_e64 v24, v24, v25, s[16:17]
	v_rsq_f32_e32 v25, v24
	v_add_u32_e32 v24, s80, v143
	v_mul_f32_e32 v34, 0x45800000, v25
	v_cndmask_b32_e64 v34, v25, v34, s[16:17]
	v_pk_mul_f32 v[28:29], v[34:35], v[28:29] op_sel_hi:[0,1]
	v_pk_mul_f32 v[30:31], v[34:35], v[30:31] op_sel_hi:[0,1]
	v_pk_mul_f32 v[32:33], v[34:35], v[32:33] op_sel_hi:[0,1]
	v_pk_mul_f32 v[26:27], v[34:35], v[26:27] op_sel_hi:[0,1]
	v_pk_mul_f32 v[0:1], v[0:1], v[28:29]
	v_pk_mul_f32 v[2:3], v[2:3], v[30:31]
	v_pk_mul_f32 v[4:5], v[4:5], v[32:33]
	v_pk_mul_f32 v[6:7], v[6:7], v[26:27]
	s_cbranch_vccnz .LBB0_1433
	v_ashrrev_i32_e32 v25, 6, v24
	v_bfe_u32 v26, v95, 4, 6
	v_cndmask_b32_e64 v25, v26, v25, s[12:13]
	v_lshl_or_b32 v26, v25, 5, v138
	v_ashrrev_i32_e32 v27, 31, v26
	v_lshl_add_u64 v[38:39], v[26:27], 2, s[56:57]
	s_waitcnt vmcnt(1)
	v_mov_b32_e32 v26, v188
	v_mov_b32_e32 v27, v189
	v_mov_b32_e32 v28, v190
	v_mov_b32_e32 v29, v191
	v_mov_b32_e32 v30, v184
	v_mov_b32_e32 v31, v185
	v_mov_b32_e32 v32, v186
	v_mov_b32_e32 v33, v187
	v_mov_b32_e32 v34, v180
	v_mov_b32_e32 v35, v181
	v_mov_b32_e32 v36, v182
	v_mov_b32_e32 v37, v183
	v_mov_b32_e32 v38, v176
	v_mov_b32_e32 v39, v177
	v_mov_b32_e32 v40, v178
	v_mov_b32_e32 v41, v179
	v_lshl_add_u64 v[192:193], v[192:193], 0, v[194:195]
	global_load_dwordx4 v[188:191], v[192:193], off offset:48
	global_load_dwordx4 v[184:187], v[192:193], off offset:32
	global_load_dwordx4 v[180:183], v[192:193], off offset:16
	global_load_dwordx4 v[176:179], v[192:193], off
	ds_bpermute_b32 v42, v75, v0
	ds_bpermute_b32 v43, v75, v1
	v_mov_b32_e32 v45, v40
	v_mov_b32_e32 v40, v39
	v_mov_b32_e32 v44, v38
	s_waitcnt lgkmcnt(0)
	v_pk_mul_f32 v[38:39], v[40:41], v[42:43]
	v_mov_b32_e32 v41, v36
	v_cndmask_b32_e64 v39, v39, -v39, s[10:11]
	v_cndmask_b32_e64 v38, v38, -v38, s[10:11]
	v_pk_fma_f32 v[0:1], v[0:1], v[44:45], v[38:39]
	ds_bpermute_b32 v38, v75, v2
	ds_bpermute_b32 v39, v75, v3
	v_mov_b32_e32 v36, v35
	v_mov_b32_e32 v40, v34
	s_waitcnt lgkmcnt(0)
	v_pk_mul_f32 v[34:35], v[36:37], v[38:39]
	s_nop 0
	v_cndmask_b32_e64 v35, v35, -v35, s[10:11]
	v_cndmask_b32_e64 v34, v34, -v34, s[10:11]
	v_pk_fma_f32 v[2:3], v[2:3], v[40:41], v[34:35]
	ds_bpermute_b32 v34, v75, v4
	ds_bpermute_b32 v35, v75, v5
	v_mov_b32_e32 v37, v32
	v_mov_b32_e32 v32, v31
	v_mov_b32_e32 v36, v30
	s_waitcnt lgkmcnt(0)
	v_pk_mul_f32 v[30:31], v[32:33], v[34:35]
	s_nop 0
	v_cndmask_b32_e64 v31, v31, -v31, s[10:11]
	v_cndmask_b32_e64 v30, v30, -v30, s[10:11]
	v_pk_fma_f32 v[4:5], v[4:5], v[36:37], v[30:31]
	ds_bpermute_b32 v30, v75, v6
	ds_bpermute_b32 v31, v75, v7
	v_mov_b32_e32 v33, v28
	v_mov_b32_e32 v28, v27
	v_mov_b32_e32 v32, v26
	s_waitcnt lgkmcnt(0)
	v_pk_mul_f32 v[26:27], v[28:29], v[30:31]
	s_nop 0
	v_cndmask_b32_e64 v27, v27, -v27, s[10:11]
	v_cndmask_b32_e64 v26, v26, -v26, s[10:11]
	v_pk_fma_f32 v[6:7], v[6:7], v[32:33], v[26:27]
	v_mov_b64_e32 v[26:27], s[40:41]
	s_and_saveexec_b64 s[4:5], s[96:97]
	s_xor_b64 s[4:5], exec, s[4:5]
	s_cbranch_execnz .LBB0_1434

.LBB0_1348:
	s_or_b64 exec, exec, s[4:5]
	v_mov_b32_e32 v87, v71
	v_lshl_add_u64 v[4:5], v[26:27], 0, v[86:87]
	v_mov_b32_e32 v0, v168
	v_mov_b32_e32 v1, v169
	v_mov_b32_e32 v2, v170
	v_mov_b32_e32 v3, v171
	s_nop 0
	v_mov_b32_e32 v4, v172
	v_mov_b32_e32 v5, v173
	v_mov_b32_e32 v6, v174
	v_mov_b32_e32 v7, v175
	v_lshlrev_b32_e32 v24, 16, v20
	v_and_b32_e32 v25, 0xffff0000, v20
	v_lshlrev_b32_e32 v26, 16, v21
	v_and_b32_e32 v27, 0xffff0000, v21
	v_pk_mul_f32 v[20:21], v[24:25], v[24:25]
	v_pk_mul_f32 v[30:31], v[26:27], v[26:27]
	v_add_f32_e32 v20, v20, v21
	v_lshlrev_b32_e32 v28, 16, v22
	v_and_b32_e32 v29, 0xffff0000, v22
	v_add_f32_e32 v20, v30, v20
	v_pk_mul_f32 v[32:33], v[28:29], v[28:29]
	v_add_f32_e32 v20, v31, v20
	v_lshlrev_b32_e32 v22, 16, v23
	v_and_b32_e32 v23, 0xffff0000, v23
	v_add_f32_e32 v20, v32, v20
	v_pk_mul_f32 v[34:35], v[22:23], v[22:23]
	v_add_f32_e32 v20, v33, v20
	v_add_f32_e32 v20, v34, v20
	v_add_f32_e32 v20, v35, v20
	ds_bpermute_b32 v21, v132, v20
	s_and_b64 vcc, exec, s[6:7]
	s_waitcnt lgkmcnt(0)
	v_add_f32_e32 v20, v20, v21
	ds_bpermute_b32 v21, v75, v20
	s_waitcnt lgkmcnt(0)
	v_add_f32_e32 v20, v20, v21
	ds_bpermute_b32 v21, v133, v20
	s_waitcnt lgkmcnt(0)
	v_add_f32_e32 v20, v20, v21
	v_fmamk_f32 v20, v20, 0x3c800000, v127
	v_mul_f32_e32 v21, 0x4b800000, v20
	v_cmp_gt_f32_e64 s[16:17], s79, v20
	s_nop 1
	v_cndmask_b32_e64 v20, v20, v21, s[16:17]
	v_rsq_f32_e32 v21, v20
	v_add_u32_e32 v20, s80, v142
	v_mul_f32_e32 v30, 0x45800000, v21
	v_cndmask_b32_e64 v30, v21, v30, s[16:17]
	v_pk_mul_f32 v[24:25], v[30:31], v[24:25] op_sel_hi:[0,1]
	v_pk_mul_f32 v[26:27], v[30:31], v[26:27] op_sel_hi:[0,1]
	v_pk_mul_f32 v[28:29], v[30:31], v[28:29] op_sel_hi:[0,1]
	v_pk_mul_f32 v[22:23], v[30:31], v[22:23] op_sel_hi:[0,1]
	v_pk_mul_f32 v[0:1], v[0:1], v[24:25]
	v_pk_mul_f32 v[2:3], v[2:3], v[26:27]
	v_pk_mul_f32 v[4:5], v[4:5], v[28:29]
	v_pk_mul_f32 v[6:7], v[6:7], v[22:23]
	s_cbranch_vccnz .LBB0_1437
	v_ashrrev_i32_e32 v21, 6, v20
	v_bfe_u32 v22, v93, 4, 6
	v_cndmask_b32_e64 v21, v22, v21, s[12:13]
	v_lshl_or_b32 v22, v21, 5, v138
	v_ashrrev_i32_e32 v23, 31, v22
	v_lshl_add_u64 v[34:35], v[22:23], 2, s[56:57]
	s_waitcnt vmcnt(1)
	v_mov_b32_e32 v22, v188
	v_mov_b32_e32 v23, v189
	v_mov_b32_e32 v24, v190
	v_mov_b32_e32 v25, v191
	v_mov_b32_e32 v26, v184
	v_mov_b32_e32 v27, v185
	v_mov_b32_e32 v28, v186
	v_mov_b32_e32 v29, v187
	v_mov_b32_e32 v30, v180
	v_mov_b32_e32 v31, v181
	v_mov_b32_e32 v32, v182
	v_mov_b32_e32 v33, v183
	v_mov_b32_e32 v34, v176
	v_mov_b32_e32 v35, v177
	v_mov_b32_e32 v36, v178
	v_mov_b32_e32 v37, v179
	v_lshl_add_u64 v[192:193], v[192:193], 0, v[194:195]
	global_load_dwordx4 v[188:191], v[192:193], off offset:48
	global_load_dwordx4 v[184:187], v[192:193], off offset:32
	global_load_dwordx4 v[180:183], v[192:193], off offset:16
	global_load_dwordx4 v[176:179], v[192:193], off
	ds_bpermute_b32 v38, v75, v0
	ds_bpermute_b32 v39, v75, v1
	v_mov_b32_e32 v41, v36
	v_mov_b32_e32 v36, v35
	v_mov_b32_e32 v40, v34
	s_waitcnt lgkmcnt(0)
	v_pk_mul_f32 v[34:35], v[36:37], v[38:39]
	v_mov_b32_e32 v37, v32
	v_cndmask_b32_e64 v35, v35, -v35, s[10:11]
	v_cndmask_b32_e64 v34, v34, -v34, s[10:11]
	v_pk_fma_f32 v[0:1], v[0:1], v[40:41], v[34:35]
	ds_bpermute_b32 v34, v75, v2
	ds_bpermute_b32 v35, v75, v3
	v_mov_b32_e32 v32, v31
	v_mov_b32_e32 v36, v30
	s_waitcnt lgkmcnt(0)
	v_pk_mul_f32 v[30:31], v[32:33], v[34:35]
	s_nop 0
	v_cndmask_b32_e64 v31, v31, -v31, s[10:11]
	v_cndmask_b32_e64 v30, v30, -v30, s[10:11]
	v_pk_fma_f32 v[2:3], v[2:3], v[36:37], v[30:31]
	ds_bpermute_b32 v30, v75, v4
	ds_bpermute_b32 v31, v75, v5
	v_mov_b32_e32 v33, v28
	v_mov_b32_e32 v28, v27
	v_mov_b32_e32 v32, v26
	s_waitcnt lgkmcnt(0)
	v_pk_mul_f32 v[26:27], v[28:29], v[30:31]
	s_nop 0
	v_cndmask_b32_e64 v27, v27, -v27, s[10:11]
	v_cndmask_b32_e64 v26, v26, -v26, s[10:11]
	v_pk_fma_f32 v[4:5], v[4:5], v[32:33], v[26:27]
	ds_bpermute_b32 v26, v75, v6
	ds_bpermute_b32 v27, v75, v7
	v_mov_b32_e32 v29, v24
	v_mov_b32_e32 v24, v23
	v_mov_b32_e32 v28, v22
	s_waitcnt lgkmcnt(0)
	v_pk_mul_f32 v[22:23], v[24:25], v[26:27]
	s_nop 0
	v_cndmask_b32_e64 v23, v23, -v23, s[10:11]
	v_cndmask_b32_e64 v22, v22, -v22, s[10:11]
	v_pk_fma_f32 v[6:7], v[6:7], v[28:29], v[22:23]
	v_mov_b64_e32 v[22:23], s[40:41]
	s_and_saveexec_b64 s[4:5], s[96:97]
	s_xor_b64 s[4:5], exec, s[4:5]
	s_cbranch_execnz .LBB0_1438

.LBB0_1352:
	s_or_b64 exec, exec, s[4:5]
	v_mov_b32_e32 v87, v71
	v_lshl_add_u64 v[4:5], v[22:23], 0, v[86:87]
	v_mov_b32_e32 v0, v168
	v_mov_b32_e32 v1, v169
	v_mov_b32_e32 v2, v170
	v_mov_b32_e32 v3, v171
	s_nop 0
	v_mov_b32_e32 v4, v172
	v_mov_b32_e32 v5, v173
	v_mov_b32_e32 v6, v174
	v_mov_b32_e32 v7, v175
	v_lshlrev_b32_e32 v20, 16, v16
	v_and_b32_e32 v21, 0xffff0000, v16
	v_lshlrev_b32_e32 v22, 16, v17
	v_and_b32_e32 v23, 0xffff0000, v17
	v_pk_mul_f32 v[16:17], v[20:21], v[20:21]
	v_pk_mul_f32 v[26:27], v[22:23], v[22:23]
	v_add_f32_e32 v16, v16, v17
	v_lshlrev_b32_e32 v24, 16, v18
	v_and_b32_e32 v25, 0xffff0000, v18
	v_add_f32_e32 v16, v26, v16
	v_pk_mul_f32 v[28:29], v[24:25], v[24:25]
	v_add_f32_e32 v16, v27, v16
	v_lshlrev_b32_e32 v18, 16, v19
	v_and_b32_e32 v19, 0xffff0000, v19
	v_add_f32_e32 v16, v28, v16
	v_pk_mul_f32 v[30:31], v[18:19], v[18:19]
	v_add_f32_e32 v16, v29, v16
	v_add_f32_e32 v16, v30, v16
	v_add_f32_e32 v16, v31, v16
	ds_bpermute_b32 v17, v132, v16
	s_and_b64 vcc, exec, s[6:7]
	s_waitcnt lgkmcnt(0)
	v_add_f32_e32 v16, v16, v17
	ds_bpermute_b32 v17, v75, v16
	s_waitcnt lgkmcnt(0)
	v_add_f32_e32 v16, v16, v17
	ds_bpermute_b32 v17, v133, v16
	s_waitcnt lgkmcnt(0)
	v_add_f32_e32 v16, v16, v17
	v_fmamk_f32 v16, v16, 0x3c800000, v127
	v_mul_f32_e32 v17, 0x4b800000, v16
	v_cmp_gt_f32_e64 s[16:17], s79, v16
	s_nop 1
	v_cndmask_b32_e64 v16, v16, v17, s[16:17]
	v_rsq_f32_e32 v17, v16
	v_add_u32_e32 v16, s80, v141
	v_mul_f32_e32 v26, 0x45800000, v17
	v_cndmask_b32_e64 v26, v17, v26, s[16:17]
	v_pk_mul_f32 v[20:21], v[26:27], v[20:21] op_sel_hi:[0,1]
	v_pk_mul_f32 v[22:23], v[26:27], v[22:23] op_sel_hi:[0,1]
	v_pk_mul_f32 v[24:25], v[26:27], v[24:25] op_sel_hi:[0,1]
	v_pk_mul_f32 v[18:19], v[26:27], v[18:19] op_sel_hi:[0,1]
	v_pk_mul_f32 v[0:1], v[0:1], v[20:21]
	v_pk_mul_f32 v[2:3], v[2:3], v[22:23]
	v_pk_mul_f32 v[4:5], v[4:5], v[24:25]
	v_pk_mul_f32 v[6:7], v[6:7], v[18:19]
	s_cbranch_vccnz .LBB0_1441
	v_ashrrev_i32_e32 v17, 6, v16
	v_bfe_u32 v18, v91, 4, 6
	v_cndmask_b32_e64 v17, v18, v17, s[12:13]
	v_lshl_or_b32 v18, v17, 5, v138
	v_ashrrev_i32_e32 v19, 31, v18
	v_lshl_add_u64 v[30:31], v[18:19], 2, s[56:57]
	s_waitcnt vmcnt(1)
	v_mov_b32_e32 v18, v188
	v_mov_b32_e32 v19, v189
	v_mov_b32_e32 v20, v190
	v_mov_b32_e32 v21, v191
	v_mov_b32_e32 v22, v184
	v_mov_b32_e32 v23, v185
	v_mov_b32_e32 v24, v186
	v_mov_b32_e32 v25, v187
	v_mov_b32_e32 v26, v180
	v_mov_b32_e32 v27, v181
	v_mov_b32_e32 v28, v182
	v_mov_b32_e32 v29, v183
	v_mov_b32_e32 v30, v176
	v_mov_b32_e32 v31, v177
	v_mov_b32_e32 v32, v178
	v_mov_b32_e32 v33, v179
	v_lshl_add_u64 v[192:193], v[192:193], 0, v[194:195]
	global_load_dwordx4 v[188:191], v[192:193], off offset:48
	global_load_dwordx4 v[184:187], v[192:193], off offset:32
	global_load_dwordx4 v[180:183], v[192:193], off offset:16
	global_load_dwordx4 v[176:179], v[192:193], off
	ds_bpermute_b32 v34, v75, v0
	ds_bpermute_b32 v35, v75, v1
	v_mov_b32_e32 v37, v32
	v_mov_b32_e32 v32, v31
	v_mov_b32_e32 v36, v30
	s_waitcnt lgkmcnt(0)
	v_pk_mul_f32 v[30:31], v[32:33], v[34:35]
	v_mov_b32_e32 v33, v28
	v_cndmask_b32_e64 v31, v31, -v31, s[10:11]
	v_cndmask_b32_e64 v30, v30, -v30, s[10:11]
	v_pk_fma_f32 v[0:1], v[0:1], v[36:37], v[30:31]
	ds_bpermute_b32 v30, v75, v2
	ds_bpermute_b32 v31, v75, v3
	v_mov_b32_e32 v28, v27
	v_mov_b32_e32 v32, v26
	s_waitcnt lgkmcnt(0)
	v_pk_mul_f32 v[26:27], v[28:29], v[30:31]
	s_nop 0
	v_cndmask_b32_e64 v27, v27, -v27, s[10:11]
	v_cndmask_b32_e64 v26, v26, -v26, s[10:11]
	v_pk_fma_f32 v[2:3], v[2:3], v[32:33], v[26:27]
	ds_bpermute_b32 v26, v75, v4
	ds_bpermute_b32 v27, v75, v5
	v_mov_b32_e32 v29, v24
	v_mov_b32_e32 v24, v23
	v_mov_b32_e32 v28, v22
	s_waitcnt lgkmcnt(0)
	v_pk_mul_f32 v[22:23], v[24:25], v[26:27]
	s_nop 0
	v_cndmask_b32_e64 v23, v23, -v23, s[10:11]
	v_cndmask_b32_e64 v22, v22, -v22, s[10:11]
	v_pk_fma_f32 v[4:5], v[4:5], v[28:29], v[22:23]
	ds_bpermute_b32 v22, v75, v6
	ds_bpermute_b32 v23, v75, v7
	v_mov_b32_e32 v25, v20
	v_mov_b32_e32 v20, v19
	v_mov_b32_e32 v24, v18
	s_waitcnt lgkmcnt(0)
	v_pk_mul_f32 v[18:19], v[20:21], v[22:23]
	s_nop 0
	v_cndmask_b32_e64 v19, v19, -v19, s[10:11]
	v_cndmask_b32_e64 v18, v18, -v18, s[10:11]
	v_pk_fma_f32 v[6:7], v[6:7], v[24:25], v[18:19]
	v_mov_b64_e32 v[18:19], s[40:41]
	s_and_saveexec_b64 s[4:5], s[96:97]
	s_xor_b64 s[4:5], exec, s[4:5]
	s_cbranch_execnz .LBB0_1442

.LBB0_1356:
	s_or_b64 exec, exec, s[4:5]
	v_mov_b32_e32 v87, v71
	v_lshl_add_u64 v[4:5], v[18:19], 0, v[86:87]
	v_mov_b32_e32 v0, v168
	v_mov_b32_e32 v1, v169
	v_mov_b32_e32 v2, v170
	v_mov_b32_e32 v3, v171
	s_nop 0
	v_mov_b32_e32 v4, v172
	v_mov_b32_e32 v5, v173
	v_mov_b32_e32 v6, v174
	v_mov_b32_e32 v7, v175
	v_lshlrev_b32_e32 v16, 16, v12
	v_and_b32_e32 v17, 0xffff0000, v12
	v_lshlrev_b32_e32 v18, 16, v13
	v_and_b32_e32 v19, 0xffff0000, v13
	v_pk_mul_f32 v[12:13], v[16:17], v[16:17]
	v_pk_mul_f32 v[22:23], v[18:19], v[18:19]
	v_add_f32_e32 v12, v12, v13
	v_lshlrev_b32_e32 v20, 16, v14
	v_and_b32_e32 v21, 0xffff0000, v14
	v_add_f32_e32 v12, v22, v12
	v_pk_mul_f32 v[24:25], v[20:21], v[20:21]
	v_add_f32_e32 v12, v23, v12
	v_lshlrev_b32_e32 v14, 16, v15
	v_and_b32_e32 v15, 0xffff0000, v15
	v_add_f32_e32 v12, v24, v12
	v_pk_mul_f32 v[26:27], v[14:15], v[14:15]
	v_add_f32_e32 v12, v25, v12
	v_add_f32_e32 v12, v26, v12
	v_add_f32_e32 v12, v27, v12
	ds_bpermute_b32 v13, v132, v12
	s_and_b64 vcc, exec, s[6:7]
	s_waitcnt lgkmcnt(0)
	v_add_f32_e32 v12, v12, v13
	ds_bpermute_b32 v13, v75, v12
	s_waitcnt lgkmcnt(0)
	v_add_f32_e32 v12, v12, v13
	ds_bpermute_b32 v13, v133, v12
	s_waitcnt lgkmcnt(0)
	v_add_f32_e32 v12, v12, v13
	v_fmamk_f32 v12, v12, 0x3c800000, v127
	v_mul_f32_e32 v13, 0x4b800000, v12
	v_cmp_gt_f32_e64 s[16:17], s79, v12
	s_nop 1
	v_cndmask_b32_e64 v12, v12, v13, s[16:17]
	v_rsq_f32_e32 v13, v12
	v_add_u32_e32 v12, s80, v140
	v_mul_f32_e32 v22, 0x45800000, v13
	v_cndmask_b32_e64 v22, v13, v22, s[16:17]
	v_pk_mul_f32 v[16:17], v[22:23], v[16:17] op_sel_hi:[0,1]
	v_pk_mul_f32 v[18:19], v[22:23], v[18:19] op_sel_hi:[0,1]
	v_pk_mul_f32 v[20:21], v[22:23], v[20:21] op_sel_hi:[0,1]
	v_pk_mul_f32 v[14:15], v[22:23], v[14:15] op_sel_hi:[0,1]
	v_pk_mul_f32 v[0:1], v[0:1], v[16:17]
	v_pk_mul_f32 v[2:3], v[2:3], v[18:19]
	v_pk_mul_f32 v[4:5], v[4:5], v[20:21]
	v_pk_mul_f32 v[6:7], v[6:7], v[14:15]
	s_cbranch_vccnz .LBB0_1445
	v_ashrrev_i32_e32 v13, 6, v12
	v_bfe_u32 v14, v89, 4, 6
	v_cndmask_b32_e64 v13, v14, v13, s[12:13]
	v_lshl_or_b32 v14, v13, 5, v138
	v_ashrrev_i32_e32 v15, 31, v14
	v_lshl_add_u64 v[26:27], v[14:15], 2, s[56:57]
	s_waitcnt vmcnt(1)
	v_mov_b32_e32 v14, v188
	v_mov_b32_e32 v15, v189
	v_mov_b32_e32 v16, v190
	v_mov_b32_e32 v17, v191
	v_mov_b32_e32 v18, v184
	v_mov_b32_e32 v19, v185
	v_mov_b32_e32 v20, v186
	v_mov_b32_e32 v21, v187
	v_mov_b32_e32 v22, v180
	v_mov_b32_e32 v23, v181
	v_mov_b32_e32 v24, v182
	v_mov_b32_e32 v25, v183
	v_mov_b32_e32 v26, v176
	v_mov_b32_e32 v27, v177
	v_mov_b32_e32 v28, v178
	v_mov_b32_e32 v29, v179
	v_lshl_add_u64 v[192:193], v[192:193], 0, v[194:195]
	global_load_dwordx4 v[188:191], v[192:193], off offset:48
	global_load_dwordx4 v[184:187], v[192:193], off offset:32
	global_load_dwordx4 v[180:183], v[192:193], off offset:16
	global_load_dwordx4 v[176:179], v[192:193], off
	ds_bpermute_b32 v30, v75, v0
	ds_bpermute_b32 v31, v75, v1
	v_mov_b32_e32 v33, v28
	v_mov_b32_e32 v28, v27
	v_mov_b32_e32 v32, v26
	s_waitcnt lgkmcnt(0)
	v_pk_mul_f32 v[26:27], v[28:29], v[30:31]
	v_mov_b32_e32 v29, v24
	v_cndmask_b32_e64 v27, v27, -v27, s[10:11]
	v_cndmask_b32_e64 v26, v26, -v26, s[10:11]
	v_pk_fma_f32 v[0:1], v[0:1], v[32:33], v[26:27]
	ds_bpermute_b32 v26, v75, v2
	ds_bpermute_b32 v27, v75, v3
	v_mov_b32_e32 v24, v23
	v_mov_b32_e32 v28, v22
	s_waitcnt lgkmcnt(0)
	v_pk_mul_f32 v[22:23], v[24:25], v[26:27]
	s_nop 0
	v_cndmask_b32_e64 v23, v23, -v23, s[10:11]
	v_cndmask_b32_e64 v22, v22, -v22, s[10:11]
	v_pk_fma_f32 v[2:3], v[2:3], v[28:29], v[22:23]
	ds_bpermute_b32 v22, v75, v4
	ds_bpermute_b32 v23, v75, v5
	v_mov_b32_e32 v25, v20
	v_mov_b32_e32 v20, v19
	v_mov_b32_e32 v24, v18
	s_waitcnt lgkmcnt(0)
	v_pk_mul_f32 v[18:19], v[20:21], v[22:23]
	s_nop 0
	v_cndmask_b32_e64 v19, v19, -v19, s[10:11]
	v_cndmask_b32_e64 v18, v18, -v18, s[10:11]
	v_pk_fma_f32 v[4:5], v[4:5], v[24:25], v[18:19]
	ds_bpermute_b32 v18, v75, v6
	ds_bpermute_b32 v19, v75, v7
	v_mov_b32_e32 v21, v16
	v_mov_b32_e32 v16, v15
	v_mov_b32_e32 v20, v14
	s_waitcnt lgkmcnt(0)
	v_pk_mul_f32 v[14:15], v[16:17], v[18:19]
	s_nop 0
	v_cndmask_b32_e64 v15, v15, -v15, s[10:11]
	v_cndmask_b32_e64 v14, v14, -v14, s[10:11]
	v_pk_fma_f32 v[6:7], v[6:7], v[20:21], v[14:15]
	v_mov_b64_e32 v[14:15], s[40:41]
	s_and_saveexec_b64 s[4:5], s[96:97]
	s_xor_b64 s[4:5], exec, s[4:5]
	s_cbranch_execnz .LBB0_1446

.LBB0_1360:
	s_or_b64 exec, exec, s[4:5]
	v_mov_b32_e32 v87, v71
	v_lshl_add_u64 v[0:1], v[14:15], 0, v[86:87]
	v_mov_b32_e32 v4, v172
	v_mov_b32_e32 v5, v173
	v_mov_b32_e32 v6, v174
	v_mov_b32_e32 v7, v175
	s_nop 0
	v_mov_b32_e32 v0, v168
	v_mov_b32_e32 v1, v169
	v_mov_b32_e32 v2, v170
	v_mov_b32_e32 v3, v171
	v_lshlrev_b32_e32 v14, 16, v8
	v_and_b32_e32 v15, 0xffff0000, v8
	v_pk_mul_f32 v[16:17], v[14:15], v[14:15]
	v_lshlrev_b32_e32 v8, 16, v9
	v_and_b32_e32 v9, 0xffff0000, v9
	v_pk_mul_f32 v[18:19], v[8:9], v[8:9]
	v_add_f32_e32 v13, v16, v17
	v_lshlrev_b32_e32 v20, 16, v10
	v_and_b32_e32 v21, 0xffff0000, v10
	v_add_f32_e32 v13, v18, v13
	v_pk_mul_f32 v[22:23], v[20:21], v[20:21]
	v_add_f32_e32 v13, v19, v13
	v_lshlrev_b32_e32 v10, 16, v11
	v_and_b32_e32 v11, 0xffff0000, v11
	v_add_f32_e32 v13, v22, v13
	v_pk_mul_f32 v[24:25], v[10:11], v[10:11]
	v_add_f32_e32 v13, v23, v13
	v_add_f32_e32 v13, v24, v13
	v_add_f32_e32 v13, v25, v13
	ds_bpermute_b32 v16, v132, v13
	v_add_u32_e32 v12, s80, v139
	s_waitcnt lgkmcnt(0)
	v_add_f32_e32 v13, v13, v16
	ds_bpermute_b32 v16, v75, v13
	s_waitcnt lgkmcnt(0)
	v_add_f32_e32 v13, v13, v16
	ds_bpermute_b32 v16, v133, v13
	s_waitcnt lgkmcnt(0)
	v_add_f32_e32 v13, v13, v16
	v_fmamk_f32 v13, v13, 0x3c800000, v127
	v_cmp_gt_f32_e32 vcc, s79, v13
	v_mul_f32_e32 v16, 0x4b800000, v13
	s_nop 0
	v_cndmask_b32_e32 v13, v13, v16, vcc
	v_rsq_f32_e32 v13, v13
	s_nop 0
	v_mul_f32_e32 v16, 0x45800000, v13
	v_cndmask_b32_e32 v16, v13, v16, vcc
	v_pk_mul_f32 v[8:9], v[16:17], v[8:9] op_sel_hi:[0,1]
	v_pk_mul_f32 v[14:15], v[16:17], v[14:15] op_sel_hi:[0,1]
	s_and_b64 vcc, exec, s[6:7]
	v_pk_mul_f32 v[2:3], v[2:3], v[8:9]
	v_pk_mul_f32 v[8:9], v[16:17], v[20:21] op_sel_hi:[0,1]
	v_pk_mul_f32 v[4:5], v[4:5], v[8:9]
	v_pk_mul_f32 v[8:9], v[16:17], v[10:11] op_sel_hi:[0,1]
	v_pk_mul_f32 v[0:1], v[0:1], v[14:15]
	v_pk_mul_f32 v[6:7], v[6:7], v[8:9]
	s_cbranch_vccnz .LBB0_1362
	v_ashrrev_i32_e32 v8, 6, v12
	v_bfe_u32 v9, v137, 4, 6
	v_cndmask_b32_e64 v8, v9, v8, s[12:13]
	v_lshl_or_b32 v8, v8, 5, v138
	v_ashrrev_i32_e32 v9, 31, v8
	v_lshl_add_u64 v[22:23], v[8:9], 2, s[56:57]
	s_waitcnt vmcnt(1)
	v_mov_b32_e32 v8, v188
	v_mov_b32_e32 v9, v189
	v_mov_b32_e32 v10, v190
	v_mov_b32_e32 v11, v191
	v_mov_b32_e32 v14, v184
	v_mov_b32_e32 v15, v185
	v_mov_b32_e32 v16, v186
	v_mov_b32_e32 v17, v187
	v_mov_b32_e32 v18, v180
	v_mov_b32_e32 v19, v181
	v_mov_b32_e32 v20, v182
	v_mov_b32_e32 v21, v183
	v_mov_b32_e32 v22, v176
	v_mov_b32_e32 v23, v177
	v_mov_b32_e32 v24, v178
	v_mov_b32_e32 v25, v179
	ds_bpermute_b32 v26, v75, v0
	ds_bpermute_b32 v27, v75, v1
	v_mov_b32_e32 v29, v24
	v_mov_b32_e32 v24, v23
	v_mov_b32_e32 v28, v22
	s_waitcnt lgkmcnt(0)
	v_pk_mul_f32 v[22:23], v[24:25], v[26:27]
	v_mov_b32_e32 v25, v20
	v_cndmask_b32_e64 v23, v23, -v23, s[10:11]
	v_cndmask_b32_e64 v22, v22, -v22, s[10:11]
	v_pk_fma_f32 v[0:1], v[0:1], v[28:29], v[22:23]
	ds_bpermute_b32 v22, v75, v2
	ds_bpermute_b32 v23, v75, v3
	v_mov_b32_e32 v20, v19
	v_mov_b32_e32 v24, v18
	s_waitcnt lgkmcnt(0)
	v_pk_mul_f32 v[18:19], v[20:21], v[22:23]
	s_nop 0
	v_cndmask_b32_e64 v19, v19, -v19, s[10:11]
	v_cndmask_b32_e64 v18, v18, -v18, s[10:11]
	v_pk_fma_f32 v[2:3], v[2:3], v[24:25], v[18:19]
	ds_bpermute_b32 v18, v75, v4
	ds_bpermute_b32 v19, v75, v5
	v_mov_b32_e32 v21, v16
	v_mov_b32_e32 v16, v15
	v_mov_b32_e32 v20, v14
	s_waitcnt lgkmcnt(0)
	v_pk_mul_f32 v[14:15], v[16:17], v[18:19]
	s_nop 0
	v_cndmask_b32_e64 v15, v15, -v15, s[10:11]
	v_cndmask_b32_e64 v14, v14, -v14, s[10:11]
	v_pk_fma_f32 v[4:5], v[4:5], v[20:21], v[14:15]
	ds_bpermute_b32 v14, v75, v6
	ds_bpermute_b32 v15, v75, v7
	v_mov_b32_e32 v17, v10
	v_mov_b32_e32 v10, v9
	v_mov_b32_e32 v16, v8
	s_waitcnt lgkmcnt(0)
	v_pk_mul_f32 v[8:9], v[10:11], v[14:15]
	s_nop 0
	v_cndmask_b32_e64 v9, v9, -v9, s[10:11]
	v_cndmask_b32_e64 v8, v8, -v8, s[10:11]
	v_pk_fma_f32 v[6:7], v[6:7], v[16:17], v[8:9]
